# plus nt policy also on the retention / attention / scan phase loads (read-once tiles)
# speedup vs baseline: 1.0088x; 1.0002x over previous
; #define LAS __attribute__((address_space(3)))
; __device__ __forceinline__ unsigned cvt_pk_bf16(float lo, float hi) { unsigned r; asm volatile("s_nop 1\n\tv_cvt_pk_bf16_f32 %0, %1, %2" : "=v"(r) : "v"(lo), "v"(hi)); return r; }
; template <int R>
; __device__ __forceinline__ void stage_tile(ldsp dst, const bf16_t* src, size_t ld, int tid) {
;     ...
;     for (int i = 0; i < R * 16 / 512; ++i) { const int idx = tid + 512 * i, r = idx >> 4, c = idx & 15;
;         const u32x4 v = *(const u32x4*)(src + (size_t)r * ld + c * 8); *(LAS u32x4*)(dst + r * 272 + c * 16) = v; }
; }
; __device__ __forceinline__ void stage_kdT(ldsp dst, const bf16_t* src, float lg, int tid) {
;     const int c = tid & 15;
; #pragma unroll
;     for (int ii = 0; ii < 4; ++ii) {
;         const int r = (tid >> 4) + 32 * ii;
;         const u32x4 v = *(const u32x4*)(src + (size_t)r * 1024 + c * 8);
;         const float dec = __builtin_amdgcn_exp2f((float)(127 - r) * lg);
; #pragma unroll
;         for (int e = 0; e < 8; ++e) {
;             const int ee = (e + c) & 7, q2 = ee >> 1;
;             const unsigned d = q2 == 0 ? v.x : (q2 == 1 ? v.y : (q2 == 2 ? v.z : v.w));
;             const float f = __uint_as_float((ee & 1) ? (d & 0xffff0000u) : (d << 16)) * dec;
;             *(LAS unsigned short*)(dst + (8 * c + ee) * 272 + r * 2) = (unsigned short)(cvt_pk_bf16(f, 0.f) & 0xffffu);
; __device__ __forceinline__ void ret_state_item(ldsp lds, int item, const bf16_t* vT, const bf16_t* kdT, float* L, float lg, int tid_, int w, int fr, int fq) {
;     ...
;     for (int c = 0; c < 8; ++c) {
;         int tid = tid_; asm volatile("" : "+v"(tid));
;         const size_t row0 = (size_t)b * SEQ + g * 1024 + c * 128;
;         stage_tile<256>(lds + RY, vT + ((row0 >> 7) * 2048 + h * 256) * 128, 128, tid);
.LBB0_431:
	v_mov_b32_e32 v82, v84
	s_add_u32 s0, s60, s66
	v_lshlrev_b32_e32 v83, 4, v82
	v_ashrrev_i32_e32 v86, 4, v82
	v_add_u32_e32 v90, 0x600, v82
	v_add_u32_e32 v101, 2, v82
	v_add_u32_e32 v91, 0x800, v82
	v_lshlrev_b32_e32 v99, 3, v82
	v_add_u32_e32 v100, 1, v82
	v_add_u32_e32 v102, 3, v82
	v_add_u32_e32 v103, 5, v82
	v_and_b32_e32 v124, 0xf0, v83
	v_ashrrev_i32_e32 v87, 31, v86
	v_ashrrev_i32_e32 v90, 4, v90
	v_lshl_add_u32 v125, v86, 1, 0
	v_and_b32_e32 v134, 7, v101
	v_bfe_u32 v135, v101, 1, 2
	v_sub_u32_e32 v101, 0x5f, v86
	v_add_u32_e32 v88, 0x200, v82
	v_add_u32_e32 v89, 0x400, v82
	v_and_b32_e32 v128, 7, v82
	v_add_u32_e32 v104, 6, v82
	v_add_u32_e32 v105, 7, v82
	v_ashrrev_i32_e32 v92, 4, v91
	v_and_b32_e32 v106, 0x78, v99
	v_and_b32_e32 v132, 7, v100
	v_bfe_u32 v133, v100, 1, 2
	v_and_b32_e32 v136, 7, v102
	v_bfe_u32 v137, v102, 1, 2
	v_and_b32_e32 v138, 1, v102
	v_and_b32_e32 v140, 7, v103
	v_bfe_u32 v141, v103, 1, 2
	v_and_b32_e32 v142, 1, v103
	v_add_u32_e32 v100, s71, v124
	v_lshlrev_b64 v[102:103], 8, v[86:87]
	v_ashrrev_i32_e32 v91, 31, v90
	v_cvt_f32_i32_e32 v154, v101
	v_add_u32_e32 v101, 64, v125
	s_addc_u32 s1, s61, s78
	v_add_u32_e32 v93, 0xa00, v82
	v_add_u32_e32 v95, 0xc00, v82
	v_add_u32_e32 v97, 0xe00, v82
	v_bfe_u32 v129, v82, 1, 2
	v_and_b32_e32 v130, 1, v82
	v_bitop3_b32 v131, v82, 4, 7 bitop3:0x6c
	v_ashrrev_i32_e32 v82, 4, v88
	v_ashrrev_i32_e32 v88, 4, v89
	v_sub_u32_e32 v107, 0x7f, v86
	v_and_b32_e32 v143, 7, v104
	v_bfe_u32 v144, v104, 1, 2
	v_and_b32_e32 v145, 7, v105
	v_bfe_u32 v146, v105, 1, 2
	v_and_b32_e32 v147, 1, v105
	v_lshlrev_b64 v[104:105], 11, v[86:87]
	v_or_b32_e32 v87, v106, v128
	v_add_u32_e32 v156, 0x80, v125
	v_add_u32_e32 v158, 0xc0, v125
	v_or_b32_e32 v102, v102, v124
	v_lshlrev_b64 v[114:115], 8, v[90:91]
	v_mad_u64_u32 v[90:91], s[6:7], v90, s70, v[100:101]
	v_sub_u32_e32 v108, 63, v86
	v_sub_u32_e32 v109, 31, v86
	v_ashrrev_i32_e32 v83, 31, v82
	v_ashrrev_i32_e32 v89, 31, v88
	v_cvt_f32_i32_e32 v148, v107
	v_or_b32_e32 v126, v132, v106
	v_or_b32_e32 v127, v134, v106
	v_or_b32_e32 v149, v136, v106
	v_or_b32_e32 v150, v131, v106
	v_or_b32_e32 v151, v140, v106
	v_or_b32_e32 v152, v143, v106
	v_or_b32_e32 v153, v145, v106
	v_mad_u64_u32 v[106:107], s[6:7], v86, s70, v[100:101]
	v_mad_u32_u24 v91, v87, s70, v125
	v_mad_u32_u24 v159, v87, s70, v101
	v_mad_u32_u24 v167, v87, s70, v156
	v_mad_u32_u24 v174, v87, s70, v158
	v_lshl_add_u64 v[86:87], s[0:1], 0, v[102:103]
	v_cvt_f32_i32_e32 v155, v108
	v_cvt_f32_i32_e32 v157, v109
	v_lshlrev_b64 v[108:109], 8, v[82:83]
	v_mad_u64_u32 v[110:111], s[6:7], v82, s70, v[100:101]
	v_lshlrev_b64 v[82:83], 8, v[88:89]
	v_mad_u64_u32 v[112:113], s[6:7], v88, s70, v[100:101]
	flat_load_dwordx4 v[86:89], v[86:87] nt
	v_or_b32_e32 v108, v108, v124
	v_lshl_add_u64 v[102:103], s[0:1], 0, v[108:109]
	s_add_u32 s4, s60, s3
	v_ashrrev_i32_e32 v94, 4, v93
	v_ashrrev_i32_e32 v96, 4, v95
	v_ashrrev_i32_e32 v98, 4, v97
	s_addc_u32 s5, s61, s67
	v_ashrrev_i32_e32 v93, 31, v92
	v_ashrrev_i32_e32 v95, 31, v94
	v_ashrrev_i32_e32 v97, 31, v96
	v_ashrrev_i32_e32 v99, 31, v98
	v_or_b32_e32 v104, v104, v124
	v_or_b32_e32 v82, v82, v124
	v_lshlrev_b64 v[116:117], 8, v[92:93]
	v_mad_u64_u32 v[92:93], s[6:7], v92, s70, v[100:101]
	v_lshlrev_b64 v[118:119], 8, v[94:95]
	v_mad_u64_u32 v[94:95], s[6:7], v94, s70, v[100:101]
	v_lshlrev_b64 v[120:121], 8, v[96:97]
	v_mad_u64_u32 v[96:97], s[6:7], v96, s70, v[100:101]
	v_lshlrev_b64 v[122:123], 8, v[98:99]
	v_mad_u64_u32 v[98:99], s[6:7], v98, s70, v[100:101]
	v_mad_u32_u24 v160, v126, s70, v101
	v_mad_u32_u24 v161, v127, s70, v101
	v_mad_u32_u24 v162, v149, s70, v101
	v_mad_u32_u24 v163, v150, s70, v101
	v_mad_u32_u24 v164, v151, s70, v101
	v_mad_u32_u24 v165, v152, s70, v101
	v_mad_u32_u24 v166, v153, s70, v101
	v_lshl_add_u64 v[100:101], s[4:5], 0, v[104:105]
	v_lshl_add_u64 v[104:105], s[0:1], 0, v[82:83]
	v_or_b32_e32 v114, v114, v124
	v_lshl_add_u64 v[108:109], s[0:1], 0, v[114:115]
	v_or_b32_e32 v116, v116, v124
	v_lshl_add_u64 v[114:115], s[0:1], 0, v[116:117]
	v_or_b32_e32 v118, v118, v124
	v_lshl_add_u64 v[116:117], s[0:1], 0, v[118:119]
	v_or_b32_e32 v120, v120, v124
	v_lshl_add_u64 v[118:119], s[0:1], 0, v[120:121]
	v_or_b32_e32 v122, v122, v124
	v_lshl_add_u64 v[120:121], s[0:1], 0, v[122:123]
	v_add_co_u32_e32 v122, vcc, s74, v100
	v_mad_u32_u24 v93, v126, s70, v125
	s_nop 0
	v_addc_co_u32_e32 v123, vcc, 0, v101, vcc
	v_add_co_u32_e32 v124, vcc, s75, v100
	v_mad_u32_u24 v95, v127, s70, v125
	v_mad_u32_u24 v97, v149, s70, v125
	v_mad_u32_u24 v99, v150, s70, v125
	v_mad_u32_u24 v107, v151, s70, v125
	v_mad_u32_u24 v111, v152, s70, v125
	v_mad_u32_u24 v113, v153, s70, v125
	v_addc_co_u32_e32 v125, vcc, 0, v101, vcc
	v_mad_u32_u24 v168, v126, s70, v156
	v_mad_u32_u24 v175, v126, s70, v158
	v_add_co_u32_e32 v126, vcc, s76, v100
	v_mad_u32_u24 v169, v127, s70, v156
	v_mad_u32_u24 v176, v127, s70, v158
	v_addc_co_u32_e32 v127, vcc, 0, v101, vcc
	v_add_co_u32_e32 v82, vcc, s77, v100
	v_lshrrev_b32_e32 v139, 1, v131
	s_nop 0
	v_addc_co_u32_e32 v83, vcc, 0, v101, vcc
	v_cmp_eq_u32_e64 s[24:25], 2, v129
	v_mul_f32_e32 v100, v76, v148
	v_cmp_eq_u32_e32 vcc, 2, v133
	v_cmp_eq_u32_e64 s[0:1], 2, v135
	v_cmp_eq_u32_e64 s[56:57], 2, v137
	v_cmp_eq_u32_e64 s[4:5], 2, v139
	v_cmp_eq_u32_e64 s[6:7], 2, v141
	s_waitcnt vmcnt(0) lgkmcnt(0)
; #define LAS __attribute__((address_space(3)))
; __device__ __forceinline__ unsigned cvt_pk_bf16(float lo, float hi) { unsigned r; asm volatile("s_nop 1\n\tv_cvt_pk_bf16_f32 %0, %1, %2" : "=v"(r) : "v"(lo), "v"(hi)); return r; }
; template <int R>
; __device__ __forceinline__ void stage_tile(ldsp dst, const bf16_t* src, size_t ld, int tid) {
;     ...
;     for (int i = 0; i < R * 16 / 512; ++i) { const int idx = tid + 512 * i, r = idx >> 4, c = idx & 15;
;         const u32x4 v = *(const u32x4*)(src + (size_t)r * ld + c * 8); *(LAS u32x4*)(dst + r * 272 + c * 16) = v; }
; }
; __device__ __forceinline__ void stage_kdT(ldsp dst, const bf16_t* src, float lg, int tid) {
;     const int c = tid & 15;
; #pragma unroll
;     for (int ii = 0; ii < 4; ++ii) {
;         const int r = (tid >> 4) + 32 * ii;
;         const u32x4 v = *(const u32x4*)(src + (size_t)r * 1024 + c * 8);
;         const float dec = __builtin_amdgcn_exp2f((float)(127 - r) * lg);
; #pragma unroll
;         for (int e = 0; e < 8; ++e) {
;             const int ee = (e + c) & 7, q2 = ee >> 1;
;             const unsigned d = q2 == 0 ? v.x : (q2 == 1 ? v.y : (q2 == 2 ? v.z : v.w));
;             const float f = __uint_as_float((ee & 1) ? (d & 0xffff0000u) : (d << 16)) * dec;
;             *(LAS unsigned short*)(dst + (8 * c + ee) * 272 + r * 2) = (unsigned short)(cvt_pk_bf16(f, 0.f) & 0xffffu);
; __device__ __forceinline__ void ret_state_item(ldsp lds, int item, const bf16_t* vT, const bf16_t* kdT, float* L, float lg, int tid_, int w, int fr, int fq) {
;     ...
;         for (int mt = 0; mt < 2; ++mt)
; #pragma unroll
;             for (int nt = 0; nt < 8; ++nt) st[mt][nt] = st[mt][nt] * gC;
	ds_write_b128 v106, v[86:89]
	flat_load_dwordx4 v[86:89], v[102:103] nt
	v_cmp_eq_u32_e64 s[8:9], 2, v144
	v_cmp_eq_u32_e64 s[10:11], 2, v146
	v_cmp_eq_u32_e64 s[44:45], 1, v129
	v_exp_f32_e32 v100, v100
	v_cmp_eq_u32_e64 s[12:13], 1, v133
	v_cmp_eq_u32_e64 s[14:15], 1, v135
	v_cmp_eq_u32_e64 s[16:17], 1, v137
	v_cmp_eq_u32_e64 s[18:19], 1, v139
	v_cmp_eq_u32_e64 s[20:21], 1, v141
	v_cmp_eq_u32_e64 s[22:23], 1, v144
	v_cmp_eq_u32_e64 s[26:27], 1, v146
	v_cmp_gt_u32_e64 s[54:55], 2, v128
	v_cmp_gt_u32_e64 s[28:29], 2, v132
	v_cmp_gt_u32_e64 s[30:31], 2, v134
	v_cmp_gt_u32_e64 s[34:35], 2, v136
	v_cmp_gt_u32_e64 s[36:37], 2, v131
	v_cmp_gt_u32_e64 s[40:41], 2, v140
	v_cmp_gt_u32_e64 s[42:43], 2, v143
	v_cmp_gt_u32_e64 s[46:47], 2, v145
	v_cmp_eq_u32_e64 s[52:53], 0, v130
	v_cmp_eq_u32_e64 s[38:39], 0, v138
	v_cmp_eq_u32_e64 s[48:49], 0, v142
	v_cmp_eq_u32_e64 s[50:51], 0, v147
	v_mul_f32_e32 v101, v76, v154
	v_exp_f32_e32 v101, v101
	v_mul_f32_e32 v148, v76, v155
	v_exp_f32_e32 v148, v148
	v_mad_u32_u24 v170, v149, s70, v156
	v_mad_u32_u24 v171, v150, s70, v156
	v_mad_u32_u24 v172, v151, s70, v156
	v_mad_u32_u24 v173, v152, s70, v156
	v_mad_u32_u24 v156, v153, s70, v156
	v_mul_f32_e32 v154, v76, v157
	v_exp_f32_e32 v154, v154
	v_mad_u32_u24 v149, v149, s70, v158
	v_mad_u32_u24 v150, v150, s70, v158
	v_mad_u32_u24 v151, v151, s70, v158
	v_mad_u32_u24 v152, v152, s70, v158
	v_mad_u32_u24 v153, v153, s70, v158
	v_mov_b32_e32 v79, v78
	v_pk_mul_f32 v[60:61], v[80:81], v[60:61]
	v_pk_mul_f32 v[52:53], v[80:81], v[52:53]
	v_pk_mul_f32 v[62:63], v[78:79], v[62:63]
	v_pk_mul_f32 v[54:55], v[78:79], v[54:55]
	v_pk_mul_f32 v[56:57], v[80:81], v[56:57]
	v_pk_mul_f32 v[58:59], v[78:79], v[58:59]
	v_pk_mul_f32 v[24:25], v[80:81], v[24:25]
	v_pk_mul_f32 v[26:27], v[78:79], v[26:27]
	v_pk_mul_f32 v[44:45], v[80:81], v[44:45]
	v_pk_mul_f32 v[46:47], v[78:79], v[46:47]
	v_pk_mul_f32 v[16:17], v[80:81], v[16:17]
	v_pk_mul_f32 v[18:19], v[78:79], v[18:19]
	v_pk_mul_f32 v[40:41], v[80:81], v[40:41]
	v_pk_mul_f32 v[42:43], v[78:79], v[42:43]
	v_pk_mul_f32 v[12:13], v[80:81], v[12:13]
	v_pk_mul_f32 v[14:15], v[78:79], v[14:15]
	v_pk_mul_f32 v[36:37], v[80:81], v[36:37]
	v_pk_mul_f32 v[38:39], v[78:79], v[38:39]
	v_pk_mul_f32 v[8:9], v[80:81], v[8:9]
	v_pk_mul_f32 v[10:11], v[78:79], v[10:11]
	v_pk_mul_f32 v[32:33], v[80:81], v[32:33]
	v_pk_mul_f32 v[34:35], v[78:79], v[34:35]
	v_pk_mul_f32 v[4:5], v[80:81], v[4:5]
	v_pk_mul_f32 v[6:7], v[78:79], v[6:7]
	v_pk_mul_f32 v[20:21], v[80:81], v[20:21]
	v_pk_mul_f32 v[22:23], v[78:79], v[22:23]
	v_pk_mul_f32 v[0:1], v[80:81], v[0:1]
	v_pk_mul_f32 v[2:3], v[78:79], v[2:3]
	v_pk_mul_f32 v[48:49], v[80:81], v[48:49]
	v_pk_mul_f32 v[50:51], v[78:79], v[50:51]
	v_pk_mul_f32 v[28:29], v[80:81], v[28:29]
	v_pk_mul_f32 v[30:31], v[78:79], v[30:31]
	s_add_i32 s65, s65, -1
	s_add_u32 s3, s3, 0x40000
	s_addc_u32 s67, s67, 0
	s_add_u32 s66, s66, 0x80000
	s_addc_u32 s78, s78, 0
	s_cmp_lg_u32 s65, 0
	s_waitcnt vmcnt(0) lgkmcnt(0)
	ds_write_b128 v110, v[86:89]
	flat_load_dwordx4 v[86:89], v[104:105] nt
	s_waitcnt vmcnt(0) lgkmcnt(0)
	ds_write_b128 v112, v[86:89]
	flat_load_dwordx4 v[86:89], v[108:109] nt
	s_waitcnt vmcnt(0) lgkmcnt(0)
	ds_write_b128 v90, v[86:89]
	flat_load_dwordx4 v[86:89], v[114:115] nt
	s_waitcnt vmcnt(0) lgkmcnt(0)
	ds_write_b128 v92, v[86:89]
	flat_load_dwordx4 v[86:89], v[116:117] nt
	s_waitcnt vmcnt(0) lgkmcnt(0)
	ds_write_b128 v94, v[86:89]
	flat_load_dwordx4 v[86:89], v[118:119] nt
	s_waitcnt vmcnt(0) lgkmcnt(0)
	ds_write_b128 v96, v[86:89]
	flat_load_dwordx4 v[86:89], v[120:121] nt
	s_waitcnt vmcnt(0) lgkmcnt(0)
	ds_write_b128 v98, v[86:89]
	flat_load_dwordx4 v[86:89], v[122:123] nt
	s_waitcnt vmcnt(0) lgkmcnt(0)
	v_cndmask_b32_e64 v90, v89, v88, s[24:25]
	v_cndmask_b32_e32 v92, v89, v88, vcc
	v_cndmask_b32_e64 v94, v89, v88, s[0:1]
	v_cndmask_b32_e64 v96, v89, v88, s[56:57]
	v_cndmask_b32_e64 v98, v89, v88, s[4:5]
	v_cndmask_b32_e64 v102, v89, v88, s[6:7]
	v_cndmask_b32_e64 v103, v89, v88, s[8:9]
	v_cndmask_b32_e64 v88, v89, v88, s[10:11]
	v_cndmask_b32_e64 v89, v90, v87, s[44:45]
	v_cndmask_b32_e64 v90, v92, v87, s[12:13]
	v_cndmask_b32_e64 v92, v94, v87, s[14:15]
	v_cndmask_b32_e64 v94, v96, v87, s[16:17]
	v_cndmask_b32_e64 v96, v98, v87, s[18:19]
	v_cndmask_b32_e64 v98, v102, v87, s[20:21]
	v_cndmask_b32_e64 v102, v103, v87, s[22:23]
	v_cndmask_b32_e64 v87, v88, v87, s[26:27]
	v_cndmask_b32_e64 v88, v89, v86, s[54:55]
	v_cndmask_b32_e64 v89, v90, v86, s[28:29]
	v_cndmask_b32_e64 v90, v92, v86, s[30:31]
	v_cndmask_b32_e64 v92, v94, v86, s[34:35]
	v_cndmask_b32_e64 v94, v96, v86, s[36:37]
	v_cndmask_b32_e64 v96, v98, v86, s[40:41]
	v_cndmask_b32_e64 v98, v102, v86, s[42:43]
	v_cndmask_b32_e64 v86, v87, v86, s[46:47]
	v_and_b32_e32 v87, 0xffff0000, v88
	v_lshlrev_b32_e32 v88, 16, v88
	v_cndmask_b32_e64 v87, v87, v88, s[52:53]
	v_and_b32_e32 v102, 0xffff0000, v89
	v_lshlrev_b32_e32 v89, 16, v89
	v_mul_f32_e32 v87, v100, v87
	v_and_b32_e32 v103, 0xffff0000, v90
	v_lshlrev_b32_e32 v90, 16, v90
	v_cndmask_b32_e64 v88, v89, v102, s[52:53]
	s_nop 1
	v_cvt_pk_bf16_f32 v87, v87, v65
	v_and_b32_e32 v104, 0xffff0000, v92
	v_lshlrev_b32_e32 v92, 16, v92
	v_cndmask_b32_e64 v89, v103, v90, s[52:53]
	v_mul_f32_e32 v88, v100, v88
	ds_write_b16 v91, v87
	s_nop 1
	v_cvt_pk_bf16_f32 v87, v88, v65
	v_and_b32_e32 v105, 0xffff0000, v94
	v_lshlrev_b32_e32 v94, 16, v94
	v_cndmask_b32_e64 v90, v104, v92, s[38:39]
	v_mul_f32_e32 v89, v100, v89
	ds_write_b16 v93, v87
	s_nop 1
	v_cvt_pk_bf16_f32 v87, v89, v65
	v_and_b32_e32 v106, 0xffff0000, v96
	v_lshlrev_b32_e32 v96, 16, v96
	v_and_b32_e32 v109, 0xffff0000, v86
	v_lshlrev_b32_e32 v86, 16, v86
	v_cndmask_b32_e64 v92, v105, v94, s[52:53]
	v_mul_f32_e32 v90, v100, v90
	ds_write_b16 v95, v87
	s_nop 1
	v_cvt_pk_bf16_f32 v87, v90, v65
	v_and_b32_e32 v108, 0xffff0000, v98
	v_lshlrev_b32_e32 v98, 16, v98
	v_cndmask_b32_e64 v94, v106, v96, s[48:49]
	v_cndmask_b32_e64 v86, v109, v86, s[50:51]
	v_mul_f32_e32 v92, v100, v92
	ds_write_b16 v97, v87
	s_nop 1
	v_cvt_pk_bf16_f32 v87, v92, v65
	v_cndmask_b32_e64 v96, v108, v98, s[52:53]
	v_mul_f32_e32 v94, v100, v94
	v_mul_f32_e32 v86, v100, v86
	ds_write_b16 v99, v87
	s_nop 1
	v_cvt_pk_bf16_f32 v87, v94, v65
	v_mul_f32_e32 v96, v100, v96
	ds_write_b16 v107, v87
	s_nop 1
	v_cvt_pk_bf16_f32 v87, v96, v65
	ds_write_b16 v111, v87
	s_nop 1
	v_cvt_pk_bf16_f32 v86, v86, v65
	ds_write_b16 v113, v86
	flat_load_dwordx4 v[86:89], v[124:125] nt
	s_waitcnt vmcnt(0) lgkmcnt(0)
; #define LAS __attribute__((address_space(3)))
; __device__ __forceinline__ unsigned cvt_pk_bf16(float lo, float hi) { unsigned r; asm volatile("s_nop 1\n\tv_cvt_pk_bf16_f32 %0, %1, %2" : "=v"(r) : "v"(lo), "v"(hi)); return r; }
; __device__ __forceinline__ void stage_kdT(ldsp dst, const bf16_t* src, float lg, int tid) {
;     ...
;     for (int ii = 0; ii < 4; ++ii) {
;         const int r = (tid >> 4) + 32 * ii;
;         const u32x4 v = *(const u32x4*)(src + (size_t)r * 1024 + c * 8);
;         const float dec = __builtin_amdgcn_exp2f((float)(127 - r) * lg);
; #pragma unroll
;         for (int e = 0; e < 8; ++e) {
;             const int ee = (e + c) & 7, q2 = ee >> 1;
;             const unsigned d = q2 == 0 ? v.x : (q2 == 1 ? v.y : (q2 == 2 ? v.z : v.w));
;             const float f = __uint_as_float((ee & 1) ? (d & 0xffff0000u) : (d << 16)) * dec;
;             *(LAS unsigned short*)(dst + (8 * c + ee) * 272 + r * 2) = (unsigned short)(cvt_pk_bf16(f, 0.f) & 0xffffu);
	v_cndmask_b32_e64 v90, v89, v88, s[24:25]
	v_cndmask_b32_e32 v91, v89, v88, vcc
	v_cndmask_b32_e64 v92, v89, v88, s[0:1]
	v_cndmask_b32_e64 v93, v89, v88, s[56:57]
	v_cndmask_b32_e64 v94, v89, v88, s[4:5]
	v_cndmask_b32_e64 v95, v89, v88, s[6:7]
	v_cndmask_b32_e64 v96, v89, v88, s[8:9]
	v_cndmask_b32_e64 v88, v89, v88, s[10:11]
	v_cndmask_b32_e64 v89, v90, v87, s[44:45]
	v_cndmask_b32_e64 v90, v91, v87, s[12:13]
	v_cndmask_b32_e64 v91, v92, v87, s[14:15]
	v_cndmask_b32_e64 v92, v93, v87, s[16:17]
	v_cndmask_b32_e64 v93, v94, v87, s[18:19]
	v_cndmask_b32_e64 v94, v95, v87, s[20:21]
	v_cndmask_b32_e64 v95, v96, v87, s[22:23]
	v_cndmask_b32_e64 v87, v88, v87, s[26:27]
	v_cndmask_b32_e64 v88, v89, v86, s[54:55]
	v_cndmask_b32_e64 v89, v90, v86, s[28:29]
	v_cndmask_b32_e64 v90, v91, v86, s[30:31]
	v_cndmask_b32_e64 v91, v92, v86, s[34:35]
	v_cndmask_b32_e64 v92, v93, v86, s[36:37]
	v_cndmask_b32_e64 v93, v94, v86, s[40:41]
	v_cndmask_b32_e64 v94, v95, v86, s[42:43]
	v_cndmask_b32_e64 v86, v87, v86, s[46:47]
	v_and_b32_e32 v87, 0xffff0000, v88
	v_lshlrev_b32_e32 v88, 16, v88
	v_cndmask_b32_e64 v87, v87, v88, s[52:53]
	v_and_b32_e32 v95, 0xffff0000, v89
	v_lshlrev_b32_e32 v89, 16, v89
	v_mul_f32_e32 v87, v101, v87
	v_and_b32_e32 v96, 0xffff0000, v90
	v_lshlrev_b32_e32 v90, 16, v90
	v_cndmask_b32_e64 v88, v89, v95, s[52:53]
	s_nop 1
	v_cvt_pk_bf16_f32 v87, v87, v65
	v_and_b32_e32 v97, 0xffff0000, v91
	v_lshlrev_b32_e32 v91, 16, v91
	v_cndmask_b32_e64 v89, v96, v90, s[52:53]
	v_mul_f32_e32 v88, v101, v88
	ds_write_b16 v159, v87
	s_nop 1
	v_cvt_pk_bf16_f32 v87, v88, v65
	v_and_b32_e32 v98, 0xffff0000, v92
	v_lshlrev_b32_e32 v92, 16, v92
	v_cndmask_b32_e64 v90, v97, v91, s[38:39]
	v_mul_f32_e32 v89, v101, v89
	ds_write_b16 v160, v87
	s_nop 1
	v_cvt_pk_bf16_f32 v87, v89, v65
	v_and_b32_e32 v99, 0xffff0000, v93
	v_lshlrev_b32_e32 v93, 16, v93
	v_and_b32_e32 v102, 0xffff0000, v86
	v_lshlrev_b32_e32 v86, 16, v86
	v_cndmask_b32_e64 v91, v98, v92, s[52:53]
	v_mul_f32_e32 v90, v101, v90
	ds_write_b16 v161, v87
	s_nop 1
	v_cvt_pk_bf16_f32 v87, v90, v65
	v_and_b32_e32 v100, 0xffff0000, v94
	v_lshlrev_b32_e32 v94, 16, v94
	v_cndmask_b32_e64 v92, v99, v93, s[48:49]
	v_cndmask_b32_e64 v86, v102, v86, s[50:51]
	v_mul_f32_e32 v91, v101, v91
	ds_write_b16 v162, v87
	s_nop 1
	v_cvt_pk_bf16_f32 v87, v91, v65
	v_cndmask_b32_e64 v93, v100, v94, s[52:53]
	v_mul_f32_e32 v92, v101, v92
	v_mul_f32_e32 v86, v101, v86
	ds_write_b16 v163, v87
	s_nop 1
	v_cvt_pk_bf16_f32 v87, v92, v65
	v_mul_f32_e32 v93, v101, v93
	ds_write_b16 v164, v87
	s_nop 1
	v_cvt_pk_bf16_f32 v87, v93, v65
	ds_write_b16 v165, v87
	s_nop 1
	v_cvt_pk_bf16_f32 v86, v86, v65
	ds_write_b16 v166, v86
	flat_load_dwordx4 v[86:89], v[126:127] nt
	s_waitcnt vmcnt(0) lgkmcnt(0)
	v_cndmask_b32_e64 v90, v89, v88, s[24:25]
	v_cndmask_b32_e32 v91, v89, v88, vcc
	v_cndmask_b32_e64 v92, v89, v88, s[0:1]
	v_cndmask_b32_e64 v93, v89, v88, s[56:57]
	v_cndmask_b32_e64 v94, v89, v88, s[4:5]
	v_cndmask_b32_e64 v95, v89, v88, s[6:7]
	v_cndmask_b32_e64 v96, v89, v88, s[8:9]
	v_cndmask_b32_e64 v88, v89, v88, s[10:11]
	v_cndmask_b32_e64 v89, v90, v87, s[44:45]
	v_cndmask_b32_e64 v90, v91, v87, s[12:13]
	v_cndmask_b32_e64 v91, v92, v87, s[14:15]
	v_cndmask_b32_e64 v92, v93, v87, s[16:17]
	v_cndmask_b32_e64 v93, v94, v87, s[18:19]
	v_cndmask_b32_e64 v94, v95, v87, s[20:21]
	v_cndmask_b32_e64 v95, v96, v87, s[22:23]
	v_cndmask_b32_e64 v87, v88, v87, s[26:27]
	v_cndmask_b32_e64 v88, v89, v86, s[54:55]
	v_cndmask_b32_e64 v89, v90, v86, s[28:29]
	v_cndmask_b32_e64 v90, v91, v86, s[30:31]
	v_cndmask_b32_e64 v91, v92, v86, s[34:35]
	v_cndmask_b32_e64 v92, v93, v86, s[36:37]
	v_cndmask_b32_e64 v93, v94, v86, s[40:41]
	v_cndmask_b32_e64 v94, v95, v86, s[42:43]
	v_cndmask_b32_e64 v86, v87, v86, s[46:47]
	v_and_b32_e32 v87, 0xffff0000, v88
	v_lshlrev_b32_e32 v88, 16, v88
	v_cndmask_b32_e64 v87, v87, v88, s[52:53]
	v_and_b32_e32 v95, 0xffff0000, v89
	v_lshlrev_b32_e32 v89, 16, v89
	v_mul_f32_e32 v87, v148, v87
	v_and_b32_e32 v96, 0xffff0000, v90
	v_lshlrev_b32_e32 v90, 16, v90
	v_cndmask_b32_e64 v88, v89, v95, s[52:53]
	s_nop 1
	v_cvt_pk_bf16_f32 v87, v87, v65
	v_and_b32_e32 v97, 0xffff0000, v91
	v_lshlrev_b32_e32 v91, 16, v91
	v_cndmask_b32_e64 v89, v96, v90, s[52:53]
	v_mul_f32_e32 v88, v148, v88
	ds_write_b16 v167, v87
	s_nop 1
	v_cvt_pk_bf16_f32 v87, v88, v65
	v_and_b32_e32 v98, 0xffff0000, v92
	v_lshlrev_b32_e32 v92, 16, v92
	v_cndmask_b32_e64 v90, v97, v91, s[38:39]
	v_mul_f32_e32 v89, v148, v89
	ds_write_b16 v168, v87
	s_nop 1
	v_cvt_pk_bf16_f32 v87, v89, v65
	v_and_b32_e32 v99, 0xffff0000, v93
	v_lshlrev_b32_e32 v93, 16, v93
	v_and_b32_e32 v101, 0xffff0000, v86
	v_lshlrev_b32_e32 v86, 16, v86
	v_cndmask_b32_e64 v91, v98, v92, s[52:53]
	v_mul_f32_e32 v90, v148, v90
	ds_write_b16 v169, v87
	s_nop 1
	v_cvt_pk_bf16_f32 v87, v90, v65
	v_and_b32_e32 v100, 0xffff0000, v94
	v_lshlrev_b32_e32 v94, 16, v94
	v_cndmask_b32_e64 v92, v99, v93, s[48:49]
	v_cndmask_b32_e64 v86, v101, v86, s[50:51]
	v_mul_f32_e32 v91, v148, v91
	ds_write_b16 v170, v87
	s_nop 1
	v_cvt_pk_bf16_f32 v87, v91, v65
	v_cndmask_b32_e64 v93, v100, v94, s[52:53]
	v_mul_f32_e32 v92, v148, v92
	v_mul_f32_e32 v86, v148, v86
	ds_write_b16 v171, v87
	s_nop 1
	v_cvt_pk_bf16_f32 v87, v92, v65
	v_mul_f32_e32 v93, v148, v93
	ds_write_b16 v172, v87
	s_nop 1
	v_cvt_pk_bf16_f32 v87, v93, v65
	ds_write_b16 v173, v87
	s_nop 1
	v_cvt_pk_bf16_f32 v86, v86, v65
	ds_write_b16 v156, v86
	flat_load_dwordx4 v[86:89], v[82:83] nt
	s_waitcnt vmcnt(0) lgkmcnt(0)
; #define LAS __attribute__((address_space(3)))
; __device__ __forceinline__ unsigned cvt_pk_bf16(float lo, float hi) { unsigned r; asm volatile("s_nop 1\n\tv_cvt_pk_bf16_f32 %0, %1, %2" : "=v"(r) : "v"(lo), "v"(hi)); return r; }
; #define MFMA16(a, b, c) __builtin_amdgcn_mfma_f32_16x16x32_bf16((a), (b), (c), 0, 0, 0)
; __device__ __forceinline__ void stage_kdT(ldsp dst, const bf16_t* src, float lg, int tid) {
;     ...
;         for (int e = 0; e < 8; ++e) {
;             const int ee = (e + c) & 7, q2 = ee >> 1;
;             const unsigned d = q2 == 0 ? v.x : (q2 == 1 ? v.y : (q2 == 2 ? v.z : v.w));
;             const float f = __uint_as_float((ee & 1) ? (d & 0xffff0000u) : (d << 16)) * dec;
;             *(LAS unsigned short*)(dst + (8 * c + ee) * 272 + r * 2) = (unsigned short)(cvt_pk_bf16(f, 0.f) & 0xffffu);
; __device__ __forceinline__ void ret_state_item(ldsp lds, int item, const bf16_t* vT, const bf16_t* kdT, float* L, float lg, int tid_, int w, int fr, int fq) {
;     ...
;         for (int ks = 0; ks < 4; ++ks) {
;             const bf16x8 a0 = frag(lds + RY, 32 * w + fr, ks, fq), a1 = frag(lds + RY, 32 * w + 16 + fr, ks, fq);
; #pragma unroll
;             for (int nt = 0; nt < 8; ++nt) { const bf16x8 bb = frag(lds + RX0, 16 * nt + fr, ks, fq); st[0][nt] = MFMA16(bb, a0, st[0][nt]); st[1][nt] = MFMA16(bb, a1, st[1][nt]); }
	v_cndmask_b32_e64 v82, v89, v88, s[24:25]
	v_cndmask_b32_e32 v83, v89, v88, vcc
	v_cndmask_b32_e64 v90, v89, v88, s[0:1]
	v_cndmask_b32_e64 v91, v89, v88, s[56:57]
	v_cndmask_b32_e64 v92, v89, v88, s[4:5]
	v_cndmask_b32_e64 v93, v89, v88, s[6:7]
	v_cndmask_b32_e64 v94, v89, v88, s[8:9]
	v_cndmask_b32_e64 v88, v89, v88, s[10:11]
	v_cndmask_b32_e64 v82, v82, v87, s[44:45]
	v_cndmask_b32_e64 v83, v83, v87, s[12:13]
	v_cndmask_b32_e64 v89, v90, v87, s[14:15]
	v_cndmask_b32_e64 v90, v91, v87, s[16:17]
	v_cndmask_b32_e64 v91, v92, v87, s[18:19]
	v_cndmask_b32_e64 v92, v93, v87, s[20:21]
	v_cndmask_b32_e64 v93, v94, v87, s[22:23]
	v_cndmask_b32_e64 v87, v88, v87, s[26:27]
	v_cndmask_b32_e64 v82, v82, v86, s[54:55]
	v_cndmask_b32_e64 v83, v83, v86, s[28:29]
	v_cndmask_b32_e64 v88, v89, v86, s[30:31]
	v_cndmask_b32_e64 v89, v90, v86, s[34:35]
	v_cndmask_b32_e64 v90, v91, v86, s[36:37]
	v_cndmask_b32_e64 v91, v92, v86, s[40:41]
	v_cndmask_b32_e64 v92, v93, v86, s[42:43]
	v_cndmask_b32_e64 v86, v87, v86, s[46:47]
	v_and_b32_e32 v87, 0xffff0000, v82
	v_lshlrev_b32_e32 v82, 16, v82
	v_cndmask_b32_e64 v82, v87, v82, s[52:53]
	v_and_b32_e32 v93, 0xffff0000, v83
	v_lshlrev_b32_e32 v83, 16, v83
	v_mul_f32_e32 v82, v154, v82
	v_and_b32_e32 v94, 0xffff0000, v88
	v_lshlrev_b32_e32 v88, 16, v88
	v_cndmask_b32_e64 v83, v83, v93, s[52:53]
	s_nop 1
	v_cvt_pk_bf16_f32 v82, v82, v65
	v_and_b32_e32 v95, 0xffff0000, v89
	v_lshlrev_b32_e32 v89, 16, v89
	v_cndmask_b32_e64 v87, v94, v88, s[52:53]
	v_mul_f32_e32 v83, v154, v83
	ds_write_b16 v174, v82
	s_nop 1
	v_cvt_pk_bf16_f32 v82, v83, v65
	v_and_b32_e32 v96, 0xffff0000, v90
	v_lshlrev_b32_e32 v90, 16, v90
	v_cndmask_b32_e64 v88, v95, v89, s[38:39]
	v_mul_f32_e32 v87, v154, v87
	ds_write_b16 v175, v82
	s_nop 1
	v_cvt_pk_bf16_f32 v82, v87, v65
	v_and_b32_e32 v97, 0xffff0000, v91
	v_lshlrev_b32_e32 v91, 16, v91
	v_cndmask_b32_e64 v89, v96, v90, s[52:53]
	v_mul_f32_e32 v88, v154, v88
	ds_write_b16 v176, v82
	s_nop 1
	v_cvt_pk_bf16_f32 v82, v88, v65
	v_and_b32_e32 v98, 0xffff0000, v92
	v_lshlrev_b32_e32 v92, 16, v92
	v_and_b32_e32 v99, 0xffff0000, v86
	v_lshlrev_b32_e32 v86, 16, v86
	v_cndmask_b32_e64 v90, v97, v91, s[48:49]
	v_mul_f32_e32 v89, v154, v89
	ds_write_b16 v149, v82
	s_nop 1
	v_cvt_pk_bf16_f32 v82, v89, v65
	v_cndmask_b32_e64 v91, v98, v92, s[52:53]
	v_cndmask_b32_e64 v86, v99, v86, s[50:51]
	v_mul_f32_e32 v90, v154, v90
	ds_write_b16 v150, v82
	s_nop 1
	v_cvt_pk_bf16_f32 v82, v90, v65
	v_mul_f32_e32 v91, v154, v91
	v_mul_f32_e32 v86, v154, v86
	ds_write_b16 v151, v82
	s_nop 1
	v_cvt_pk_bf16_f32 v82, v91, v65
	ds_write_b16 v152, v82
	s_nop 1
	v_cvt_pk_bf16_f32 v82, v86, v65
	ds_write_b16 v153, v82
	s_waitcnt lgkmcnt(0)
	s_barrier
	ds_read_b128 v[86:89], v85
	ds_read_b128 v[90:93], v64
	ds_read_b128 v[94:97], v64 offset:64
	ds_read_b128 v[98:101], v85 offset:64
	ds_read_b128 v[102:105], v64 offset:4352
	ds_read_b128 v[106:109], v64 offset:4416
	s_waitcnt lgkmcnt(4)
	v_mfma_f32_16x16x32_bf16 v[60:63], v[86:89], v[90:93], v[60:63]
	s_waitcnt lgkmcnt(1)
	v_mfma_f32_16x16x32_bf16 v[52:55], v[86:89], v[102:105], v[52:55]
	ds_read_b128 v[86:89], v85 offset:4352
	ds_read_b128 v[110:113], v85 offset:4416
	s_waitcnt lgkmcnt(1)
	v_mfma_f32_16x16x32_bf16 v[56:59], v[86:89], v[90:93], v[56:59]
	v_mfma_f32_16x16x32_bf16 v[24:27], v[86:89], v[102:105], v[24:27]
	ds_read_b128 v[86:89], v85 offset:8704
	ds_read_b128 v[114:117], v85 offset:8768
	s_waitcnt lgkmcnt(1)
	v_mfma_f32_16x16x32_bf16 v[44:47], v[86:89], v[90:93], v[44:47]
	v_mfma_f32_16x16x32_bf16 v[16:19], v[86:89], v[102:105], v[16:19]
	ds_read_b128 v[86:89], v85 offset:13056
	ds_read_b128 v[118:121], v85 offset:13120
	s_waitcnt lgkmcnt(1)
	v_mfma_f32_16x16x32_bf16 v[40:43], v[86:89], v[90:93], v[40:43]
	v_mfma_f32_16x16x32_bf16 v[12:15], v[86:89], v[102:105], v[12:15]
	ds_read_b128 v[86:89], v85 offset:17408
	ds_read_b128 v[122:125], v85 offset:17472
	s_waitcnt lgkmcnt(1)
	v_mfma_f32_16x16x32_bf16 v[36:39], v[86:89], v[90:93], v[36:39]
	v_mfma_f32_16x16x32_bf16 v[8:11], v[86:89], v[102:105], v[8:11]
	ds_read_b128 v[86:89], v85 offset:21760
	ds_read_b128 v[126:129], v85 offset:21824
	s_waitcnt lgkmcnt(1)
	v_mfma_f32_16x16x32_bf16 v[32:35], v[86:89], v[90:93], v[32:35]
	v_mfma_f32_16x16x32_bf16 v[4:7], v[86:89], v[102:105], v[4:7]
	ds_read_b128 v[86:89], v85 offset:26112
	ds_read_b128 v[130:133], v85 offset:26176
	s_waitcnt lgkmcnt(1)
	v_mfma_f32_16x16x32_bf16 v[20:23], v[86:89], v[90:93], v[20:23]
	v_mfma_f32_16x16x32_bf16 v[0:3], v[86:89], v[102:105], v[0:3]
	ds_read_b128 v[86:89], v85 offset:30464
	ds_read_b128 v[134:137], v85 offset:30528
	s_waitcnt lgkmcnt(1)
; #define MFMA16(a, b, c) __builtin_amdgcn_mfma_f32_16x16x32_bf16((a), (b), (c), 0, 0, 0)
; __device__ __forceinline__ void ret_state_item(ldsp lds, int item, const bf16_t* vT, const bf16_t* kdT, float* L, float lg, int tid_, int w, int fr, int fq) {
;     ...
;         for (int ks = 0; ks < 4; ++ks) {
;             const bf16x8 a0 = frag(lds + RY, 32 * w + fr, ks, fq), a1 = frag(lds + RY, 32 * w + 16 + fr, ks, fq);
; #pragma unroll
;             for (int nt = 0; nt < 8; ++nt) { const bf16x8 bb = frag(lds + RX0, 16 * nt + fr, ks, fq); st[0][nt] = MFMA16(bb, a0, st[0][nt]); st[1][nt] = MFMA16(bb, a1, st[1][nt]); }
;         }
;         __syncthreads();
;     }
;     float* Lp = L + (size_t)item * 32768;
; #pragma unroll
;     for (int mt = 0; mt < 2; ++mt)
; #pragma unroll
;         for (int nt = 0; nt < 8; ++nt) *(f32x4*)(Lp + (32 * w + 16 * mt + fr) * 128 + 16 * nt + 4 * fq) = st[mt][nt];
	v_mfma_f32_16x16x32_bf16 v[48:51], v[86:89], v[90:93], v[48:51]
	v_mfma_f32_16x16x32_bf16 v[28:31], v[86:89], v[102:105], v[28:31]
	ds_read_b128 v[86:89], v85 offset:128
	v_mfma_f32_16x16x32_bf16 v[60:63], v[98:101], v[94:97], v[60:63]
	v_mfma_f32_16x16x32_bf16 v[52:55], v[98:101], v[106:109], v[52:55]
	v_mfma_f32_16x16x32_bf16 v[56:59], v[110:113], v[94:97], v[56:59]
	v_mfma_f32_16x16x32_bf16 v[24:27], v[110:113], v[106:109], v[24:27]
	v_mfma_f32_16x16x32_bf16 v[44:47], v[114:117], v[94:97], v[44:47]
	v_mfma_f32_16x16x32_bf16 v[16:19], v[114:117], v[106:109], v[16:19]
	v_mfma_f32_16x16x32_bf16 v[40:43], v[118:121], v[94:97], v[40:43]
	v_mfma_f32_16x16x32_bf16 v[12:15], v[118:121], v[106:109], v[12:15]
	v_mfma_f32_16x16x32_bf16 v[36:39], v[122:125], v[94:97], v[36:39]
	v_mfma_f32_16x16x32_bf16 v[8:11], v[122:125], v[106:109], v[8:11]
	v_mfma_f32_16x16x32_bf16 v[32:35], v[126:129], v[94:97], v[32:35]
	v_mfma_f32_16x16x32_bf16 v[4:7], v[126:129], v[106:109], v[4:7]
	v_mfma_f32_16x16x32_bf16 v[20:23], v[130:133], v[94:97], v[20:23]
	v_mfma_f32_16x16x32_bf16 v[0:3], v[130:133], v[106:109], v[0:3]
	s_waitcnt lgkmcnt(1)
	v_mfma_f32_16x16x32_bf16 v[48:51], v[134:137], v[94:97], v[48:51]
	ds_read_b128 v[90:93], v64 offset:128
	ds_read_b128 v[94:97], v64 offset:192
	ds_read_b128 v[98:101], v85 offset:192
	v_mfma_f32_16x16x32_bf16 v[28:31], v[134:137], v[106:109], v[28:31]
	ds_read_b128 v[102:105], v64 offset:4480
	ds_read_b128 v[106:109], v64 offset:4544
	s_waitcnt lgkmcnt(4)
	v_mfma_f32_16x16x32_bf16 v[60:63], v[86:89], v[90:93], v[60:63]
	s_waitcnt lgkmcnt(1)
	v_mfma_f32_16x16x32_bf16 v[52:55], v[86:89], v[102:105], v[52:55]
	ds_read_b128 v[86:89], v85 offset:4480
	ds_read_b128 v[110:113], v85 offset:4544
	s_waitcnt lgkmcnt(1)
	v_mfma_f32_16x16x32_bf16 v[56:59], v[86:89], v[90:93], v[56:59]
	v_mfma_f32_16x16x32_bf16 v[24:27], v[86:89], v[102:105], v[24:27]
	ds_read_b128 v[86:89], v85 offset:8832
	ds_read_b128 v[114:117], v85 offset:8896
	s_waitcnt lgkmcnt(1)
	v_mfma_f32_16x16x32_bf16 v[44:47], v[86:89], v[90:93], v[44:47]
	v_mfma_f32_16x16x32_bf16 v[16:19], v[86:89], v[102:105], v[16:19]
	ds_read_b128 v[86:89], v85 offset:13184
	ds_read_b128 v[118:121], v85 offset:13248
	s_waitcnt lgkmcnt(1)
	v_mfma_f32_16x16x32_bf16 v[40:43], v[86:89], v[90:93], v[40:43]
	v_mfma_f32_16x16x32_bf16 v[12:15], v[86:89], v[102:105], v[12:15]
	ds_read_b128 v[86:89], v85 offset:17536
	ds_read_b128 v[122:125], v85 offset:17600
	s_waitcnt lgkmcnt(1)
	v_mfma_f32_16x16x32_bf16 v[36:39], v[86:89], v[90:93], v[36:39]
	v_mfma_f32_16x16x32_bf16 v[8:11], v[86:89], v[102:105], v[8:11]
	ds_read_b128 v[86:89], v85 offset:21888
	ds_read_b128 v[126:129], v85 offset:21952
	s_waitcnt lgkmcnt(1)
	v_mfma_f32_16x16x32_bf16 v[32:35], v[86:89], v[90:93], v[32:35]
	v_mfma_f32_16x16x32_bf16 v[4:7], v[86:89], v[102:105], v[4:7]
	ds_read_b128 v[86:89], v85 offset:26240
	ds_read_b128 v[130:133], v85 offset:26304
	s_waitcnt lgkmcnt(1)
	v_mfma_f32_16x16x32_bf16 v[20:23], v[86:89], v[90:93], v[20:23]
	v_mfma_f32_16x16x32_bf16 v[0:3], v[86:89], v[102:105], v[0:3]
	ds_read_b128 v[86:89], v85 offset:30592
	ds_read_b128 v[134:137], v85 offset:30656
	s_waitcnt lgkmcnt(0)
	s_barrier
	v_mfma_f32_16x16x32_bf16 v[48:51], v[86:89], v[90:93], v[48:51]
	v_mfma_f32_16x16x32_bf16 v[28:31], v[86:89], v[102:105], v[28:31]
	v_mfma_f32_16x16x32_bf16 v[60:63], v[98:101], v[94:97], v[60:63]
	v_mfma_f32_16x16x32_bf16 v[52:55], v[98:101], v[106:109], v[52:55]
	v_mfma_f32_16x16x32_bf16 v[56:59], v[110:113], v[94:97], v[56:59]
	v_mfma_f32_16x16x32_bf16 v[24:27], v[110:113], v[106:109], v[24:27]
	v_mfma_f32_16x16x32_bf16 v[44:47], v[114:117], v[94:97], v[44:47]
	v_mfma_f32_16x16x32_bf16 v[16:19], v[114:117], v[106:109], v[16:19]
	v_mfma_f32_16x16x32_bf16 v[40:43], v[118:121], v[94:97], v[40:43]
	v_mfma_f32_16x16x32_bf16 v[12:15], v[118:121], v[106:109], v[12:15]
	v_mfma_f32_16x16x32_bf16 v[36:39], v[122:125], v[94:97], v[36:39]
	v_mfma_f32_16x16x32_bf16 v[8:11], v[122:125], v[106:109], v[8:11]
	v_mfma_f32_16x16x32_bf16 v[32:35], v[126:129], v[94:97], v[32:35]
	v_mfma_f32_16x16x32_bf16 v[4:7], v[126:129], v[106:109], v[4:7]
	v_mfma_f32_16x16x32_bf16 v[20:23], v[130:133], v[94:97], v[20:23]
	v_mfma_f32_16x16x32_bf16 v[0:3], v[130:133], v[106:109], v[0:3]
	v_mfma_f32_16x16x32_bf16 v[48:51], v[134:137], v[94:97], v[48:51]
	v_mfma_f32_16x16x32_bf16 v[28:31], v[134:137], v[106:109], v[28:31]
	s_cbranch_scc1 .LBB0_431
	s_ashr_i32 s65, s64, 31
	s_lshl_b64 s[0:1], s[64:65], 17
	v_lshl_add_u64 v[78:79], v[66:67], 0, s[0:1]
	flat_store_dwordx4 v[78:79], v[60:63]
	flat_store_dwordx4 v[78:79], v[56:59] offset:64
	flat_store_dwordx4 v[78:79], v[44:47] offset:128
	flat_store_dwordx4 v[78:79], v[40:43] offset:192
	flat_store_dwordx4 v[78:79], v[36:39] offset:256
	flat_store_dwordx4 v[78:79], v[32:35] offset:320
	flat_store_dwordx4 v[78:79], v[20:23] offset:384
	flat_store_dwordx4 v[78:79], v[48:51] offset:448
	s_nop 0
	v_add_co_u32_e32 v20, vcc, 0x2000, v78
	s_nop 1
	v_addc_co_u32_e32 v21, vcc, 0, v79, vcc
	flat_store_dwordx4 v[20:21], v[52:55]
	flat_store_dwordx4 v[20:21], v[24:27] offset:64
	flat_store_dwordx4 v[20:21], v[16:19] offset:128
	flat_store_dwordx4 v[20:21], v[12:15] offset:192
	flat_store_dwordx4 v[20:21], v[8:11] offset:256
	flat_store_dwordx4 v[20:21], v[4:7] offset:320
	flat_store_dwordx4 v[20:21], v[0:3] offset:384
	flat_store_dwordx4 v[20:21], v[28:31] offset:448
	s_branch .LBB0_428

; #define LAS __attribute__((address_space(3)))
; #define MFMA16(a, b, c) __builtin_amdgcn_mfma_f32_16x16x32_bf16((a), (b), (c), 0, 0, 0)
; __device__ __forceinline__ void attn_item(ldsp lds, int item, bf16_t* aq, const bf16_t* ak, const bf16_t* avT, const float* sinks, int tid, int w, int fr, int fq) {
;     ...
; #pragma unroll
;         for (int tt = 0; tt < 10; ++tt) { s[tt] = (f32x4){0.f, 0.f, 0.f, 0.f};
;             const bf16x8 b0 = *(const LAS bf16x8*)(Kb + (16 * (r + tt) + fr) * 144 + fq * 16), b1 = *(const LAS bf16x8*)(Kb + (16 * (r + tt) + fr) * 144 + 64 + fq * 16);
;             s[tt] = MFMA16(b0, a0, s[tt]); s[tt] = MFMA16(b1, a1, s[tt]); }
;         const float sink2 = sinks[hq] * LOG2E; float mx = sink2;
; #pragma unroll
;         for (int tt = 0; tt < 10; ++tt)
; #pragma unroll
;             for (int j = 0; j < 4; ++j) { const int kr = 16 * tt + 4 * fq + j; const bool valid = (kr > fr) && (kr <= fr + 128) && (n > 0 || 16 * r + kr >= 128);
;                 s[tt][j] = valid ? s[tt][j] : -INFINITY; mx = fmaxf(mx, s[tt][j]); }
.LBB0_435:
	s_or_b64 exec, exec, s[4:5]
	v_mov_b32_e32 v89, v65
	v_add_u32_e32 v64, v96, v93
	s_waitcnt lgkmcnt(0)
	s_barrier
	v_lshl_add_u64 v[90:91], v[34:35], 0, v[88:89]
	ds_read_b128 v[28:31], v64
	ds_read_b128 v[32:35], v64 offset:64
	s_waitcnt lgkmcnt(1)
	v_mfma_f32_16x16x32_bf16 v[28:31], v[28:31], v[24:27], 0
	s_lshl_b32 s4, s10, 4
	s_add_u32 s4, s11, s4
	s_addc_u32 s5, s12, 0
	s_waitcnt lgkmcnt(0)
	v_mfma_f32_16x16x32_bf16 v[124:127], v[32:35], v[48:51], v[28:31]
	s_nop 2
	ds_read_b128 v[28:31], v104
	ds_read_b128 v[32:35], v104 offset:64
	v_readlane_b32 s8, v254, 27
	v_readlane_b32 s9, v254, 28
	s_waitcnt lgkmcnt(1)
	v_mfma_f32_16x16x32_bf16 v[28:31], v[28:31], v[24:27], 0
	v_readlane_b32 s12, v254, 31
	v_readlane_b32 s13, v254, 32
	v_readlane_b32 s72, v255, 23
	s_waitcnt lgkmcnt(0)
	v_mfma_f32_16x16x32_bf16 v[56:59], v[32:35], v[48:51], v[28:31]
	s_nop 2
	ds_read_b128 v[28:31], v105
	ds_read_b128 v[32:35], v105 offset:64
	v_readlane_b32 s73, v255, 24
	s_or_b64 s[78:79], s[70:71], s[72:73]
	s_waitcnt lgkmcnt(1)
	v_mfma_f32_16x16x32_bf16 v[28:31], v[28:31], v[24:27], 0
	v_readlane_b32 s72, v255, 25
	v_readlane_b32 s73, v255, 26
	s_or_b64 s[80:81], s[70:71], s[72:73]
	s_waitcnt lgkmcnt(0)
	v_mfma_f32_16x16x32_bf16 v[52:55], v[32:35], v[48:51], v[28:31]
	s_nop 2
	ds_read_b128 v[28:31], v106
	ds_read_b128 v[32:35], v106 offset:64
	v_readlane_b32 s72, v255, 27
	v_readlane_b32 s73, v255, 28
	s_waitcnt lgkmcnt(1)
	v_mfma_f32_16x16x32_bf16 v[28:31], v[28:31], v[24:27], 0
	s_or_b64 s[76:77], s[70:71], s[72:73]
	v_readlane_b32 s72, v255, 29
	v_readlane_b32 s73, v255, 30
	s_waitcnt lgkmcnt(0)
	v_mfma_f32_16x16x32_bf16 v[44:47], v[32:35], v[48:51], v[28:31]
	s_nop 2
	ds_read_b128 v[28:31], v107
	ds_read_b128 v[32:35], v107 offset:64
	s_or_b64 s[74:75], s[70:71], s[72:73]
	s_or_b64 s[72:73], s[70:71], s[96:97]
	s_waitcnt lgkmcnt(1)
	v_mfma_f32_16x16x32_bf16 v[28:31], v[28:31], v[24:27], 0
	s_add_i32 s92, s92, s33
	s_waitcnt lgkmcnt(0)
	v_mfma_f32_16x16x32_bf16 v[40:43], v[32:35], v[48:51], v[28:31]
	s_nop 4
	ds_read_b128 v[28:31], v108
	ds_read_b128 v[32:35], v108 offset:64
	s_waitcnt lgkmcnt(1)
	v_mfma_f32_16x16x32_bf16 v[28:31], v[28:31], v[24:27], 0
	s_waitcnt lgkmcnt(0)
	v_mfma_f32_16x16x32_bf16 v[36:39], v[32:35], v[48:51], v[28:31]
	s_nop 5
	ds_read_b128 v[28:31], v109
	ds_read_b128 v[32:35], v109 offset:64
	s_waitcnt lgkmcnt(1)
	v_mfma_f32_16x16x32_bf16 v[28:31], v[28:31], v[24:27], 0
	s_waitcnt lgkmcnt(0)
	v_mfma_f32_16x16x32_bf16 v[32:35], v[32:35], v[48:51], v[28:31]
	s_nop 5
	ds_read_b128 v[28:31], v110
	ds_read_b128 v[128:131], v110 offset:64
	s_waitcnt lgkmcnt(1)
	v_mfma_f32_16x16x32_bf16 v[28:31], v[28:31], v[24:27], 0
	s_waitcnt lgkmcnt(0)
	v_mfma_f32_16x16x32_bf16 v[28:31], v[128:131], v[48:51], v[28:31]
	ds_read_b128 v[128:131], v111
	ds_read_b128 v[132:135], v111 offset:64
	s_waitcnt lgkmcnt(1)
	v_mfma_f32_16x16x32_bf16 v[24:27], v[128:131], v[24:27], 0
	s_nop 3
	v_cndmask_b32_e64 v30, v118, v30, s[78:79]
	v_cndmask_b32_e64 v31, v118, v31, s[80:81]
	s_waitcnt lgkmcnt(0)
	v_mfma_f32_16x16x32_bf16 v[24:27], v[132:135], v[48:51], v[24:27]
	v_mov_b64_e32 v[48:49], s[4:5]
	flat_load_dword v50, v[48:49] nt
	v_readlane_b32 s4, v254, 23
	v_readlane_b32 s5, v254, 24
	s_or_b64 s[4:5], s[70:71], s[4:5]
	s_and_b64 s[6:7], s[14:15], s[4:5]
	v_readlane_b32 s4, v254, 25
	v_readlane_b32 s5, v254, 26
	s_or_b64 s[10:11], s[70:71], s[4:5]
	v_readlane_b32 s4, v254, 29
	v_readlane_b32 s5, v254, 30
	s_or_b64 s[4:5], s[70:71], s[4:5]
	s_and_b64 s[8:9], s[8:9], s[4:5]
	v_readlane_b32 s4, v254, 33
	v_readlane_b32 s5, v254, 34
	s_or_b64 s[4:5], s[70:71], s[4:5]
	s_and_b64 s[4:5], s[12:13], s[4:5]
	v_readlane_b32 s12, v254, 35
	v_readlane_b32 s13, v254, 36
	s_or_b64 s[40:41], s[70:71], s[12:13]
	v_readlane_b32 s12, v254, 37
	v_readlane_b32 s13, v254, 38
	s_or_b64 s[28:29], s[70:71], s[12:13]
	v_readlane_b32 s12, v254, 39
	v_readlane_b32 s13, v254, 40
	s_or_b64 s[38:39], s[70:71], s[12:13]
	v_readlane_b32 s12, v254, 41
	v_readlane_b32 s13, v254, 42
	s_or_b64 s[44:45], s[70:71], s[12:13]
	v_readlane_b32 s12, v254, 43
	v_readlane_b32 s13, v254, 44
	s_or_b64 s[34:35], s[70:71], s[12:13]
	v_readlane_b32 s12, v254, 45
	v_readlane_b32 s13, v254, 46
	s_or_b64 s[22:23], s[70:71], s[12:13]
	v_readlane_b32 s12, v254, 47
	v_readlane_b32 s13, v254, 48
	s_or_b64 s[30:31], s[70:71], s[12:13]
	v_readlane_b32 s12, v254, 49
	v_readlane_b32 s13, v254, 50
	s_or_b64 s[42:43], s[70:71], s[12:13]
	v_readlane_b32 s12, v254, 51
	v_readlane_b32 s13, v254, 52
	s_or_b64 s[26:27], s[70:71], s[12:13]
	v_readlane_b32 s12, v254, 53
	v_readlane_b32 s13, v254, 54
	s_or_b64 s[16:17], s[70:71], s[12:13]
	v_readlane_b32 s12, v254, 55
	v_readlane_b32 s13, v254, 56
	s_or_b64 s[24:25], s[70:71], s[12:13]
	v_readlane_b32 s12, v254, 57
	v_readlane_b32 s13, v254, 58
	s_or_b64 s[36:37], s[70:71], s[12:13]
	v_readlane_b32 s12, v254, 59
	v_readlane_b32 s13, v254, 60
	s_or_b64 s[20:21], s[70:71], s[12:13]
	v_readlane_b32 s12, v254, 61
	v_readlane_b32 s13, v254, 62
	s_or_b64 s[66:67], s[70:71], s[12:13]
	v_readlane_b32 s12, v254, 63
	v_readlane_b32 s13, v255, 0
	s_or_b64 s[68:69], s[70:71], s[12:13]
	v_readlane_b32 s12, v255, 1
	v_readlane_b32 s13, v255, 2
	s_or_b64 s[64:65], s[70:71], s[12:13]
	v_readlane_b32 s12, v255, 3
	v_readlane_b32 s13, v255, 4
	s_or_b64 s[62:63], s[70:71], s[12:13]
	v_readlane_b32 s12, v255, 5
	v_readlane_b32 s13, v255, 6
	v_cndmask_b32_e64 v89, v118, v124, s[6:7]
	s_or_b64 s[58:59], s[70:71], s[12:13]
	v_readlane_b32 s12, v255, 7
	v_max_f32_e32 v119, v89, v89
	v_readlane_b32 s13, v255, 8
	s_or_b64 s[60:61], s[70:71], s[12:13]
	v_readlane_b32 s12, v255, 9
	v_cndmask_b32_e64 v124, v118, v126, s[8:9]
	v_readlane_b32 s13, v255, 10
	v_cndmask_b32_e64 v56, v118, v56, s[40:41]
	s_or_b64 s[56:57], s[70:71], s[12:13]
	s_waitcnt vmcnt(0) lgkmcnt(0)
; __device__ __forceinline__ float shx(float v, int o, int lane) { return __int_as_float(__builtin_amdgcn_ds_bpermute((lane ^ o) << 2, __float_as_int(v))); }
; __device__ __forceinline__ void attn_item(ldsp lds, int item, bf16_t* aq, const bf16_t* ak, const bf16_t* avT, const float* sinks, int tid, int w, int fr, int fq) {
;     ...
;         const float sink2 = sinks[hq] * LOG2E; float mx = sink2;
; #pragma unroll
;         for (int tt = 0; tt < 10; ++tt)
; #pragma unroll
;             for (int j = 0; j < 4; ++j) { const int kr = 16 * tt + 4 * fq + j; const bool valid = (kr > fr) && (kr <= fr + 128) && (n > 0 || 16 * r + kr >= 128);
;                 s[tt][j] = valid ? s[tt][j] : -INFINITY; mx = fmaxf(mx, s[tt][j]); }
;         const int ln = fr + 16 * fq;
;         mx = fmaxf(mx, shx(mx, 16, ln)); mx = fmaxf(mx, shx(mx, 32, ln));
;         float sum = 0.f;
; #pragma unroll
;         for (int tt = 0; tt < 10; ++tt)
; #pragma unroll
;             for (int j = 0; j < 4; ++j) { s[tt][j] = __builtin_amdgcn_exp2f(s[tt][j] - mx); sum += s[tt][j]; }
;         sum += shx(sum, 16, ln); sum += shx(sum, 32, ln);
	v_mul_f32_e32 v51, 0x3fb8aa3b, v50
	v_max_f32_e32 v51, v51, v119
	v_cndmask_b32_e64 v119, v118, v125, s[10:11]
	v_cndmask_b32_e64 v119, v119, v118, s[18:19]
	v_max3_f32 v51, v51, v119, v124
	v_cndmask_b32_e64 v125, v118, v127, s[4:5]
	v_readlane_b32 s12, v255, 11
	v_max3_f32 v51, v51, v125, v56
	v_cndmask_b32_e64 v57, v118, v57, s[28:29]
	v_cndmask_b32_e64 v58, v118, v58, s[38:39]
	v_readlane_b32 s13, v255, 12
	v_max3_f32 v51, v51, v57, v58
	v_cndmask_b32_e64 v59, v118, v59, s[44:45]
	v_cndmask_b32_e64 v52, v118, v52, s[34:35]
	s_or_b64 s[54:55], s[70:71], s[12:13]
	v_readlane_b32 s12, v255, 13
	v_max3_f32 v51, v51, v59, v52
	v_cndmask_b32_e64 v53, v118, v53, s[22:23]
	v_cndmask_b32_e64 v54, v118, v54, s[30:31]
	v_readlane_b32 s13, v255, 14
	v_max3_f32 v51, v51, v53, v54
	v_cndmask_b32_e64 v55, v118, v55, s[42:43]
	v_cndmask_b32_e64 v44, v118, v44, s[26:27]
	s_or_b64 s[48:49], s[70:71], s[12:13]
	v_readlane_b32 s12, v255, 15
	v_max3_f32 v51, v51, v55, v44
	v_cndmask_b32_e64 v45, v118, v45, s[16:17]
	v_cndmask_b32_e64 v46, v118, v46, s[24:25]
	v_readlane_b32 s13, v255, 16
	v_max3_f32 v51, v51, v45, v46
	v_cndmask_b32_e64 v47, v118, v47, s[36:37]
	v_cndmask_b32_e64 v40, v118, v40, s[20:21]
	s_or_b64 s[52:53], s[70:71], s[12:13]
	v_readlane_b32 s12, v255, 17
	v_max3_f32 v51, v51, v47, v40
	v_cndmask_b32_e64 v41, v118, v41, s[66:67]
	v_cndmask_b32_e64 v42, v118, v42, s[68:69]
	v_readlane_b32 s13, v255, 18
	v_max3_f32 v51, v51, v41, v42
	v_cndmask_b32_e64 v43, v118, v43, s[64:65]
	v_cndmask_b32_e64 v36, v118, v36, s[62:63]
	s_or_b64 s[46:47], s[70:71], s[12:13]
	v_readlane_b32 s12, v255, 19
	v_max3_f32 v51, v51, v43, v36
	v_cndmask_b32_e64 v37, v118, v37, s[58:59]
	v_cndmask_b32_e64 v38, v118, v38, s[60:61]
	v_readlane_b32 s13, v255, 20
	v_max3_f32 v51, v51, v37, v38
	v_cndmask_b32_e64 v39, v118, v39, s[56:57]
	v_cndmask_b32_e64 v32, v118, v32, s[54:55]
	s_or_b64 s[50:51], s[70:71], s[12:13]
	v_readlane_b32 s12, v255, 21
	v_max3_f32 v51, v51, v39, v32
	v_cndmask_b32_e64 v33, v118, v33, s[48:49]
	v_cndmask_b32_e64 v34, v118, v34, s[52:53]
	v_readlane_b32 s13, v255, 22
	v_max3_f32 v51, v51, v33, v34
	v_cndmask_b32_e64 v35, v118, v35, s[46:47]
	v_cndmask_b32_e64 v28, v118, v28, s[50:51]
	s_or_b64 s[12:13], s[70:71], s[12:13]
	v_max3_f32 v51, v51, v35, v28
	v_cndmask_b32_e64 v29, v118, v29, s[12:13]
	v_cndmask_b32_e64 v24, v118, v24, s[76:77]
	v_max3_f32 v51, v51, v29, v30
	v_cndmask_b32_e64 v24, v24, v118, s[14:15]
	v_cndmask_b32_e64 v25, v118, v25, s[74:75]
	v_cndmask_b32_e64 v26, v118, v26, s[72:73]
	s_or_b64 s[70:71], s[70:71], s[82:83]
	v_max3_f32 v51, v51, v31, v24
	v_cndmask_b32_e64 v25, v25, v118, s[90:91]
	v_cndmask_b32_e64 v26, v26, v118, s[94:95]
	v_cndmask_b32_e64 v27, v118, v27, s[70:71]
	v_max3_f32 v51, v51, v25, v26
	v_cndmask_b32_e64 v27, v27, v118, s[0:1]
	v_max3_f32 v51, v51, v27, s89
	ds_bpermute_b32 v126, v94, v51
	s_waitcnt lgkmcnt(0)
	v_max_f32_e32 v126, v126, v126
	v_max_f32_e32 v51, v51, v126
	ds_bpermute_b32 v126, v95, v51
	s_waitcnt lgkmcnt(0)
	v_max_f32_e32 v126, v126, v126
	v_max_f32_e32 v51, v51, v126
	v_sub_f32_e32 v89, v89, v51
	v_exp_f32_e32 v89, v89
	v_sub_f32_e32 v119, v119, v51
	v_exp_f32_e32 v119, v119
	v_sub_f32_e32 v124, v124, v51
	v_exp_f32_e32 v124, v124
	v_sub_f32_e32 v125, v125, v51
	v_exp_f32_e32 v125, v125
	v_sub_f32_e32 v56, v56, v51
	v_add_f32_e32 v126, 0, v89
	v_exp_f32_e32 v56, v56
	v_sub_f32_e32 v57, v57, v51
	v_add_f32_e32 v126, v119, v126
	v_exp_f32_e32 v57, v57
	v_sub_f32_e32 v58, v58, v51
	v_add_f32_e32 v126, v124, v126
	v_exp_f32_e32 v58, v58
	v_sub_f32_e32 v59, v59, v51
	v_add_f32_e32 v126, v125, v126
	v_exp_f32_e32 v59, v59
	v_sub_f32_e32 v52, v52, v51
	v_add_f32_e32 v126, v56, v126
	v_exp_f32_e32 v52, v52
	v_sub_f32_e32 v53, v53, v51
	v_add_f32_e32 v126, v57, v126
	v_exp_f32_e32 v53, v53
	v_sub_f32_e32 v54, v54, v51
	v_add_f32_e32 v126, v58, v126
	v_exp_f32_e32 v54, v54
	v_sub_f32_e32 v55, v55, v51
	v_add_f32_e32 v126, v59, v126
	v_exp_f32_e32 v55, v55
	v_sub_f32_e32 v44, v44, v51
	v_add_f32_e32 v126, v52, v126
	v_exp_f32_e32 v44, v44
	v_sub_f32_e32 v45, v45, v51
	v_add_f32_e32 v126, v53, v126
	v_exp_f32_e32 v45, v45
	v_sub_f32_e32 v46, v46, v51
	v_add_f32_e32 v126, v54, v126
	v_exp_f32_e32 v46, v46
	v_sub_f32_e32 v47, v47, v51
	v_add_f32_e32 v126, v55, v126
	v_exp_f32_e32 v47, v47
	v_sub_f32_e32 v40, v40, v51
	v_add_f32_e32 v126, v44, v126
	v_exp_f32_e32 v40, v40
	v_sub_f32_e32 v41, v41, v51
	v_add_f32_e32 v126, v45, v126
	v_exp_f32_e32 v41, v41
	v_sub_f32_e32 v42, v42, v51
	v_add_f32_e32 v126, v46, v126
	v_exp_f32_e32 v42, v42
	v_sub_f32_e32 v43, v43, v51
	v_add_f32_e32 v126, v47, v126
	v_exp_f32_e32 v43, v43
	v_sub_f32_e32 v36, v36, v51
	v_add_f32_e32 v126, v40, v126
	v_exp_f32_e32 v36, v36
	v_sub_f32_e32 v37, v37, v51
	v_add_f32_e32 v126, v41, v126
	v_exp_f32_e32 v37, v37
	v_sub_f32_e32 v38, v38, v51
	v_add_f32_e32 v126, v42, v126
	v_exp_f32_e32 v38, v38
	v_sub_f32_e32 v39, v39, v51
	v_add_f32_e32 v126, v43, v126
	v_exp_f32_e32 v39, v39
	v_sub_f32_e32 v32, v32, v51
	v_add_f32_e32 v126, v36, v126
	v_exp_f32_e32 v32, v32
	v_sub_f32_e32 v33, v33, v51
	v_add_f32_e32 v126, v37, v126
	v_exp_f32_e32 v33, v33
	v_sub_f32_e32 v34, v34, v51
	v_add_f32_e32 v126, v38, v126
	v_exp_f32_e32 v34, v34
	v_sub_f32_e32 v35, v35, v51
	v_add_f32_e32 v126, v39, v126
	v_exp_f32_e32 v35, v35
	v_sub_f32_e32 v28, v28, v51
	v_add_f32_e32 v126, v32, v126
	v_exp_f32_e32 v28, v28
	v_sub_f32_e32 v29, v29, v51
	v_add_f32_e32 v126, v33, v126
	v_exp_f32_e32 v29, v29
	v_sub_f32_e32 v30, v30, v51
	v_add_f32_e32 v126, v34, v126
	v_exp_f32_e32 v30, v30
	v_sub_f32_e32 v31, v31, v51
	v_add_f32_e32 v126, v35, v126
	v_exp_f32_e32 v31, v31
	v_sub_f32_e32 v24, v24, v51
	v_add_f32_e32 v126, v28, v126
	v_exp_f32_e32 v127, v24
	v_add_f32_e32 v126, v29, v126
	v_add_f32_e32 v126, v30, v126
	v_add_f32_e32 v126, v31, v126
	v_sub_f32_e32 v25, v25, v51
	v_add_f32_e32 v24, v127, v126
	v_exp_f32_e32 v126, v25
	v_sub_f32_e32 v25, v26, v51
	v_exp_f32_e32 v26, v25
	v_sub_f32_e32 v25, v27, v51
	v_exp_f32_e32 v27, v25
	v_sub_f32_e32 v25, 0xff800000, v51
	v_exp_f32_e32 v128, v25
	v_add_f32_e32 v24, v126, v24
	v_add_f32_e32 v24, v26, v24
	v_add_f32_e32 v24, v27, v24
	v_add_f32_e32 v24, v128, v24
	v_add_f32_e32 v24, v128, v24
	v_add_f32_e32 v24, v128, v24
	v_add_f32_e32 v24, v128, v24
	ds_bpermute_b32 v25, v94, v24
	s_waitcnt lgkmcnt(0)
; #define LAS __attribute__((address_space(3)))
; __device__ __forceinline__ unsigned cvt_pk_bf16(float lo, float hi) { unsigned r; asm volatile("s_nop 1\n\tv_cvt_pk_bf16_f32 %0, %1, %2" : "=v"(r) : "v"(lo), "v"(hi)); return r; }
; __device__ __forceinline__ float shx(float v, int o, int lane) { return __int_as_float(__builtin_amdgcn_ds_bpermute((lane ^ o) << 2, __float_as_int(v))); }
; #define MFMA16(a, b, c) __builtin_amdgcn_mfma_f32_16x16x32_bf16((a), (b), (c), 0, 0, 0)
; __device__ __forceinline__ void attn_item(ldsp lds, int item, bf16_t* aq, const bf16_t* ak, const bf16_t* avT, const float* sinks, int tid, int w, int fr, int fq) {
;     ...
;         sum += shx(sum, 16, ln); sum += shx(sum, 32, ln);
;         const float inv = 1.0f / (sum + __builtin_amdgcn_exp2f(sink2 - mx));
; #pragma unroll
;         for (int tt = 0; tt < 10; ++tt) { u32x2 wv; wv.x = cvt_pk_bf16(s[tt][0] * inv, s[tt][1] * inv); wv.y = cvt_pk_bf16(s[tt][2] * inv, s[tt][3] * inv);
;             *(LAS u32x2*)(Pb + fr * 336 + (16 * tt + 4 * fq) * 2) = wv; }
;         asm volatile("s_waitcnt lgkmcnt(0)" ::: "memory");
;         f32x4 o[4];
; #pragma unroll
;         for (int nt = 0; nt < 4; ++nt) o[nt] = (f32x4){0.f, 0.f, 0.f, 0.f};
; #pragma unroll
;         for (int ks = 0; ks < 5; ++ks) {
;             const bf16x8 a = *(const LAS bf16x8*)(Pb + fr * 336 + ks * 64 + fq * 16);
; #pragma unroll
;             for (int nt = 0; nt < 4; ++nt) o[nt] = MFMA16(*(const LAS bf16x8*)(Vb + (16 * nt + fr) * 560 + (16 * r + 32 * ks + 8 * fq) * 2), a, o[nt]);
;         }
; #pragma unroll
;         for (int nt = 0; nt < 4; ++nt) { u32x2 wv; wv.x = cvt_pk_bf16(o[nt][0], o[nt][1]); wv.y = cvt_pk_bf16(o[nt][2], o[nt][3]); *(u32x2*)(qp + 16 * nt + 4 * fq) = wv; }
	v_add_f32_e32 v24, v24, v25
	ds_bpermute_b32 v25, v95, v24
	s_waitcnt lgkmcnt(0)
	v_add_f32_e32 v24, v24, v25
	v_fma_f32 v25, v50, s88, -v51
	v_exp_f32_e32 v25, v25
	s_nop 0
	v_add_f32_e32 v24, v25, v24
	v_div_scale_f32 v25, vcc, v24, v24, 1.0
	v_rcp_f32_e32 v50, v25
	s_nop 0
	v_fma_f32 v51, -v25, v50, 1.0
	v_fmac_f32_e32 v50, v51, v50
	v_div_scale_f32 v51, vcc, 1.0, v24, 1.0
	v_mul_f32_e32 v129, v51, v50
	v_fma_f32 v130, -v25, v129, v51
	v_fmac_f32_e32 v129, v130, v50
	v_fma_f32 v25, -v25, v129, v51
	v_div_fmas_f32 v25, v25, v50, v129
	v_div_fixup_f32 v50, v25, v24, 1.0
	v_mul_f32_e32 v24, v89, v50
	v_mul_f32_e32 v25, v119, v50
	s_nop 1
	v_cvt_pk_bf16_f32 v24, v24, v25
	v_mul_f32_e32 v25, v124, v50
	v_mul_f32_e32 v51, v125, v50
	s_nop 1
	v_cvt_pk_bf16_f32 v25, v25, v51
	ds_write_b64 v112, v[24:25]
	v_mul_f32_e32 v24, v56, v50
	v_mul_f32_e32 v25, v57, v50
	s_nop 1
	v_cvt_pk_bf16_f32 v24, v24, v25
	v_mul_f32_e32 v25, v58, v50
	v_mul_f32_e32 v51, v59, v50
	s_nop 1
	v_cvt_pk_bf16_f32 v25, v25, v51
	ds_write_b64 v112, v[24:25] offset:32
	v_mul_f32_e32 v24, v52, v50
	v_mul_f32_e32 v25, v53, v50
	s_nop 1
	v_cvt_pk_bf16_f32 v24, v24, v25
	v_mul_f32_e32 v25, v54, v50
	v_mul_f32_e32 v51, v55, v50
	s_nop 1
	v_cvt_pk_bf16_f32 v25, v25, v51
	ds_write_b64 v112, v[24:25] offset:64
	v_mul_f32_e32 v24, v44, v50
	v_mul_f32_e32 v25, v45, v50
	s_nop 1
	v_cvt_pk_bf16_f32 v24, v24, v25
	v_mul_f32_e32 v25, v46, v50
	v_mul_f32_e32 v44, v47, v50
	s_nop 1
	v_cvt_pk_bf16_f32 v25, v25, v44
	ds_write_b64 v112, v[24:25] offset:96
	v_mul_f32_e32 v24, v40, v50
	v_mul_f32_e32 v25, v41, v50
	s_nop 1
	v_cvt_pk_bf16_f32 v24, v24, v25
	v_mul_f32_e32 v25, v42, v50
	v_mul_f32_e32 v40, v43, v50
	s_nop 1
	v_cvt_pk_bf16_f32 v25, v25, v40
	ds_write_b64 v112, v[24:25] offset:128
	v_mul_f32_e32 v24, v36, v50
	v_mul_f32_e32 v25, v37, v50
	s_nop 1
	v_cvt_pk_bf16_f32 v24, v24, v25
	v_mul_f32_e32 v25, v38, v50
	v_mul_f32_e32 v36, v39, v50
	s_nop 1
	v_cvt_pk_bf16_f32 v25, v25, v36
	ds_write_b64 v112, v[24:25] offset:160
	v_mul_f32_e32 v24, v32, v50
	v_mul_f32_e32 v25, v33, v50
	s_nop 1
	v_cvt_pk_bf16_f32 v24, v24, v25
	v_mul_f32_e32 v25, v34, v50
	v_mul_f32_e32 v32, v35, v50
	s_nop 1
	v_cvt_pk_bf16_f32 v25, v25, v32
	ds_write_b64 v112, v[24:25] offset:192
	v_mul_f32_e32 v24, v28, v50
	v_mul_f32_e32 v25, v29, v50
	s_nop 1
	v_cvt_pk_bf16_f32 v24, v24, v25
	v_mul_f32_e32 v25, v30, v50
	v_mul_f32_e32 v28, v31, v50
	s_nop 1
	v_cvt_pk_bf16_f32 v25, v25, v28
	ds_write_b64 v112, v[24:25] offset:224
	v_mul_f32_e32 v24, v127, v50
	v_mul_f32_e32 v25, v126, v50
	s_nop 1
	v_cvt_pk_bf16_f32 v24, v24, v25
	v_mul_f32_e32 v25, v26, v50
	v_mul_f32_e32 v26, v27, v50
	s_nop 1
	v_cvt_pk_bf16_f32 v25, v25, v26
	ds_write_b64 v112, v[24:25] offset:256
	v_mul_f32_e32 v25, v128, v50
	s_nop 1
	v_cvt_pk_bf16_f32 v24, v25, v25
	s_nop 1
	v_cvt_pk_bf16_f32 v25, v25, v25
	ds_write_b64 v112, v[24:25] offset:288
	s_waitcnt lgkmcnt(0)
	ds_read_b128 v[24:27], v113
	ds_read_b128 v[28:31], v114 offset:39168
	ds_read_b128 v[32:35], v114 offset:48128
	ds_read_b128 v[36:39], v114 offset:57088
	ds_read_b128 v[40:43], v115 offset:39168
	s_waitcnt lgkmcnt(3)
	v_mfma_f32_16x16x32_bf16 v[28:31], v[28:31], v[24:27], 0
	s_lshl_b32 vcc_lo, s93, 1
	s_mov_b32 vcc_hi, s3
	s_waitcnt lgkmcnt(2)
	v_mfma_f32_16x16x32_bf16 v[32:35], v[32:35], v[24:27], 0
	s_waitcnt lgkmcnt(1)
	v_mfma_f32_16x16x32_bf16 v[36:39], v[36:39], v[24:27], 0
	s_waitcnt lgkmcnt(0)
	v_mfma_f32_16x16x32_bf16 v[24:27], v[40:43], v[24:27], 0
	ds_read_b128 v[40:43], v113 offset:64
	ds_read_b128 v[44:47], v114 offset:39232
	s_waitcnt lgkmcnt(0)
	v_mfma_f32_16x16x32_bf16 v[28:31], v[44:47], v[40:43], v[28:31]
	ds_read_b128 v[44:47], v114 offset:48192
	s_waitcnt lgkmcnt(0)
	v_mfma_f32_16x16x32_bf16 v[32:35], v[44:47], v[40:43], v[32:35]
	ds_read_b128 v[44:47], v114 offset:57152
	s_waitcnt lgkmcnt(0)
	v_mfma_f32_16x16x32_bf16 v[36:39], v[44:47], v[40:43], v[36:39]
	ds_read_b128 v[44:47], v115 offset:39232
	s_waitcnt lgkmcnt(0)
	v_mfma_f32_16x16x32_bf16 v[24:27], v[44:47], v[40:43], v[24:27]
	ds_read_b128 v[40:43], v113 offset:128
	ds_read_b128 v[44:47], v114 offset:39296
	s_waitcnt lgkmcnt(0)
	v_mfma_f32_16x16x32_bf16 v[28:31], v[44:47], v[40:43], v[28:31]
	ds_read_b128 v[44:47], v114 offset:48256
	s_waitcnt lgkmcnt(0)
	v_mfma_f32_16x16x32_bf16 v[32:35], v[44:47], v[40:43], v[32:35]
	ds_read_b128 v[44:47], v114 offset:57216
	s_waitcnt lgkmcnt(0)
	v_mfma_f32_16x16x32_bf16 v[36:39], v[44:47], v[40:43], v[36:39]
	ds_read_b128 v[44:47], v115 offset:39296
	s_waitcnt lgkmcnt(0)
	v_mfma_f32_16x16x32_bf16 v[24:27], v[44:47], v[40:43], v[24:27]
	ds_read_b128 v[40:43], v113 offset:192
	ds_read_b128 v[44:47], v114 offset:39360
	s_waitcnt lgkmcnt(0)
	v_mfma_f32_16x16x32_bf16 v[28:31], v[44:47], v[40:43], v[28:31]
	ds_read_b128 v[44:47], v114 offset:48320
	s_waitcnt lgkmcnt(0)
	v_mfma_f32_16x16x32_bf16 v[32:35], v[44:47], v[40:43], v[32:35]
	ds_read_b128 v[44:47], v114 offset:57280
	s_waitcnt lgkmcnt(0)
	v_mfma_f32_16x16x32_bf16 v[36:39], v[44:47], v[40:43], v[36:39]
	ds_read_b128 v[44:47], v115 offset:39360
	s_waitcnt lgkmcnt(0)
	v_mfma_f32_16x16x32_bf16 v[40:43], v[44:47], v[40:43], v[24:27]
	ds_read_b128 v[44:47], v113 offset:256
	s_nop 1
	ds_read_b128 v[24:27], v114 offset:39424
	s_waitcnt lgkmcnt(0)
	v_mfma_f32_16x16x32_bf16 v[24:27], v[24:27], v[44:47], v[28:31]
	s_nop 2
	ds_read_b128 v[28:31], v114 offset:48384
	s_waitcnt lgkmcnt(0)
	v_mfma_f32_16x16x32_bf16 v[28:31], v[28:31], v[44:47], v[32:35]
	s_nop 2
	ds_read_b128 v[32:35], v114 offset:57344
	s_waitcnt lgkmcnt(0)
	v_mfma_f32_16x16x32_bf16 v[36:39], v[32:35], v[44:47], v[36:39]
	ds_read_b128 v[32:35], v115 offset:39424
	s_nop 1
	v_cvt_pk_bf16_f32 v24, v24, v25
	s_nop 1
	v_cvt_pk_bf16_f32 v25, v26, v27
	s_waitcnt lgkmcnt(0)
; #define LAS __attribute__((address_space(3)))
; __device__ __forceinline__ unsigned cvt_pk_bf16(float lo, float hi) { unsigned r; asm volatile("s_nop 1\n\tv_cvt_pk_bf16_f32 %0, %1, %2" : "=v"(r) : "v"(lo), "v"(hi)); return r; }
; __device__ __forceinline__ float shx(float v, int o, int lane) { return __int_as_float(__builtin_amdgcn_ds_bpermute((lane ^ o) << 2, __float_as_int(v))); }
; #define MFMA16(a, b, c) __builtin_amdgcn_mfma_f32_16x16x32_bf16((a), (b), (c), 0, 0, 0)
; __device__ __forceinline__ void attn_item(ldsp lds, int item, bf16_t* aq, const bf16_t* ak, const bf16_t* avT, const float* sinks, int tid, int w, int fr, int fq) {
;     ...
; #pragma unroll
;         for (int tt = 0; tt < 10; ++tt) { s[tt] = (f32x4){0.f, 0.f, 0.f, 0.f};
;             const bf16x8 b0 = *(const LAS bf16x8*)(Kb + (16 * (r + tt) + fr) * 144 + fq * 16), b1 = *(const LAS bf16x8*)(Kb + (16 * (r + tt) + fr) * 144 + 64 + fq * 16);
;             s[tt] = MFMA16(b0, a0, s[tt]); s[tt] = MFMA16(b1, a1, s[tt]); }
;         const float sink2 = sinks[hq] * LOG2E; float mx = sink2;
; #pragma unroll
;         for (int tt = 0; tt < 10; ++tt)
; #pragma unroll
;             for (int j = 0; j < 4; ++j) { const int kr = 16 * tt + 4 * fq + j; const bool valid = (kr > fr) && (kr <= fr + 128) && (n > 0 || 16 * r + kr >= 128);
;                 s[tt][j] = valid ? s[tt][j] : -INFINITY; mx = fmaxf(mx, s[tt][j]); }
;         const int ln = fr + 16 * fq;
;         mx = fmaxf(mx, shx(mx, 16, ln)); mx = fmaxf(mx, shx(mx, 32, ln));
;     ...
;         for (int nt = 0; nt < 4; ++nt) { u32x2 wv; wv.x = cvt_pk_bf16(o[nt][0], o[nt][1]); wv.y = cvt_pk_bf16(o[nt][2], o[nt][3]); *(u32x2*)(qp + 16 * nt + 4 * fq) = wv; }
	v_mfma_f32_16x16x32_bf16 v[32:35], v[32:35], v[44:47], v[40:43]
	s_nop 2
	v_lshl_add_u64 v[40:41], v[90:91], 0, vcc
	flat_store_dwordx2 v[40:41], v[24:25]
	s_nop 1
	v_cvt_pk_bf16_f32 v24, v28, v29
	s_nop 1
	v_cvt_pk_bf16_f32 v25, v30, v31
	flat_store_dwordx2 v[40:41], v[24:25] offset:32
	s_nop 1
	v_cvt_pk_bf16_f32 v24, v36, v37
	s_nop 1
	v_cvt_pk_bf16_f32 v25, v38, v39
	flat_store_dwordx2 v[40:41], v[24:25] offset:64
	s_nop 1
	v_cvt_pk_bf16_f32 v24, v32, v33
	s_nop 1
	v_cvt_pk_bf16_f32 v25, v34, v35
	flat_store_dwordx2 v[40:41], v[24:25] offset:96
	s_waitcnt lgkmcnt(0)
	ds_read_b128 v[24:27], v64
	ds_read_b128 v[28:31], v64 offset:64
	s_waitcnt lgkmcnt(0)
	v_mfma_f32_16x16x32_bf16 v[24:27], v[24:27], v[16:19], 0
	v_mfma_f32_16x16x32_bf16 v[24:27], v[28:31], v[20:23], v[24:27]
	ds_read_b128 v[28:31], v104
	ds_read_b128 v[32:35], v104 offset:64
	s_waitcnt lgkmcnt(0)
	v_mfma_f32_16x16x32_bf16 v[28:31], v[28:31], v[16:19], 0
	v_mfma_f32_16x16x32_bf16 v[28:31], v[32:35], v[20:23], v[28:31]
	ds_read_b128 v[32:35], v105
	ds_read_b128 v[36:39], v105 offset:64
	s_waitcnt lgkmcnt(0)
	v_mfma_f32_16x16x32_bf16 v[32:35], v[32:35], v[16:19], 0
	v_mfma_f32_16x16x32_bf16 v[32:35], v[36:39], v[20:23], v[32:35]
	ds_read_b128 v[36:39], v106
	ds_read_b128 v[40:43], v106 offset:64
	s_waitcnt lgkmcnt(0)
	v_mfma_f32_16x16x32_bf16 v[36:39], v[36:39], v[16:19], 0
	v_mfma_f32_16x16x32_bf16 v[36:39], v[40:43], v[20:23], v[36:39]
	ds_read_b128 v[40:43], v107
	ds_read_b128 v[44:47], v107 offset:64
	s_waitcnt lgkmcnt(0)
	v_mfma_f32_16x16x32_bf16 v[40:43], v[40:43], v[16:19], 0
	v_mfma_f32_16x16x32_bf16 v[40:43], v[44:47], v[20:23], v[40:43]
	ds_read_b128 v[44:47], v108
	ds_read_b128 v[50:53], v108 offset:64
	s_waitcnt lgkmcnt(0)
	v_mfma_f32_16x16x32_bf16 v[44:47], v[44:47], v[16:19], 0
	v_mfma_f32_16x16x32_bf16 v[44:47], v[50:53], v[20:23], v[44:47]
	ds_read_b128 v[50:53], v109
	ds_read_b128 v[54:57], v109 offset:64
	s_waitcnt lgkmcnt(0)
	v_mfma_f32_16x16x32_bf16 v[50:53], v[50:53], v[16:19], 0
	v_mfma_f32_16x16x32_bf16 v[50:53], v[54:57], v[20:23], v[50:53]
	ds_read_b128 v[54:57], v110
	ds_read_b128 v[124:127], v110 offset:64
	s_waitcnt lgkmcnt(0)
	v_mfma_f32_16x16x32_bf16 v[54:57], v[54:57], v[16:19], 0
	v_mfma_f32_16x16x32_bf16 v[54:57], v[124:127], v[20:23], v[54:57]
	ds_read_b128 v[124:127], v111
	ds_read_b128 v[128:131], v111 offset:64
	s_waitcnt lgkmcnt(0)
	v_mfma_f32_16x16x32_bf16 v[16:19], v[124:127], v[16:19], 0
	v_mfma_f32_16x16x32_bf16 v[16:19], v[128:131], v[20:23], v[16:19]
	flat_load_dword v20, v[48:49] offset:4 nt
	v_cndmask_b32_e64 v22, v118, v24, s[6:7]
	v_max_f32_e32 v23, v22, v22
	v_cndmask_b32_e64 v24, v118, v26, s[8:9]
	v_cndmask_b32_e64 v26, v118, v28, s[40:41]
	v_cndmask_b32_e64 v28, v118, v30, s[38:39]
	v_cndmask_b32_e64 v30, v118, v32, s[34:35]
	v_cndmask_b32_e64 v32, v118, v34, s[30:31]
	v_cndmask_b32_e64 v34, v118, v36, s[26:27]
	v_cndmask_b32_e64 v36, v118, v38, s[24:25]
	v_cndmask_b32_e64 v38, v118, v40, s[20:21]
	v_cndmask_b32_e64 v40, v118, v42, s[68:69]
	v_cndmask_b32_e64 v42, v118, v44, s[62:63]
	v_cndmask_b32_e64 v44, v118, v46, s[60:61]
	v_cndmask_b32_e64 v46, v118, v50, s[54:55]
	v_cndmask_b32_e64 v50, v118, v52, s[52:53]
	v_cndmask_b32_e64 v52, v118, v54, s[50:51]
	v_cndmask_b32_e64 v54, v118, v56, s[78:79]
	v_cndmask_b32_e64 v16, v118, v16, s[76:77]
	v_cndmask_b32_e64 v16, v16, v118, s[14:15]
	v_cndmask_b32_e64 v17, v118, v17, s[74:75]
	v_cndmask_b32_e64 v18, v118, v18, s[72:73]
	v_cndmask_b32_e64 v17, v17, v118, s[90:91]
	v_cndmask_b32_e64 v18, v18, v118, s[94:95]
	v_cndmask_b32_e64 v19, v118, v19, s[70:71]
	v_cndmask_b32_e64 v19, v19, v118, s[0:1]
	s_waitcnt vmcnt(0) lgkmcnt(0)
	v_mul_f32_e32 v21, 0x3fb8aa3b, v20
	v_max_f32_e32 v21, v21, v23
	v_cndmask_b32_e64 v23, v118, v25, s[10:11]
	v_cndmask_b32_e64 v23, v23, v118, s[18:19]
	v_max3_f32 v21, v21, v23, v24
	v_cndmask_b32_e64 v25, v118, v27, s[4:5]
	v_max3_f32 v21, v21, v25, v26
	v_cndmask_b32_e64 v27, v118, v29, s[28:29]
	v_max3_f32 v21, v21, v27, v28
	v_cndmask_b32_e64 v29, v118, v31, s[44:45]
	v_max3_f32 v21, v21, v29, v30
	v_cndmask_b32_e64 v31, v118, v33, s[22:23]
	v_max3_f32 v21, v21, v31, v32
	v_cndmask_b32_e64 v33, v118, v35, s[42:43]
	v_max3_f32 v21, v21, v33, v34
	v_cndmask_b32_e64 v35, v118, v37, s[16:17]
	v_max3_f32 v21, v21, v35, v36
	v_cndmask_b32_e64 v37, v118, v39, s[36:37]
	v_max3_f32 v21, v21, v37, v38
	v_cndmask_b32_e64 v39, v118, v41, s[66:67]
	v_max3_f32 v21, v21, v39, v40
	v_cndmask_b32_e64 v41, v118, v43, s[64:65]
	v_max3_f32 v21, v21, v41, v42
	v_cndmask_b32_e64 v43, v118, v45, s[58:59]
	v_max3_f32 v21, v21, v43, v44
	v_cndmask_b32_e64 v45, v118, v47, s[56:57]
	v_max3_f32 v21, v21, v45, v46
	v_cndmask_b32_e64 v47, v118, v51, s[48:49]
	v_max3_f32 v21, v21, v47, v50
	v_cndmask_b32_e64 v51, v118, v53, s[46:47]
	v_max3_f32 v21, v21, v51, v52
	v_cndmask_b32_e64 v53, v118, v55, s[12:13]
	v_max3_f32 v21, v21, v53, v54
	v_cndmask_b32_e64 v55, v118, v57, s[80:81]
	v_max3_f32 v21, v21, v55, v16
	v_max3_f32 v21, v21, v17, v18
	v_max3_f32 v21, v21, v19, s89
	ds_bpermute_b32 v56, v94, v21
	s_waitcnt lgkmcnt(0)
	v_max_f32_e32 v56, v56, v56
	v_max_f32_e32 v21, v21, v56
	ds_bpermute_b32 v56, v95, v21
	s_waitcnt lgkmcnt(0)
; #define LAS __attribute__((address_space(3)))
; __device__ __forceinline__ unsigned cvt_pk_bf16(float lo, float hi) { unsigned r; asm volatile("s_nop 1\n\tv_cvt_pk_bf16_f32 %0, %1, %2" : "=v"(r) : "v"(lo), "v"(hi)); return r; }
; __device__ __forceinline__ float shx(float v, int o, int lane) { return __int_as_float(__builtin_amdgcn_ds_bpermute((lane ^ o) << 2, __float_as_int(v))); }
; __device__ __forceinline__ void attn_item(ldsp lds, int item, bf16_t* aq, const bf16_t* ak, const bf16_t* avT, const float* sinks, int tid, int w, int fr, int fq) {
;     ...
;         const int ln = fr + 16 * fq;
;         mx = fmaxf(mx, shx(mx, 16, ln)); mx = fmaxf(mx, shx(mx, 32, ln));
;         float sum = 0.f;
; #pragma unroll
;         for (int tt = 0; tt < 10; ++tt)
; #pragma unroll
;             for (int j = 0; j < 4; ++j) { s[tt][j] = __builtin_amdgcn_exp2f(s[tt][j] - mx); sum += s[tt][j]; }
;         sum += shx(sum, 16, ln); sum += shx(sum, 32, ln);
;         const float inv = 1.0f / (sum + __builtin_amdgcn_exp2f(sink2 - mx));
; #pragma unroll
;         for (int tt = 0; tt < 10; ++tt) { u32x2 wv; wv.x = cvt_pk_bf16(s[tt][0] * inv, s[tt][1] * inv); wv.y = cvt_pk_bf16(s[tt][2] * inv, s[tt][3] * inv);
;             *(LAS u32x2*)(Pb + fr * 336 + (16 * tt + 4 * fq) * 2) = wv; }
	v_max_f32_e32 v56, v56, v56
	v_max_f32_e32 v21, v21, v56
	v_sub_f32_e32 v22, v22, v21
	v_exp_f32_e32 v22, v22
	v_sub_f32_e32 v23, v23, v21
	v_exp_f32_e32 v23, v23
	v_sub_f32_e32 v24, v24, v21
	v_exp_f32_e32 v24, v24
	v_sub_f32_e32 v25, v25, v21
	v_exp_f32_e32 v25, v25
	v_sub_f32_e32 v26, v26, v21
	v_add_f32_e32 v56, 0, v22
	v_exp_f32_e32 v26, v26
	v_sub_f32_e32 v27, v27, v21
	v_add_f32_e32 v56, v23, v56
	v_exp_f32_e32 v27, v27
	v_sub_f32_e32 v28, v28, v21
	v_add_f32_e32 v56, v24, v56
	v_exp_f32_e32 v28, v28
	v_sub_f32_e32 v29, v29, v21
	v_add_f32_e32 v56, v25, v56
	v_exp_f32_e32 v29, v29
	v_sub_f32_e32 v30, v30, v21
	v_add_f32_e32 v56, v26, v56
	v_exp_f32_e32 v30, v30
	v_sub_f32_e32 v31, v31, v21
	v_add_f32_e32 v56, v27, v56
	v_exp_f32_e32 v31, v31
	v_sub_f32_e32 v32, v32, v21
	v_add_f32_e32 v56, v28, v56
	v_exp_f32_e32 v32, v32
	v_sub_f32_e32 v33, v33, v21
	v_add_f32_e32 v56, v29, v56
	v_exp_f32_e32 v33, v33
	v_sub_f32_e32 v34, v34, v21
	v_add_f32_e32 v56, v30, v56
	v_exp_f32_e32 v34, v34
	v_sub_f32_e32 v35, v35, v21
	v_add_f32_e32 v56, v31, v56
	v_exp_f32_e32 v35, v35
	v_sub_f32_e32 v36, v36, v21
	v_add_f32_e32 v56, v32, v56
	v_exp_f32_e32 v36, v36
	v_sub_f32_e32 v37, v37, v21
	v_add_f32_e32 v56, v33, v56
	v_exp_f32_e32 v37, v37
	v_sub_f32_e32 v38, v38, v21
	v_add_f32_e32 v56, v34, v56
	v_exp_f32_e32 v38, v38
	v_sub_f32_e32 v39, v39, v21
	v_add_f32_e32 v56, v35, v56
	v_exp_f32_e32 v39, v39
	v_sub_f32_e32 v40, v40, v21
	v_add_f32_e32 v56, v36, v56
	v_exp_f32_e32 v40, v40
	v_sub_f32_e32 v41, v41, v21
	v_add_f32_e32 v56, v37, v56
	v_exp_f32_e32 v41, v41
	v_sub_f32_e32 v42, v42, v21
	v_add_f32_e32 v56, v38, v56
	v_exp_f32_e32 v42, v42
	v_sub_f32_e32 v43, v43, v21
	v_add_f32_e32 v56, v39, v56
	v_exp_f32_e32 v43, v43
	v_sub_f32_e32 v44, v44, v21
	v_add_f32_e32 v56, v40, v56
	v_exp_f32_e32 v44, v44
	v_sub_f32_e32 v45, v45, v21
	v_add_f32_e32 v56, v41, v56
	v_exp_f32_e32 v45, v45
	v_sub_f32_e32 v46, v46, v21
	v_add_f32_e32 v56, v42, v56
	v_exp_f32_e32 v46, v46
	v_sub_f32_e32 v47, v47, v21
	v_add_f32_e32 v56, v43, v56
	v_exp_f32_e32 v47, v47
	v_sub_f32_e32 v50, v50, v21
	v_add_f32_e32 v56, v44, v56
	v_exp_f32_e32 v50, v50
	v_sub_f32_e32 v51, v51, v21
	v_add_f32_e32 v56, v45, v56
	v_exp_f32_e32 v51, v51
	v_sub_f32_e32 v52, v52, v21
	v_add_f32_e32 v56, v46, v56
	v_exp_f32_e32 v52, v52
	v_sub_f32_e32 v53, v53, v21
	v_add_f32_e32 v56, v47, v56
	v_exp_f32_e32 v53, v53
	v_sub_f32_e32 v54, v54, v21
	v_add_f32_e32 v56, v50, v56
	v_exp_f32_e32 v54, v54
	v_sub_f32_e32 v55, v55, v21
	v_add_f32_e32 v56, v51, v56
	v_exp_f32_e32 v55, v55
	v_sub_f32_e32 v16, v16, v21
	v_add_f32_e32 v56, v52, v56
	v_exp_f32_e32 v57, v16
	v_add_f32_e32 v56, v53, v56
	v_add_f32_e32 v56, v54, v56
	v_add_f32_e32 v56, v55, v56
	v_sub_f32_e32 v17, v17, v21
	v_add_f32_e32 v16, v57, v56
	v_exp_f32_e32 v56, v17
	v_sub_f32_e32 v17, v18, v21
	v_exp_f32_e32 v18, v17
	v_sub_f32_e32 v17, v19, v21
	v_exp_f32_e32 v19, v17
	v_sub_f32_e32 v17, 0xff800000, v21
	v_exp_f32_e32 v58, v17
	v_add_f32_e32 v16, v56, v16
	v_add_f32_e32 v16, v18, v16
	v_add_f32_e32 v16, v19, v16
	v_add_f32_e32 v16, v58, v16
	v_add_f32_e32 v16, v58, v16
	v_add_f32_e32 v16, v58, v16
	v_add_f32_e32 v16, v58, v16
	ds_bpermute_b32 v17, v94, v16
	s_waitcnt lgkmcnt(0)
	v_add_f32_e32 v16, v16, v17
	ds_bpermute_b32 v17, v95, v16
	s_waitcnt lgkmcnt(0)
	v_add_f32_e32 v16, v16, v17
	v_fma_f32 v17, v20, s88, -v21
	v_exp_f32_e32 v17, v17
	s_nop 0
	v_add_f32_e32 v16, v17, v16
	v_div_scale_f32 v17, vcc, v16, v16, 1.0
	v_rcp_f32_e32 v20, v17
	s_nop 0
	v_fma_f32 v21, -v17, v20, 1.0
	v_fmac_f32_e32 v20, v21, v20
	v_div_scale_f32 v21, vcc, 1.0, v16, 1.0
	v_mul_f32_e32 v59, v21, v20
	v_fma_f32 v89, -v17, v59, v21
	v_fmac_f32_e32 v59, v89, v20
	v_fma_f32 v17, -v17, v59, v21
	v_div_fmas_f32 v17, v17, v20, v59
	v_div_fixup_f32 v20, v17, v16, 1.0
	v_mul_f32_e32 v16, v22, v20
	v_mul_f32_e32 v17, v23, v20
	s_nop 1
	v_cvt_pk_bf16_f32 v16, v16, v17
	v_mul_f32_e32 v17, v24, v20
	v_mul_f32_e32 v21, v25, v20
	s_nop 1
	v_cvt_pk_bf16_f32 v17, v17, v21
	ds_write_b64 v112, v[16:17]
	v_mul_f32_e32 v16, v26, v20
	v_mul_f32_e32 v17, v27, v20
	s_nop 1
	v_cvt_pk_bf16_f32 v16, v16, v17
	v_mul_f32_e32 v17, v28, v20
	v_mul_f32_e32 v21, v29, v20
	s_nop 1
	v_cvt_pk_bf16_f32 v17, v17, v21
	ds_write_b64 v112, v[16:17] offset:32
	v_mul_f32_e32 v16, v30, v20
	v_mul_f32_e32 v17, v31, v20
	s_nop 1
	v_cvt_pk_bf16_f32 v16, v16, v17
	v_mul_f32_e32 v17, v32, v20
	v_mul_f32_e32 v21, v33, v20
	s_nop 1
	v_cvt_pk_bf16_f32 v17, v17, v21
	ds_write_b64 v112, v[16:17] offset:64
	v_mul_f32_e32 v16, v34, v20
	v_mul_f32_e32 v17, v35, v20
	s_nop 1
	v_cvt_pk_bf16_f32 v16, v16, v17
	v_mul_f32_e32 v17, v36, v20
	v_mul_f32_e32 v21, v37, v20
	s_nop 1
	v_cvt_pk_bf16_f32 v17, v17, v21
	ds_write_b64 v112, v[16:17] offset:96
	v_mul_f32_e32 v16, v38, v20
	v_mul_f32_e32 v17, v39, v20
	s_nop 1
	v_cvt_pk_bf16_f32 v16, v16, v17
	v_mul_f32_e32 v17, v40, v20
	v_mul_f32_e32 v21, v41, v20
	s_nop 1
	v_cvt_pk_bf16_f32 v17, v17, v21
	ds_write_b64 v112, v[16:17] offset:128
	v_mul_f32_e32 v16, v42, v20
	v_mul_f32_e32 v17, v43, v20
	s_nop 1
	v_cvt_pk_bf16_f32 v16, v16, v17
	v_mul_f32_e32 v17, v44, v20
	v_mul_f32_e32 v21, v45, v20
	s_nop 1
	v_cvt_pk_bf16_f32 v17, v17, v21
	ds_write_b64 v112, v[16:17] offset:160
	v_mul_f32_e32 v16, v46, v20
	v_mul_f32_e32 v17, v47, v20
	s_nop 1
	v_cvt_pk_bf16_f32 v16, v16, v17
	v_mul_f32_e32 v17, v50, v20
	v_mul_f32_e32 v21, v51, v20
	s_nop 1
	v_cvt_pk_bf16_f32 v17, v17, v21
	ds_write_b64 v112, v[16:17] offset:192
	v_mul_f32_e32 v16, v52, v20
	v_mul_f32_e32 v17, v53, v20
	s_nop 1
	v_cvt_pk_bf16_f32 v16, v16, v17
	v_mul_f32_e32 v17, v54, v20
	v_mul_f32_e32 v21, v55, v20
	s_nop 1
	v_cvt_pk_bf16_f32 v17, v17, v21
	ds_write_b64 v112, v[16:17] offset:224
	v_mul_f32_e32 v16, v57, v20
	v_mul_f32_e32 v17, v56, v20
	s_nop 1
	v_cvt_pk_bf16_f32 v16, v16, v17
	v_mul_f32_e32 v17, v18, v20
	v_mul_f32_e32 v18, v19, v20
	s_nop 1
	v_cvt_pk_bf16_f32 v17, v17, v18
	ds_write_b64 v112, v[16:17] offset:256
	v_mul_f32_e32 v17, v58, v20
	s_nop 1
	v_cvt_pk_bf16_f32 v16, v17, v17
	s_nop 1
	v_cvt_pk_bf16_f32 v17, v17, v17
	ds_write_b64 v112, v[16:17] offset:288
	s_waitcnt lgkmcnt(0)
; #define LAS __attribute__((address_space(3)))
; __device__ __forceinline__ unsigned cvt_pk_bf16(float lo, float hi) { unsigned r; asm volatile("s_nop 1\n\tv_cvt_pk_bf16_f32 %0, %1, %2" : "=v"(r) : "v"(lo), "v"(hi)); return r; }
; #define MFMA16(a, b, c) __builtin_amdgcn_mfma_f32_16x16x32_bf16((a), (b), (c), 0, 0, 0)
; __device__ __forceinline__ void attn_item(ldsp lds, int item, bf16_t* aq, const bf16_t* ak, const bf16_t* avT, const float* sinks, int tid, int w, int fr, int fq) {
;     ...
; #pragma unroll
;         for (int tt = 0; tt < 10; ++tt) { s[tt] = (f32x4){0.f, 0.f, 0.f, 0.f};
;             const bf16x8 b0 = *(const LAS bf16x8*)(Kb + (16 * (r + tt) + fr) * 144 + fq * 16), b1 = *(const LAS bf16x8*)(Kb + (16 * (r + tt) + fr) * 144 + 64 + fq * 16);
;             s[tt] = MFMA16(b0, a0, s[tt]); s[tt] = MFMA16(b1, a1, s[tt]); }
;     ...
; #pragma unroll
;         for (int ks = 0; ks < 5; ++ks) {
;             const bf16x8 a = *(const LAS bf16x8*)(Pb + fr * 336 + ks * 64 + fq * 16);
; #pragma unroll
;             for (int nt = 0; nt < 4; ++nt) o[nt] = MFMA16(*(const LAS bf16x8*)(Vb + (16 * nt + fr) * 560 + (16 * r + 32 * ks + 8 * fq) * 2), a, o[nt]);
;         }
; #pragma unroll
;         for (int nt = 0; nt < 4; ++nt) { u32x2 wv; wv.x = cvt_pk_bf16(o[nt][0], o[nt][1]); wv.y = cvt_pk_bf16(o[nt][2], o[nt][3]); *(u32x2*)(qp + 16 * nt + 4 * fq) = wv; }
	ds_read_b128 v[16:19], v113
	ds_read_b128 v[20:23], v114 offset:39168
	ds_read_b128 v[24:27], v114 offset:48128
	ds_read_b128 v[28:31], v114 offset:57088
	ds_read_b128 v[32:35], v115 offset:39168
	s_waitcnt lgkmcnt(3)
	v_mfma_f32_16x16x32_bf16 v[20:23], v[20:23], v[16:19], 0
	s_or_b32 vcc_lo, s2, 0x80
	s_mov_b32 vcc_hi, s3
	s_waitcnt lgkmcnt(2)
	v_mfma_f32_16x16x32_bf16 v[24:27], v[24:27], v[16:19], 0
	s_waitcnt lgkmcnt(1)
	v_mfma_f32_16x16x32_bf16 v[28:31], v[28:31], v[16:19], 0
	s_waitcnt lgkmcnt(0)
	v_mfma_f32_16x16x32_bf16 v[16:19], v[32:35], v[16:19], 0
	ds_read_b128 v[32:35], v113 offset:64
	ds_read_b128 v[36:39], v114 offset:39232
	s_waitcnt lgkmcnt(0)
	v_mfma_f32_16x16x32_bf16 v[20:23], v[36:39], v[32:35], v[20:23]
	ds_read_b128 v[36:39], v114 offset:48192
	s_waitcnt lgkmcnt(0)
	v_mfma_f32_16x16x32_bf16 v[24:27], v[36:39], v[32:35], v[24:27]
	ds_read_b128 v[36:39], v114 offset:57152
	s_waitcnt lgkmcnt(0)
	v_mfma_f32_16x16x32_bf16 v[28:31], v[36:39], v[32:35], v[28:31]
	ds_read_b128 v[36:39], v115 offset:39232
	s_waitcnt lgkmcnt(0)
	v_mfma_f32_16x16x32_bf16 v[16:19], v[36:39], v[32:35], v[16:19]
	ds_read_b128 v[32:35], v113 offset:128
	ds_read_b128 v[36:39], v114 offset:39296
	s_waitcnt lgkmcnt(0)
	v_mfma_f32_16x16x32_bf16 v[20:23], v[36:39], v[32:35], v[20:23]
	ds_read_b128 v[36:39], v114 offset:48256
	s_waitcnt lgkmcnt(0)
	v_mfma_f32_16x16x32_bf16 v[24:27], v[36:39], v[32:35], v[24:27]
	ds_read_b128 v[36:39], v114 offset:57216
	s_waitcnt lgkmcnt(0)
	v_mfma_f32_16x16x32_bf16 v[28:31], v[36:39], v[32:35], v[28:31]
	ds_read_b128 v[36:39], v115 offset:39296
	s_waitcnt lgkmcnt(0)
	v_mfma_f32_16x16x32_bf16 v[16:19], v[36:39], v[32:35], v[16:19]
	ds_read_b128 v[32:35], v113 offset:192
	ds_read_b128 v[36:39], v114 offset:39360
	s_waitcnt lgkmcnt(0)
	v_mfma_f32_16x16x32_bf16 v[20:23], v[36:39], v[32:35], v[20:23]
	ds_read_b128 v[36:39], v114 offset:48320
	s_waitcnt lgkmcnt(0)
	v_mfma_f32_16x16x32_bf16 v[24:27], v[36:39], v[32:35], v[24:27]
	ds_read_b128 v[36:39], v114 offset:57280
	s_waitcnt lgkmcnt(0)
	v_mfma_f32_16x16x32_bf16 v[28:31], v[36:39], v[32:35], v[28:31]
	ds_read_b128 v[36:39], v115 offset:39360
	s_waitcnt lgkmcnt(0)
	v_mfma_f32_16x16x32_bf16 v[32:35], v[36:39], v[32:35], v[16:19]
	ds_read_b128 v[36:39], v113 offset:256
	s_nop 1
	ds_read_b128 v[16:19], v114 offset:39424
	s_waitcnt lgkmcnt(0)
	v_mfma_f32_16x16x32_bf16 v[16:19], v[16:19], v[36:39], v[20:23]
	s_nop 2
	ds_read_b128 v[20:23], v114 offset:48384
	s_waitcnt lgkmcnt(0)
	v_mfma_f32_16x16x32_bf16 v[20:23], v[20:23], v[36:39], v[24:27]
	s_nop 2
	ds_read_b128 v[24:27], v114 offset:57344
	s_waitcnt lgkmcnt(0)
	v_mfma_f32_16x16x32_bf16 v[28:31], v[24:27], v[36:39], v[28:31]
	ds_read_b128 v[24:27], v115 offset:39424
	s_nop 1
	v_cvt_pk_bf16_f32 v16, v16, v17
	s_nop 1
	v_cvt_pk_bf16_f32 v17, v18, v19
	s_waitcnt lgkmcnt(0)
	v_mfma_f32_16x16x32_bf16 v[24:27], v[24:27], v[36:39], v[32:35]
	s_nop 2
	v_lshl_add_u64 v[32:33], v[90:91], 0, vcc
	flat_store_dwordx2 v[32:33], v[16:17]
	s_nop 1
	v_cvt_pk_bf16_f32 v16, v20, v21
	s_nop 1
	v_cvt_pk_bf16_f32 v17, v22, v23
	flat_store_dwordx2 v[32:33], v[16:17] offset:32
	s_nop 1
	v_cvt_pk_bf16_f32 v16, v28, v29
	s_nop 1
	v_cvt_pk_bf16_f32 v17, v30, v31
	flat_store_dwordx2 v[32:33], v[16:17] offset:64
	s_nop 1
	v_cvt_pk_bf16_f32 v16, v24, v25
	s_nop 1
	v_cvt_pk_bf16_f32 v17, v26, v27
	flat_store_dwordx2 v[32:33], v[16:17] offset:96
	s_waitcnt lgkmcnt(0)
	ds_read_b128 v[16:19], v64
	ds_read_b128 v[20:23], v64 offset:64
	s_waitcnt lgkmcnt(0)
	v_mfma_f32_16x16x32_bf16 v[16:19], v[16:19], v[8:11], 0
	v_mfma_f32_16x16x32_bf16 v[16:19], v[20:23], v[12:15], v[16:19]
	ds_read_b128 v[20:23], v104
	ds_read_b128 v[24:27], v104 offset:64
	s_waitcnt lgkmcnt(0)
	v_mfma_f32_16x16x32_bf16 v[20:23], v[20:23], v[8:11], 0
	v_mfma_f32_16x16x32_bf16 v[20:23], v[24:27], v[12:15], v[20:23]
	ds_read_b128 v[24:27], v105
	ds_read_b128 v[28:31], v105 offset:64
	s_waitcnt lgkmcnt(0)
	v_mfma_f32_16x16x32_bf16 v[24:27], v[24:27], v[8:11], 0
	v_mfma_f32_16x16x32_bf16 v[24:27], v[28:31], v[12:15], v[24:27]
	ds_read_b128 v[28:31], v106
	ds_read_b128 v[32:35], v106 offset:64
	s_waitcnt lgkmcnt(0)
	v_mfma_f32_16x16x32_bf16 v[28:31], v[28:31], v[8:11], 0
	v_mfma_f32_16x16x32_bf16 v[28:31], v[32:35], v[12:15], v[28:31]
	ds_read_b128 v[32:35], v107
	ds_read_b128 v[36:39], v107 offset:64
	s_waitcnt lgkmcnt(0)
	v_mfma_f32_16x16x32_bf16 v[32:35], v[32:35], v[8:11], 0
	v_mfma_f32_16x16x32_bf16 v[32:35], v[36:39], v[12:15], v[32:35]
	ds_read_b128 v[36:39], v108
	ds_read_b128 v[40:43], v108 offset:64
	s_waitcnt lgkmcnt(0)
	v_mfma_f32_16x16x32_bf16 v[36:39], v[36:39], v[8:11], 0
	v_mfma_f32_16x16x32_bf16 v[36:39], v[40:43], v[12:15], v[36:39]
	ds_read_b128 v[40:43], v109
	ds_read_b128 v[44:47], v109 offset:64
	s_waitcnt lgkmcnt(0)
	v_mfma_f32_16x16x32_bf16 v[40:43], v[40:43], v[8:11], 0
	v_mfma_f32_16x16x32_bf16 v[40:43], v[44:47], v[12:15], v[40:43]
	ds_read_b128 v[44:47], v110
	ds_read_b128 v[50:53], v110 offset:64
	s_waitcnt lgkmcnt(0)
	v_mfma_f32_16x16x32_bf16 v[44:47], v[44:47], v[8:11], 0
	v_mfma_f32_16x16x32_bf16 v[44:47], v[50:53], v[12:15], v[44:47]
	ds_read_b128 v[50:53], v111
	ds_read_b128 v[54:57], v111 offset:64
	s_waitcnt lgkmcnt(0)
; __device__ __forceinline__ float shx(float v, int o, int lane) { return __int_as_float(__builtin_amdgcn_ds_bpermute((lane ^ o) << 2, __float_as_int(v))); }
; __device__ __forceinline__ void attn_item(ldsp lds, int item, bf16_t* aq, const bf16_t* ak, const bf16_t* avT, const float* sinks, int tid, int w, int fr, int fq) {
;     ...
;         const float sink2 = sinks[hq] * LOG2E; float mx = sink2;
; #pragma unroll
;         for (int tt = 0; tt < 10; ++tt)
; #pragma unroll
;             for (int j = 0; j < 4; ++j) { const int kr = 16 * tt + 4 * fq + j; const bool valid = (kr > fr) && (kr <= fr + 128) && (n > 0 || 16 * r + kr >= 128);
;                 s[tt][j] = valid ? s[tt][j] : -INFINITY; mx = fmaxf(mx, s[tt][j]); }
;         const int ln = fr + 16 * fq;
;         mx = fmaxf(mx, shx(mx, 16, ln)); mx = fmaxf(mx, shx(mx, 32, ln));
;         float sum = 0.f;
; #pragma unroll
;         for (int tt = 0; tt < 10; ++tt)
; #pragma unroll
;             for (int j = 0; j < 4; ++j) { s[tt][j] = __builtin_amdgcn_exp2f(s[tt][j] - mx); sum += s[tt][j]; }
;         sum += shx(sum, 16, ln); sum += shx(sum, 32, ln);
	v_mfma_f32_16x16x32_bf16 v[8:11], v[50:53], v[8:11], 0
	v_mfma_f32_16x16x32_bf16 v[8:11], v[54:57], v[12:15], v[8:11]
	flat_load_dword v12, v[48:49] offset:8 nt
	v_cndmask_b32_e64 v14, v118, v16, s[6:7]
	v_max_f32_e32 v15, v14, v14
	v_cndmask_b32_e64 v16, v118, v18, s[8:9]
	v_cndmask_b32_e64 v18, v118, v20, s[40:41]
	v_cndmask_b32_e64 v20, v118, v22, s[38:39]
	v_cndmask_b32_e64 v22, v118, v24, s[34:35]
	v_cndmask_b32_e64 v24, v118, v26, s[30:31]
	v_cndmask_b32_e64 v26, v118, v28, s[26:27]
	v_cndmask_b32_e64 v28, v118, v30, s[24:25]
	v_cndmask_b32_e64 v30, v118, v32, s[20:21]
	v_cndmask_b32_e64 v32, v118, v34, s[68:69]
	v_cndmask_b32_e64 v34, v118, v36, s[62:63]
	v_cndmask_b32_e64 v36, v118, v38, s[60:61]
	v_cndmask_b32_e64 v38, v118, v40, s[54:55]
	v_cndmask_b32_e64 v40, v118, v42, s[52:53]
	v_cndmask_b32_e64 v42, v118, v44, s[50:51]
	v_cndmask_b32_e64 v44, v118, v46, s[78:79]
	v_cndmask_b32_e64 v8, v118, v8, s[76:77]
	v_cndmask_b32_e64 v8, v8, v118, s[14:15]
	v_cndmask_b32_e64 v9, v118, v9, s[74:75]
	v_cndmask_b32_e64 v10, v118, v10, s[72:73]
	v_cndmask_b32_e64 v9, v9, v118, s[90:91]
	v_cndmask_b32_e64 v10, v10, v118, s[94:95]
	v_cndmask_b32_e64 v11, v118, v11, s[70:71]
	v_cndmask_b32_e64 v11, v11, v118, s[0:1]
	s_waitcnt vmcnt(0) lgkmcnt(0)
	v_mul_f32_e32 v13, 0x3fb8aa3b, v12
	v_max_f32_e32 v13, v13, v15
	v_cndmask_b32_e64 v15, v118, v17, s[10:11]
	v_cndmask_b32_e64 v15, v15, v118, s[18:19]
	v_max3_f32 v13, v13, v15, v16
	v_cndmask_b32_e64 v17, v118, v19, s[4:5]
	v_max3_f32 v13, v13, v17, v18
	v_cndmask_b32_e64 v19, v118, v21, s[28:29]
	v_max3_f32 v13, v13, v19, v20
	v_cndmask_b32_e64 v21, v118, v23, s[44:45]
	v_max3_f32 v13, v13, v21, v22
	v_cndmask_b32_e64 v23, v118, v25, s[22:23]
	v_max3_f32 v13, v13, v23, v24
	v_cndmask_b32_e64 v25, v118, v27, s[42:43]
	v_max3_f32 v13, v13, v25, v26
	v_cndmask_b32_e64 v27, v118, v29, s[16:17]
	v_max3_f32 v13, v13, v27, v28
	v_cndmask_b32_e64 v29, v118, v31, s[36:37]
	v_max3_f32 v13, v13, v29, v30
	v_cndmask_b32_e64 v31, v118, v33, s[66:67]
	v_max3_f32 v13, v13, v31, v32
	v_cndmask_b32_e64 v33, v118, v35, s[64:65]
	v_max3_f32 v13, v13, v33, v34
	v_cndmask_b32_e64 v35, v118, v37, s[58:59]
	v_max3_f32 v13, v13, v35, v36
	v_cndmask_b32_e64 v37, v118, v39, s[56:57]
	v_max3_f32 v13, v13, v37, v38
	v_cndmask_b32_e64 v39, v118, v41, s[48:49]
	v_max3_f32 v13, v13, v39, v40
	v_cndmask_b32_e64 v41, v118, v43, s[46:47]
	v_max3_f32 v13, v13, v41, v42
	v_cndmask_b32_e64 v43, v118, v45, s[12:13]
	v_max3_f32 v13, v13, v43, v44
	v_cndmask_b32_e64 v45, v118, v47, s[80:81]
	v_max3_f32 v13, v13, v45, v8
	v_max3_f32 v13, v13, v9, v10
	v_max3_f32 v13, v13, v11, s89
	ds_bpermute_b32 v46, v94, v13
	s_waitcnt lgkmcnt(0)
	v_max_f32_e32 v46, v46, v46
	v_max_f32_e32 v13, v13, v46
	ds_bpermute_b32 v46, v95, v13
	s_waitcnt lgkmcnt(0)
	v_max_f32_e32 v46, v46, v46
	v_max_f32_e32 v13, v13, v46
	v_sub_f32_e32 v14, v14, v13
	v_exp_f32_e32 v14, v14
	v_sub_f32_e32 v15, v15, v13
	v_exp_f32_e32 v15, v15
	v_sub_f32_e32 v16, v16, v13
	v_exp_f32_e32 v16, v16
	v_sub_f32_e32 v17, v17, v13
	v_exp_f32_e32 v17, v17
	v_sub_f32_e32 v18, v18, v13
	v_add_f32_e32 v46, 0, v14
	v_exp_f32_e32 v18, v18
	v_sub_f32_e32 v19, v19, v13
	v_add_f32_e32 v46, v15, v46
	v_exp_f32_e32 v19, v19
	v_sub_f32_e32 v20, v20, v13
	v_add_f32_e32 v46, v16, v46
	v_exp_f32_e32 v20, v20
	v_sub_f32_e32 v21, v21, v13
	v_add_f32_e32 v46, v17, v46
	v_exp_f32_e32 v21, v21
	v_sub_f32_e32 v22, v22, v13
	v_add_f32_e32 v46, v18, v46
	v_exp_f32_e32 v22, v22
	v_sub_f32_e32 v23, v23, v13
	v_add_f32_e32 v46, v19, v46
	v_exp_f32_e32 v23, v23
	v_sub_f32_e32 v24, v24, v13
	v_add_f32_e32 v46, v20, v46
	v_exp_f32_e32 v24, v24
	v_sub_f32_e32 v25, v25, v13
	v_add_f32_e32 v46, v21, v46
	v_exp_f32_e32 v25, v25
	v_sub_f32_e32 v26, v26, v13
	v_add_f32_e32 v46, v22, v46
	v_exp_f32_e32 v26, v26
	v_sub_f32_e32 v27, v27, v13
	v_add_f32_e32 v46, v23, v46
	v_exp_f32_e32 v27, v27
	v_sub_f32_e32 v28, v28, v13
	v_add_f32_e32 v46, v24, v46
	v_exp_f32_e32 v28, v28
	v_sub_f32_e32 v29, v29, v13
	v_add_f32_e32 v46, v25, v46
	v_exp_f32_e32 v29, v29
	v_sub_f32_e32 v30, v30, v13
	v_add_f32_e32 v46, v26, v46
	v_exp_f32_e32 v30, v30
	v_sub_f32_e32 v31, v31, v13
	v_add_f32_e32 v46, v27, v46
	v_exp_f32_e32 v31, v31
	v_sub_f32_e32 v32, v32, v13
	v_add_f32_e32 v46, v28, v46
	v_exp_f32_e32 v32, v32
	v_sub_f32_e32 v33, v33, v13
	v_add_f32_e32 v46, v29, v46
	v_exp_f32_e32 v33, v33
	v_sub_f32_e32 v34, v34, v13
	v_add_f32_e32 v46, v30, v46
	v_exp_f32_e32 v34, v34
	v_sub_f32_e32 v35, v35, v13
	v_add_f32_e32 v46, v31, v46
	v_exp_f32_e32 v35, v35
	v_sub_f32_e32 v36, v36, v13
	v_add_f32_e32 v46, v32, v46
	v_exp_f32_e32 v36, v36
	v_sub_f32_e32 v37, v37, v13
	v_add_f32_e32 v46, v33, v46
	v_exp_f32_e32 v37, v37
	v_sub_f32_e32 v38, v38, v13
	v_add_f32_e32 v46, v34, v46
	v_exp_f32_e32 v38, v38
	v_sub_f32_e32 v39, v39, v13
	v_add_f32_e32 v46, v35, v46
	v_exp_f32_e32 v39, v39
	v_sub_f32_e32 v40, v40, v13
	v_add_f32_e32 v46, v36, v46
	v_exp_f32_e32 v40, v40
	v_sub_f32_e32 v41, v41, v13
	v_add_f32_e32 v46, v37, v46
	v_exp_f32_e32 v41, v41
	v_sub_f32_e32 v42, v42, v13
	v_add_f32_e32 v46, v38, v46
	v_exp_f32_e32 v42, v42
	v_sub_f32_e32 v43, v43, v13
	v_add_f32_e32 v46, v39, v46
	v_exp_f32_e32 v43, v43
	v_sub_f32_e32 v44, v44, v13
	v_add_f32_e32 v46, v40, v46
	v_exp_f32_e32 v44, v44
	v_sub_f32_e32 v45, v45, v13
	v_add_f32_e32 v46, v41, v46
	v_exp_f32_e32 v45, v45
	v_sub_f32_e32 v8, v8, v13
	v_add_f32_e32 v46, v42, v46
	v_exp_f32_e32 v47, v8
	v_add_f32_e32 v46, v43, v46
	v_add_f32_e32 v46, v44, v46
	v_add_f32_e32 v46, v45, v46
	v_sub_f32_e32 v9, v9, v13
	v_add_f32_e32 v8, v47, v46
	v_exp_f32_e32 v46, v9
	v_sub_f32_e32 v9, v10, v13
	v_exp_f32_e32 v10, v9
	v_sub_f32_e32 v9, v11, v13
	v_exp_f32_e32 v11, v9
	v_sub_f32_e32 v9, 0xff800000, v13
	v_exp_f32_e32 v50, v9
	v_add_f32_e32 v8, v46, v8
	v_add_f32_e32 v8, v10, v8
	v_add_f32_e32 v8, v11, v8
	v_add_f32_e32 v8, v50, v8
	v_add_f32_e32 v8, v50, v8
	v_add_f32_e32 v8, v50, v8
	v_add_f32_e32 v8, v50, v8
	ds_bpermute_b32 v9, v94, v8
	s_waitcnt lgkmcnt(0)
; #define LAS __attribute__((address_space(3)))
; __device__ __forceinline__ unsigned cvt_pk_bf16(float lo, float hi) { unsigned r; asm volatile("s_nop 1\n\tv_cvt_pk_bf16_f32 %0, %1, %2" : "=v"(r) : "v"(lo), "v"(hi)); return r; }
; __device__ __forceinline__ float shx(float v, int o, int lane) { return __int_as_float(__builtin_amdgcn_ds_bpermute((lane ^ o) << 2, __float_as_int(v))); }
; #define MFMA16(a, b, c) __builtin_amdgcn_mfma_f32_16x16x32_bf16((a), (b), (c), 0, 0, 0)
; __device__ __forceinline__ void attn_item(ldsp lds, int item, bf16_t* aq, const bf16_t* ak, const bf16_t* avT, const float* sinks, int tid, int w, int fr, int fq) {
;     ...
;         sum += shx(sum, 16, ln); sum += shx(sum, 32, ln);
;         const float inv = 1.0f / (sum + __builtin_amdgcn_exp2f(sink2 - mx));
; #pragma unroll
;         for (int tt = 0; tt < 10; ++tt) { u32x2 wv; wv.x = cvt_pk_bf16(s[tt][0] * inv, s[tt][1] * inv); wv.y = cvt_pk_bf16(s[tt][2] * inv, s[tt][3] * inv);
;             *(LAS u32x2*)(Pb + fr * 336 + (16 * tt + 4 * fq) * 2) = wv; }
;         asm volatile("s_waitcnt lgkmcnt(0)" ::: "memory");
;         f32x4 o[4];
; #pragma unroll
;         for (int nt = 0; nt < 4; ++nt) o[nt] = (f32x4){0.f, 0.f, 0.f, 0.f};
; #pragma unroll
;         for (int ks = 0; ks < 5; ++ks) {
;             const bf16x8 a = *(const LAS bf16x8*)(Pb + fr * 336 + ks * 64 + fq * 16);
; #pragma unroll
;             for (int nt = 0; nt < 4; ++nt) o[nt] = MFMA16(*(const LAS bf16x8*)(Vb + (16 * nt + fr) * 560 + (16 * r + 32 * ks + 8 * fq) * 2), a, o[nt]);
;         }
	v_add_f32_e32 v8, v8, v9
	ds_bpermute_b32 v9, v95, v8
	s_waitcnt lgkmcnt(0)
	v_add_f32_e32 v8, v8, v9
	v_fma_f32 v9, v12, s88, -v13
	v_exp_f32_e32 v9, v9
	s_nop 0
	v_add_f32_e32 v8, v9, v8
	v_div_scale_f32 v9, vcc, v8, v8, 1.0
	v_rcp_f32_e32 v12, v9
	s_nop 0
	v_fma_f32 v13, -v9, v12, 1.0
	v_fmac_f32_e32 v12, v13, v12
	v_div_scale_f32 v13, vcc, 1.0, v8, 1.0
	v_mul_f32_e32 v51, v13, v12
	v_fma_f32 v52, -v9, v51, v13
	v_fmac_f32_e32 v51, v52, v12
	v_fma_f32 v9, -v9, v51, v13
	v_div_fmas_f32 v9, v9, v12, v51
	v_div_fixup_f32 v12, v9, v8, 1.0
	v_mul_f32_e32 v8, v14, v12
	v_mul_f32_e32 v9, v15, v12
	s_nop 1
	v_cvt_pk_bf16_f32 v8, v8, v9
	v_mul_f32_e32 v9, v16, v12
	v_mul_f32_e32 v13, v17, v12
	s_nop 1
	v_cvt_pk_bf16_f32 v9, v9, v13
	ds_write_b64 v112, v[8:9]
	v_mul_f32_e32 v8, v18, v12
	v_mul_f32_e32 v9, v19, v12
	s_nop 1
	v_cvt_pk_bf16_f32 v8, v8, v9
	v_mul_f32_e32 v9, v20, v12
	v_mul_f32_e32 v13, v21, v12
	s_nop 1
	v_cvt_pk_bf16_f32 v9, v9, v13
	ds_write_b64 v112, v[8:9] offset:32
	v_mul_f32_e32 v8, v22, v12
	v_mul_f32_e32 v9, v23, v12
	s_nop 1
	v_cvt_pk_bf16_f32 v8, v8, v9
	v_mul_f32_e32 v9, v24, v12
	v_mul_f32_e32 v13, v25, v12
	s_nop 1
	v_cvt_pk_bf16_f32 v9, v9, v13
	ds_write_b64 v112, v[8:9] offset:64
	v_mul_f32_e32 v8, v26, v12
	v_mul_f32_e32 v9, v27, v12
	s_nop 1
	v_cvt_pk_bf16_f32 v8, v8, v9
	v_mul_f32_e32 v9, v28, v12
	v_mul_f32_e32 v13, v29, v12
	s_nop 1
	v_cvt_pk_bf16_f32 v9, v9, v13
	ds_write_b64 v112, v[8:9] offset:96
	v_mul_f32_e32 v8, v30, v12
	v_mul_f32_e32 v9, v31, v12
	s_nop 1
	v_cvt_pk_bf16_f32 v8, v8, v9
	v_mul_f32_e32 v9, v32, v12
	v_mul_f32_e32 v13, v33, v12
	s_nop 1
	v_cvt_pk_bf16_f32 v9, v9, v13
	ds_write_b64 v112, v[8:9] offset:128
	v_mul_f32_e32 v8, v34, v12
	v_mul_f32_e32 v9, v35, v12
	s_nop 1
	v_cvt_pk_bf16_f32 v8, v8, v9
	v_mul_f32_e32 v9, v36, v12
	v_mul_f32_e32 v13, v37, v12
	s_nop 1
	v_cvt_pk_bf16_f32 v9, v9, v13
	ds_write_b64 v112, v[8:9] offset:160
	v_mul_f32_e32 v8, v38, v12
	v_mul_f32_e32 v9, v39, v12
	s_nop 1
	v_cvt_pk_bf16_f32 v8, v8, v9
	v_mul_f32_e32 v9, v40, v12
	v_mul_f32_e32 v13, v41, v12
	s_nop 1
	v_cvt_pk_bf16_f32 v9, v9, v13
	ds_write_b64 v112, v[8:9] offset:192
	v_mul_f32_e32 v8, v42, v12
	v_mul_f32_e32 v9, v43, v12
	s_nop 1
	v_cvt_pk_bf16_f32 v8, v8, v9
	v_mul_f32_e32 v9, v44, v12
	v_mul_f32_e32 v13, v45, v12
	s_nop 1
	v_cvt_pk_bf16_f32 v9, v9, v13
	ds_write_b64 v112, v[8:9] offset:224
	v_mul_f32_e32 v8, v47, v12
	v_mul_f32_e32 v9, v46, v12
	s_nop 1
	v_cvt_pk_bf16_f32 v8, v8, v9
	v_mul_f32_e32 v9, v10, v12
	v_mul_f32_e32 v10, v11, v12
	s_nop 1
	v_cvt_pk_bf16_f32 v9, v9, v10
	ds_write_b64 v112, v[8:9] offset:256
	v_mul_f32_e32 v9, v50, v12
	s_nop 1
	v_cvt_pk_bf16_f32 v8, v9, v9
	s_nop 1
	v_cvt_pk_bf16_f32 v9, v9, v9
	ds_write_b64 v112, v[8:9] offset:288
	s_waitcnt lgkmcnt(0)
	ds_read_b128 v[8:11], v113
	ds_read_b128 v[12:15], v114 offset:39168
	ds_read_b128 v[16:19], v114 offset:48128
	ds_read_b128 v[20:23], v114 offset:57088
	ds_read_b128 v[24:27], v115 offset:39168
	s_waitcnt lgkmcnt(3)
	v_mfma_f32_16x16x32_bf16 v[12:15], v[12:15], v[8:11], 0
	s_or_b32 vcc_lo, s2, 0x100
	s_mov_b32 vcc_hi, s3
	s_or_b32 s2, s2, 0x180
	s_waitcnt lgkmcnt(2)
	v_mfma_f32_16x16x32_bf16 v[16:19], v[16:19], v[8:11], 0
	s_cmpk_gt_i32 s92, 0x3ff
	s_waitcnt lgkmcnt(1)
	v_mfma_f32_16x16x32_bf16 v[20:23], v[20:23], v[8:11], 0
	s_waitcnt lgkmcnt(0)
	v_mfma_f32_16x16x32_bf16 v[8:11], v[24:27], v[8:11], 0
	ds_read_b128 v[24:27], v113 offset:64
	ds_read_b128 v[28:31], v114 offset:39232
	s_waitcnt lgkmcnt(0)
	v_mfma_f32_16x16x32_bf16 v[12:15], v[28:31], v[24:27], v[12:15]
	ds_read_b128 v[28:31], v114 offset:48192
	s_waitcnt lgkmcnt(0)
	v_mfma_f32_16x16x32_bf16 v[16:19], v[28:31], v[24:27], v[16:19]
	ds_read_b128 v[28:31], v114 offset:57152
	s_waitcnt lgkmcnt(0)
	v_mfma_f32_16x16x32_bf16 v[20:23], v[28:31], v[24:27], v[20:23]
	ds_read_b128 v[28:31], v115 offset:39232
	s_waitcnt lgkmcnt(0)
	v_mfma_f32_16x16x32_bf16 v[8:11], v[28:31], v[24:27], v[8:11]
	ds_read_b128 v[24:27], v113 offset:128
	ds_read_b128 v[28:31], v114 offset:39296
	s_waitcnt lgkmcnt(0)
	v_mfma_f32_16x16x32_bf16 v[12:15], v[28:31], v[24:27], v[12:15]
	ds_read_b128 v[28:31], v114 offset:48256
	s_waitcnt lgkmcnt(0)
	v_mfma_f32_16x16x32_bf16 v[16:19], v[28:31], v[24:27], v[16:19]
	ds_read_b128 v[28:31], v114 offset:57216
	s_waitcnt lgkmcnt(0)
	v_mfma_f32_16x16x32_bf16 v[20:23], v[28:31], v[24:27], v[20:23]
	ds_read_b128 v[28:31], v115 offset:39296
	s_waitcnt lgkmcnt(0)
	v_mfma_f32_16x16x32_bf16 v[8:11], v[28:31], v[24:27], v[8:11]
	ds_read_b128 v[24:27], v113 offset:192
	ds_read_b128 v[28:31], v114 offset:39360
	s_waitcnt lgkmcnt(0)
	v_mfma_f32_16x16x32_bf16 v[12:15], v[28:31], v[24:27], v[12:15]
	ds_read_b128 v[28:31], v114 offset:48320
	s_waitcnt lgkmcnt(0)
	v_mfma_f32_16x16x32_bf16 v[16:19], v[28:31], v[24:27], v[16:19]
	ds_read_b128 v[28:31], v114 offset:57280
	s_waitcnt lgkmcnt(0)
	v_mfma_f32_16x16x32_bf16 v[20:23], v[28:31], v[24:27], v[20:23]
	ds_read_b128 v[28:31], v115 offset:39360
	s_waitcnt lgkmcnt(0)
	v_mfma_f32_16x16x32_bf16 v[24:27], v[28:31], v[24:27], v[8:11]
	ds_read_b128 v[28:31], v113 offset:256
	s_nop 1
	ds_read_b128 v[8:11], v114 offset:39424
	s_waitcnt lgkmcnt(0)
	v_mfma_f32_16x16x32_bf16 v[8:11], v[8:11], v[28:31], v[12:15]
	s_nop 2
	ds_read_b128 v[12:15], v114 offset:48384
	s_waitcnt lgkmcnt(0)
	v_mfma_f32_16x16x32_bf16 v[12:15], v[12:15], v[28:31], v[16:19]
	s_nop 2
	ds_read_b128 v[16:19], v114 offset:57344
	s_waitcnt lgkmcnt(0)
	v_mfma_f32_16x16x32_bf16 v[20:23], v[16:19], v[28:31], v[20:23]
	ds_read_b128 v[16:19], v115 offset:39424
	s_nop 1
	v_cvt_pk_bf16_f32 v8, v8, v9
	s_nop 1
	v_cvt_pk_bf16_f32 v9, v10, v11
	s_waitcnt lgkmcnt(0)
; #define LAS __attribute__((address_space(3)))
; __device__ __forceinline__ unsigned cvt_pk_bf16(float lo, float hi) { unsigned r; asm volatile("s_nop 1\n\tv_cvt_pk_bf16_f32 %0, %1, %2" : "=v"(r) : "v"(lo), "v"(hi)); return r; }
; __device__ __forceinline__ float shx(float v, int o, int lane) { return __int_as_float(__builtin_amdgcn_ds_bpermute((lane ^ o) << 2, __float_as_int(v))); }
; #define MFMA16(a, b, c) __builtin_amdgcn_mfma_f32_16x16x32_bf16((a), (b), (c), 0, 0, 0)
; __device__ __forceinline__ void attn_item(ldsp lds, int item, bf16_t* aq, const bf16_t* ak, const bf16_t* avT, const float* sinks, int tid, int w, int fr, int fq) {
;     ...
; #pragma unroll
;         for (int tt = 0; tt < 10; ++tt) { s[tt] = (f32x4){0.f, 0.f, 0.f, 0.f};
;             const bf16x8 b0 = *(const LAS bf16x8*)(Kb + (16 * (r + tt) + fr) * 144 + fq * 16), b1 = *(const LAS bf16x8*)(Kb + (16 * (r + tt) + fr) * 144 + 64 + fq * 16);
;             s[tt] = MFMA16(b0, a0, s[tt]); s[tt] = MFMA16(b1, a1, s[tt]); }
;         const float sink2 = sinks[hq] * LOG2E; float mx = sink2;
; #pragma unroll
;         for (int tt = 0; tt < 10; ++tt)
; #pragma unroll
;             for (int j = 0; j < 4; ++j) { const int kr = 16 * tt + 4 * fq + j; const bool valid = (kr > fr) && (kr <= fr + 128) && (n > 0 || 16 * r + kr >= 128);
;                 s[tt][j] = valid ? s[tt][j] : -INFINITY; mx = fmaxf(mx, s[tt][j]); }
;         const int ln = fr + 16 * fq;
;         mx = fmaxf(mx, shx(mx, 16, ln)); mx = fmaxf(mx, shx(mx, 32, ln));
;     ...
;         for (int nt = 0; nt < 4; ++nt) { u32x2 wv; wv.x = cvt_pk_bf16(o[nt][0], o[nt][1]); wv.y = cvt_pk_bf16(o[nt][2], o[nt][3]); *(u32x2*)(qp + 16 * nt + 4 * fq) = wv; }
	v_mfma_f32_16x16x32_bf16 v[16:19], v[16:19], v[28:31], v[24:27]
	s_nop 2
	v_lshl_add_u64 v[24:25], v[90:91], 0, vcc
	flat_store_dwordx2 v[24:25], v[8:9]
	s_nop 1
	v_cvt_pk_bf16_f32 v8, v12, v13
	s_nop 1
	v_cvt_pk_bf16_f32 v9, v14, v15
	flat_store_dwordx2 v[24:25], v[8:9] offset:32
	s_nop 1
	v_cvt_pk_bf16_f32 v8, v20, v21
	s_nop 1
	v_cvt_pk_bf16_f32 v9, v22, v23
	flat_store_dwordx2 v[24:25], v[8:9] offset:64
	s_nop 1
	v_cvt_pk_bf16_f32 v8, v16, v17
	s_nop 1
	v_cvt_pk_bf16_f32 v9, v18, v19
	flat_store_dwordx2 v[24:25], v[8:9] offset:96
	s_waitcnt lgkmcnt(0)
	ds_read_b128 v[8:11], v64
	ds_read_b128 v[12:15], v64 offset:64
	s_waitcnt lgkmcnt(0)
	v_mfma_f32_16x16x32_bf16 v[8:11], v[8:11], v[0:3], 0
	v_mfma_f32_16x16x32_bf16 v[28:31], v[12:15], v[4:7], v[8:11]
	s_nop 6
	ds_read_b128 v[8:11], v104
	ds_read_b128 v[12:15], v104 offset:64
	s_waitcnt lgkmcnt(0)
	v_mfma_f32_16x16x32_bf16 v[8:11], v[8:11], v[0:3], 0
	v_mfma_f32_16x16x32_bf16 v[32:35], v[12:15], v[4:7], v[8:11]
	s_nop 6
	ds_read_b128 v[8:11], v105
	ds_read_b128 v[12:15], v105 offset:64
	s_waitcnt lgkmcnt(0)
	v_mfma_f32_16x16x32_bf16 v[8:11], v[8:11], v[0:3], 0
	v_mfma_f32_16x16x32_bf16 v[36:39], v[12:15], v[4:7], v[8:11]
	s_nop 6
	ds_read_b128 v[8:11], v106
	ds_read_b128 v[12:15], v106 offset:64
	s_waitcnt lgkmcnt(0)
	v_mfma_f32_16x16x32_bf16 v[8:11], v[8:11], v[0:3], 0
	v_mfma_f32_16x16x32_bf16 v[24:27], v[12:15], v[4:7], v[8:11]
	s_nop 6
	ds_read_b128 v[8:11], v107
	ds_read_b128 v[12:15], v107 offset:64
	v_cndmask_b32_e64 v24, v118, v24, s[26:27]
	s_waitcnt lgkmcnt(0)
	v_mfma_f32_16x16x32_bf16 v[8:11], v[8:11], v[0:3], 0
	v_cndmask_b32_e64 v25, v118, v25, s[16:17]
	v_cndmask_b32_e64 v26, v118, v26, s[24:25]
	v_cndmask_b32_e64 v27, v118, v27, s[36:37]
	v_mfma_f32_16x16x32_bf16 v[20:23], v[12:15], v[4:7], v[8:11]
	s_nop 3
	ds_read_b128 v[8:11], v108
	ds_read_b128 v[12:15], v108 offset:64
	s_nop 1
	v_cndmask_b32_e64 v20, v118, v20, s[20:21]
	s_waitcnt lgkmcnt(0)
	v_mfma_f32_16x16x32_bf16 v[8:11], v[8:11], v[0:3], 0
	v_cndmask_b32_e64 v21, v118, v21, s[66:67]
	v_cndmask_b32_e64 v22, v118, v22, s[68:69]
	v_cndmask_b32_e64 v23, v118, v23, s[64:65]
	v_mfma_f32_16x16x32_bf16 v[16:19], v[12:15], v[4:7], v[8:11]
	s_nop 3
	ds_read_b128 v[8:11], v109
	ds_read_b128 v[12:15], v109 offset:64
	s_nop 1
	v_cndmask_b32_e64 v16, v118, v16, s[62:63]
	s_waitcnt lgkmcnt(0)
	v_mfma_f32_16x16x32_bf16 v[8:11], v[8:11], v[0:3], 0
	v_cndmask_b32_e64 v17, v118, v17, s[58:59]
	v_cndmask_b32_e64 v18, v118, v18, s[60:61]
	v_cndmask_b32_e64 v19, v118, v19, s[56:57]
	v_mfma_f32_16x16x32_bf16 v[12:15], v[12:15], v[4:7], v[8:11]
	s_nop 3
	ds_read_b128 v[8:11], v110
	ds_read_b128 v[40:43], v110 offset:64
	s_nop 1
	v_cndmask_b32_e64 v12, v118, v12, s[54:55]
	s_waitcnt lgkmcnt(0)
	v_mfma_f32_16x16x32_bf16 v[8:11], v[8:11], v[0:3], 0
	v_cndmask_b32_e64 v13, v118, v13, s[48:49]
	v_cndmask_b32_e64 v14, v118, v14, s[52:53]
	v_cndmask_b32_e64 v15, v118, v15, s[46:47]
	v_mfma_f32_16x16x32_bf16 v[8:11], v[40:43], v[4:7], v[8:11]
	ds_read_b128 v[40:43], v111
	ds_read_b128 v[44:47], v111 offset:64
	s_waitcnt lgkmcnt(0)
	v_mfma_f32_16x16x32_bf16 v[0:3], v[40:43], v[0:3], 0
	s_nop 3
	v_cndmask_b32_e64 v8, v118, v8, s[50:51]
	v_cndmask_b32_e64 v10, v118, v10, s[78:79]
	v_cndmask_b32_e64 v9, v118, v9, s[12:13]
	v_mfma_f32_16x16x32_bf16 v[2:5], v[44:47], v[4:7], v[0:3]
	v_cndmask_b32_e64 v6, v118, v29, s[10:11]
	v_cndmask_b32_e64 v7, v118, v30, s[8:9]
	v_cndmask_b32_e64 v6, v6, v118, s[18:19]
	flat_load_dword v0, v[48:49] offset:12 nt
	v_cndmask_b32_e64 v1, v118, v28, s[6:7]
	v_max_f32_e32 v30, v1, v1
	v_cndmask_b32_e64 v28, v118, v31, s[4:5]
	v_cndmask_b32_e64 v31, v118, v33, s[28:29]
	v_cndmask_b32_e64 v33, v118, v35, s[44:45]
	v_cndmask_b32_e64 v35, v118, v37, s[22:23]
	v_cndmask_b32_e64 v37, v118, v39, s[42:43]
	v_cndmask_b32_e64 v2, v118, v2, s[76:77]
	v_cndmask_b32_e64 v11, v118, v11, s[80:81]
	v_cndmask_b32_e64 v2, v2, v118, s[14:15]
	v_cndmask_b32_e64 v3, v118, v3, s[74:75]
	v_cndmask_b32_e64 v4, v118, v4, s[72:73]
	v_cndmask_b32_e64 v3, v3, v118, s[90:91]
	v_cndmask_b32_e64 v4, v4, v118, s[94:95]
	v_cndmask_b32_e64 v5, v118, v5, s[70:71]
	v_cndmask_b32_e64 v5, v5, v118, s[0:1]
	s_waitcnt vmcnt(0) lgkmcnt(0)
	v_mul_f32_e32 v29, 0x3fb8aa3b, v0
	v_max_f32_e32 v29, v29, v30
	v_max3_f32 v29, v29, v6, v7
	v_cndmask_b32_e64 v30, v118, v32, s[40:41]
	v_max3_f32 v29, v29, v28, v30
	v_cndmask_b32_e64 v32, v118, v34, s[38:39]
	v_max3_f32 v29, v29, v31, v32
	v_cndmask_b32_e64 v34, v118, v36, s[34:35]
	v_max3_f32 v29, v29, v33, v34
	v_cndmask_b32_e64 v36, v118, v38, s[30:31]
	v_max3_f32 v29, v29, v35, v36
	v_max3_f32 v29, v29, v37, v24
	v_max3_f32 v29, v29, v25, v26
	v_max3_f32 v29, v29, v27, v20
	v_max3_f32 v29, v29, v21, v22
	v_max3_f32 v29, v29, v23, v16
	v_max3_f32 v29, v29, v17, v18
	v_max3_f32 v29, v29, v19, v12
	v_max3_f32 v29, v29, v13, v14
	v_max3_f32 v29, v29, v15, v8
	v_max3_f32 v29, v29, v9, v10
	v_max3_f32 v29, v29, v11, v2
	v_max3_f32 v29, v29, v3, v4
	v_max3_f32 v29, v29, v5, s89
	ds_bpermute_b32 v38, v94, v29
	s_waitcnt lgkmcnt(0)
	v_max_f32_e32 v38, v38, v38
	v_max_f32_e32 v29, v29, v38
	ds_bpermute_b32 v38, v95, v29
	s_waitcnt lgkmcnt(0)
; #define LAS __attribute__((address_space(3)))
; __device__ __forceinline__ unsigned cvt_pk_bf16(float lo, float hi) { unsigned r; asm volatile("s_nop 1\n\tv_cvt_pk_bf16_f32 %0, %1, %2" : "=v"(r) : "v"(lo), "v"(hi)); return r; }
; __device__ __forceinline__ float shx(float v, int o, int lane) { return __int_as_float(__builtin_amdgcn_ds_bpermute((lane ^ o) << 2, __float_as_int(v))); }
; __device__ __forceinline__ void attn_item(ldsp lds, int item, bf16_t* aq, const bf16_t* ak, const bf16_t* avT, const float* sinks, int tid, int w, int fr, int fq) {
;     ...
;         const int ln = fr + 16 * fq;
;         mx = fmaxf(mx, shx(mx, 16, ln)); mx = fmaxf(mx, shx(mx, 32, ln));
;         float sum = 0.f;
; #pragma unroll
;         for (int tt = 0; tt < 10; ++tt)
; #pragma unroll
;             for (int j = 0; j < 4; ++j) { s[tt][j] = __builtin_amdgcn_exp2f(s[tt][j] - mx); sum += s[tt][j]; }
;         sum += shx(sum, 16, ln); sum += shx(sum, 32, ln);
;         const float inv = 1.0f / (sum + __builtin_amdgcn_exp2f(sink2 - mx));
; #pragma unroll
;         for (int tt = 0; tt < 10; ++tt) { u32x2 wv; wv.x = cvt_pk_bf16(s[tt][0] * inv, s[tt][1] * inv); wv.y = cvt_pk_bf16(s[tt][2] * inv, s[tt][3] * inv);
;             *(LAS u32x2*)(Pb + fr * 336 + (16 * tt + 4 * fq) * 2) = wv; }
	v_max_f32_e32 v38, v38, v38
	v_max_f32_e32 v29, v29, v38
	v_sub_f32_e32 v1, v1, v29
	v_exp_f32_e32 v1, v1
	v_sub_f32_e32 v6, v6, v29
	v_exp_f32_e32 v6, v6
	v_sub_f32_e32 v7, v7, v29
	v_exp_f32_e32 v7, v7
	v_sub_f32_e32 v28, v28, v29
	v_exp_f32_e32 v28, v28
	v_sub_f32_e32 v30, v30, v29
	v_add_f32_e32 v38, 0, v1
	v_exp_f32_e32 v30, v30
	v_sub_f32_e32 v31, v31, v29
	v_add_f32_e32 v38, v6, v38
	v_exp_f32_e32 v31, v31
	v_sub_f32_e32 v32, v32, v29
	v_add_f32_e32 v38, v7, v38
	v_exp_f32_e32 v32, v32
	v_sub_f32_e32 v33, v33, v29
	v_add_f32_e32 v38, v28, v38
	v_exp_f32_e32 v33, v33
	v_sub_f32_e32 v34, v34, v29
	v_add_f32_e32 v38, v30, v38
	v_exp_f32_e32 v34, v34
	v_sub_f32_e32 v35, v35, v29
	v_add_f32_e32 v38, v31, v38
	v_exp_f32_e32 v35, v35
	v_sub_f32_e32 v36, v36, v29
	v_add_f32_e32 v38, v32, v38
	v_exp_f32_e32 v36, v36
	v_sub_f32_e32 v37, v37, v29
	v_add_f32_e32 v38, v33, v38
	v_exp_f32_e32 v37, v37
	v_sub_f32_e32 v24, v24, v29
	v_add_f32_e32 v38, v34, v38
	v_exp_f32_e32 v24, v24
	v_sub_f32_e32 v25, v25, v29
	v_add_f32_e32 v38, v35, v38
	v_exp_f32_e32 v25, v25
	v_sub_f32_e32 v26, v26, v29
	v_add_f32_e32 v38, v36, v38
	v_exp_f32_e32 v26, v26
	v_sub_f32_e32 v27, v27, v29
	v_add_f32_e32 v38, v37, v38
	v_exp_f32_e32 v27, v27
	v_sub_f32_e32 v20, v20, v29
	v_add_f32_e32 v38, v24, v38
	v_exp_f32_e32 v20, v20
	v_sub_f32_e32 v21, v21, v29
	v_add_f32_e32 v38, v25, v38
	v_exp_f32_e32 v21, v21
	v_sub_f32_e32 v22, v22, v29
	v_add_f32_e32 v38, v26, v38
	v_exp_f32_e32 v22, v22
	v_sub_f32_e32 v23, v23, v29
	v_add_f32_e32 v38, v27, v38
	v_exp_f32_e32 v23, v23
	v_sub_f32_e32 v16, v16, v29
	v_add_f32_e32 v38, v20, v38
	v_exp_f32_e32 v16, v16
	v_sub_f32_e32 v17, v17, v29
	v_add_f32_e32 v38, v21, v38
	v_exp_f32_e32 v17, v17
	v_sub_f32_e32 v18, v18, v29
	v_add_f32_e32 v38, v22, v38
	v_exp_f32_e32 v18, v18
	v_sub_f32_e32 v19, v19, v29
	v_add_f32_e32 v38, v23, v38
	v_exp_f32_e32 v19, v19
	v_sub_f32_e32 v12, v12, v29
	v_add_f32_e32 v38, v16, v38
	v_exp_f32_e32 v12, v12
	v_sub_f32_e32 v13, v13, v29
	v_add_f32_e32 v38, v17, v38
	v_exp_f32_e32 v13, v13
	v_sub_f32_e32 v14, v14, v29
	v_add_f32_e32 v38, v18, v38
	v_exp_f32_e32 v14, v14
	v_sub_f32_e32 v15, v15, v29
	v_add_f32_e32 v38, v19, v38
	v_exp_f32_e32 v15, v15
	v_sub_f32_e32 v8, v8, v29
	v_add_f32_e32 v38, v12, v38
	v_exp_f32_e32 v8, v8
	v_sub_f32_e32 v9, v9, v29
	v_add_f32_e32 v38, v13, v38
	v_exp_f32_e32 v9, v9
	v_sub_f32_e32 v10, v10, v29
	v_add_f32_e32 v38, v14, v38
	v_exp_f32_e32 v10, v10
	v_sub_f32_e32 v11, v11, v29
	v_add_f32_e32 v38, v15, v38
	v_exp_f32_e32 v11, v11
	v_sub_f32_e32 v2, v2, v29
	v_add_f32_e32 v38, v8, v38
	v_exp_f32_e32 v2, v2
	v_sub_f32_e32 v3, v3, v29
	v_add_f32_e32 v38, v9, v38
	v_exp_f32_e32 v3, v3
	v_sub_f32_e32 v4, v4, v29
	v_add_f32_e32 v38, v10, v38
	v_exp_f32_e32 v4, v4
	v_sub_f32_e32 v5, v5, v29
	v_add_f32_e32 v38, v11, v38
	v_exp_f32_e32 v5, v5
	v_sub_f32_e32 v39, 0xff800000, v29
	v_add_f32_e32 v38, v2, v38
	v_exp_f32_e32 v39, v39
	v_add_f32_e32 v38, v3, v38
	v_add_f32_e32 v38, v4, v38
	v_add_f32_e32 v38, v5, v38
	v_add_f32_e32 v38, v39, v38
	v_add_f32_e32 v38, v39, v38
	v_add_f32_e32 v38, v39, v38
	v_add_f32_e32 v38, v39, v38
	ds_bpermute_b32 v40, v94, v38
	v_fma_f32 v0, v0, s88, -v29
	v_exp_f32_e32 v0, v0
	s_waitcnt lgkmcnt(0)
	v_add_f32_e32 v38, v38, v40
	ds_bpermute_b32 v40, v95, v38
	s_waitcnt lgkmcnt(0)
	v_add_f32_e32 v38, v38, v40
	v_add_f32_e32 v0, v0, v38
	v_div_scale_f32 v29, s[4:5], v0, v0, 1.0
	v_rcp_f32_e32 v38, v29
	s_nop 0
	v_fma_f32 v40, -v29, v38, 1.0
	v_fmac_f32_e32 v38, v40, v38
	v_div_scale_f32 v40, vcc, 1.0, v0, 1.0
	v_mul_f32_e32 v41, v40, v38
	v_fma_f32 v42, -v29, v41, v40
	v_fmac_f32_e32 v41, v42, v38
	v_fma_f32 v29, -v29, v41, v40
	v_div_fmas_f32 v29, v29, v38, v41
	v_div_fixup_f32 v29, v29, v0, 1.0
	v_mul_f32_e32 v0, v1, v29
	v_mul_f32_e32 v1, v6, v29
	s_nop 1
	v_cvt_pk_bf16_f32 v0, v0, v1
	v_mul_f32_e32 v1, v7, v29
	v_mul_f32_e32 v6, v28, v29
	s_nop 1
	v_cvt_pk_bf16_f32 v1, v1, v6
	ds_write_b64 v112, v[0:1]
	v_mul_f32_e32 v0, v30, v29
	v_mul_f32_e32 v1, v31, v29
	s_nop 1
	v_cvt_pk_bf16_f32 v0, v0, v1
	v_mul_f32_e32 v1, v32, v29
	v_mul_f32_e32 v6, v33, v29
	s_nop 1
	v_cvt_pk_bf16_f32 v1, v1, v6
	ds_write_b64 v112, v[0:1] offset:32
	v_mul_f32_e32 v0, v34, v29
	v_mul_f32_e32 v1, v35, v29
	s_nop 1
	v_cvt_pk_bf16_f32 v0, v0, v1
	v_mul_f32_e32 v1, v36, v29
	v_mul_f32_e32 v6, v37, v29
	s_nop 1
	v_cvt_pk_bf16_f32 v1, v1, v6
	ds_write_b64 v112, v[0:1] offset:64
	v_mul_f32_e32 v0, v24, v29
	v_mul_f32_e32 v1, v25, v29
	s_nop 1
	v_cvt_pk_bf16_f32 v0, v0, v1
	v_mul_f32_e32 v1, v26, v29
	v_mul_f32_e32 v6, v27, v29
	s_nop 1
	v_cvt_pk_bf16_f32 v1, v1, v6
	ds_write_b64 v112, v[0:1] offset:96
	v_mul_f32_e32 v0, v20, v29
	v_mul_f32_e32 v1, v21, v29
	s_nop 1
	v_cvt_pk_bf16_f32 v0, v0, v1
	v_mul_f32_e32 v1, v22, v29
	v_mul_f32_e32 v6, v23, v29
	s_nop 1
	v_cvt_pk_bf16_f32 v1, v1, v6
	ds_write_b64 v112, v[0:1] offset:128
	v_mul_f32_e32 v0, v16, v29
	v_mul_f32_e32 v1, v17, v29
	s_nop 1
	v_cvt_pk_bf16_f32 v0, v0, v1
	v_mul_f32_e32 v1, v18, v29
	v_mul_f32_e32 v6, v19, v29
	s_nop 1
	v_cvt_pk_bf16_f32 v1, v1, v6
	ds_write_b64 v112, v[0:1] offset:160
	v_mul_f32_e32 v0, v12, v29
	v_mul_f32_e32 v1, v13, v29
	s_nop 1
	v_cvt_pk_bf16_f32 v0, v0, v1
	v_mul_f32_e32 v1, v14, v29
	v_mul_f32_e32 v6, v15, v29
	s_nop 1
	v_cvt_pk_bf16_f32 v1, v1, v6
	ds_write_b64 v112, v[0:1] offset:192
	v_mul_f32_e32 v0, v8, v29
	v_mul_f32_e32 v1, v9, v29
	s_nop 1
	v_cvt_pk_bf16_f32 v0, v0, v1
	v_mul_f32_e32 v1, v10, v29
	v_mul_f32_e32 v6, v11, v29
	s_nop 1
	v_cvt_pk_bf16_f32 v1, v1, v6
	ds_write_b64 v112, v[0:1] offset:224
	v_mul_f32_e32 v0, v2, v29
	v_mul_f32_e32 v1, v3, v29
	s_nop 1
	v_cvt_pk_bf16_f32 v0, v0, v1
	v_mul_f32_e32 v1, v4, v29
	v_mul_f32_e32 v2, v5, v29
	s_nop 1
	v_cvt_pk_bf16_f32 v1, v1, v2
	ds_write_b64 v112, v[0:1] offset:256
	v_mul_f32_e32 v1, v39, v29
	s_nop 1
	v_cvt_pk_bf16_f32 v0, v1, v1
	s_nop 1
	v_cvt_pk_bf16_f32 v1, v1, v1
	ds_write_b64 v112, v[0:1] offset:288
	s_waitcnt lgkmcnt(0)
; #define LAS __attribute__((address_space(3)))
; __device__ __forceinline__ unsigned cvt_pk_bf16(float lo, float hi) { unsigned r; asm volatile("s_nop 1\n\tv_cvt_pk_bf16_f32 %0, %1, %2" : "=v"(r) : "v"(lo), "v"(hi)); return r; }
; #define MFMA16(a, b, c) __builtin_amdgcn_mfma_f32_16x16x32_bf16((a), (b), (c), 0, 0, 0)
; __device__ __forceinline__ void attn_item(ldsp lds, int item, bf16_t* aq, const bf16_t* ak, const bf16_t* avT, const float* sinks, int tid, int w, int fr, int fq) {
;     const int b = item >> 9, n = (item >> 2) & 127, kvh = item & 3;
;     const size_t row0 = (size_t)b * SEQ + n * 128;
;     ldsp Kb = lds + AK_OFF, Vb = lds + AV_OFF, Pb = lds + AP_OFF + w * 5376;
;     bf16x8 qa[4][2];
;     {
;         const bf16_t* qb = aq + (row0 + 16 * w + fr) * 1024 + kvh * 256;
; #pragma unroll
;         for (int hl = 0; hl < 4; ++hl) { qa[hl][0] = *(const bf16x8*)(qb + hl * 64 + 8 * fq); qa[hl][1] = *(const bf16x8*)(qb + hl * 64 + 32 + 8 * fq); }
;     }
;     const u32x4 z4 = (u32x4){0u, 0u, 0u, 0u};
; #pragma unroll
;     for (int i = 0; i < 4; ++i) { const int idx = tid + 512 * i, key = idx >> 3, c = idx & 7;
;         u32x4 v = z4; if (n > 0 || key >= 128) v = *(const u32x4*)(ak + (row0 - 128 + key) * 256 + kvh * 64 + c * 8);
;         *(LAS u32x4*)(Kb + key * 144 + c * 16) = v; }
;     ...
; #pragma unroll
;         for (int ks = 0; ks < 5; ++ks) {
;             const bf16x8 a = *(const LAS bf16x8*)(Pb + fr * 336 + ks * 64 + fq * 16);
; #pragma unroll
;             for (int nt = 0; nt < 4; ++nt) o[nt] = MFMA16(*(const LAS bf16x8*)(Vb + (16 * nt + fr) * 560 + (16 * r + 32 * ks + 8 * fq) * 2), a, o[nt]);
;         }
; #pragma unroll
;         for (int nt = 0; nt < 4; ++nt) { u32x2 wv; wv.x = cvt_pk_bf16(o[nt][0], o[nt][1]); wv.y = cvt_pk_bf16(o[nt][2], o[nt][3]); *(u32x2*)(qp + 16 * nt + 4 * fq) = wv; }
;         asm volatile("s_waitcnt lgkmcnt(0)" ::: "memory");
;     }
;     __syncthreads();
	ds_read_b128 v[0:3], v113
	ds_read_b128 v[4:7], v114 offset:39168
	ds_read_b128 v[8:11], v114 offset:48128
	ds_read_b128 v[12:15], v114 offset:57088
	ds_read_b128 v[16:19], v115 offset:39168
	s_waitcnt lgkmcnt(3)
	v_mfma_f32_16x16x32_bf16 v[4:7], v[4:7], v[0:3], 0
	s_waitcnt lgkmcnt(2)
	v_mfma_f32_16x16x32_bf16 v[8:11], v[8:11], v[0:3], 0
	s_waitcnt lgkmcnt(1)
	v_mfma_f32_16x16x32_bf16 v[12:15], v[12:15], v[0:3], 0
	s_waitcnt lgkmcnt(0)
	v_mfma_f32_16x16x32_bf16 v[0:3], v[16:19], v[0:3], 0
	ds_read_b128 v[16:19], v113 offset:64
	ds_read_b128 v[20:23], v114 offset:39232
	s_waitcnt lgkmcnt(0)
	v_mfma_f32_16x16x32_bf16 v[4:7], v[20:23], v[16:19], v[4:7]
	ds_read_b128 v[20:23], v114 offset:48192
	s_waitcnt lgkmcnt(0)
	v_mfma_f32_16x16x32_bf16 v[8:11], v[20:23], v[16:19], v[8:11]
	ds_read_b128 v[20:23], v114 offset:57152
	s_waitcnt lgkmcnt(0)
	v_mfma_f32_16x16x32_bf16 v[12:15], v[20:23], v[16:19], v[12:15]
	ds_read_b128 v[20:23], v115 offset:39232
	s_waitcnt lgkmcnt(0)
	v_mfma_f32_16x16x32_bf16 v[0:3], v[20:23], v[16:19], v[0:3]
	ds_read_b128 v[16:19], v113 offset:128
	ds_read_b128 v[20:23], v114 offset:39296
	s_waitcnt lgkmcnt(0)
	v_mfma_f32_16x16x32_bf16 v[4:7], v[20:23], v[16:19], v[4:7]
	ds_read_b128 v[20:23], v114 offset:48256
	s_waitcnt lgkmcnt(0)
	v_mfma_f32_16x16x32_bf16 v[8:11], v[20:23], v[16:19], v[8:11]
	ds_read_b128 v[20:23], v114 offset:57216
	s_waitcnt lgkmcnt(0)
	v_mfma_f32_16x16x32_bf16 v[12:15], v[20:23], v[16:19], v[12:15]
	ds_read_b128 v[20:23], v115 offset:39296
	s_waitcnt lgkmcnt(0)
	v_mfma_f32_16x16x32_bf16 v[0:3], v[20:23], v[16:19], v[0:3]
	ds_read_b128 v[16:19], v113 offset:192
	ds_read_b128 v[20:23], v114 offset:39360
	s_waitcnt lgkmcnt(0)
	v_mfma_f32_16x16x32_bf16 v[4:7], v[20:23], v[16:19], v[4:7]
	ds_read_b128 v[20:23], v114 offset:48320
	s_waitcnt lgkmcnt(0)
	v_mfma_f32_16x16x32_bf16 v[8:11], v[20:23], v[16:19], v[8:11]
	ds_read_b128 v[20:23], v114 offset:57280
	s_waitcnt lgkmcnt(0)
	v_mfma_f32_16x16x32_bf16 v[12:15], v[20:23], v[16:19], v[12:15]
	ds_read_b128 v[20:23], v115 offset:39360
	s_waitcnt lgkmcnt(0)
	v_mfma_f32_16x16x32_bf16 v[0:3], v[20:23], v[16:19], v[0:3]
	ds_read_b128 v[16:19], v113 offset:256
	ds_read_b128 v[20:23], v114 offset:39424
	s_waitcnt lgkmcnt(0)
	v_mfma_f32_16x16x32_bf16 v[4:7], v[20:23], v[16:19], v[4:7]
	ds_read_b128 v[20:23], v114 offset:48384
	s_waitcnt lgkmcnt(0)
	v_mfma_f32_16x16x32_bf16 v[8:11], v[20:23], v[16:19], v[8:11]
	ds_read_b128 v[20:23], v114 offset:57344
	s_waitcnt lgkmcnt(0)
	v_mfma_f32_16x16x32_bf16 v[12:15], v[20:23], v[16:19], v[12:15]
	ds_read_b128 v[20:23], v115 offset:39424
	s_nop 1
	v_cvt_pk_bf16_f32 v4, v4, v5
	s_nop 1
	v_cvt_pk_bf16_f32 v5, v6, v7
	s_waitcnt lgkmcnt(0)
	v_mfma_f32_16x16x32_bf16 v[0:3], v[20:23], v[16:19], v[0:3]
	v_lshl_add_u64 v[16:17], v[90:91], 0, s[2:3]
	flat_store_dwordx2 v[16:17], v[4:5]
	s_nop 1
	v_cvt_pk_bf16_f32 v4, v8, v9
	s_nop 1
	v_cvt_pk_bf16_f32 v5, v10, v11
	flat_store_dwordx2 v[16:17], v[4:5] offset:32
	s_nop 1
	v_cvt_pk_bf16_f32 v4, v12, v13
	s_nop 1
	v_cvt_pk_bf16_f32 v5, v14, v15
	flat_store_dwordx2 v[16:17], v[4:5] offset:64
	s_nop 1
	v_cvt_pk_bf16_f32 v0, v0, v1
	s_nop 1
	v_cvt_pk_bf16_f32 v1, v2, v3
	s_nop 3
	flat_store_dwordx2 v[16:17], v[0:1] offset:96
	s_waitcnt lgkmcnt(0)
	s_waitcnt lgkmcnt(0)
	s_barrier
	s_cbranch_scc1 .LBB0_454
.LBB0_436:
	s_ashr_i32 s4, s92, 9
	s_bfe_u32 s6, s92, 0x70002
	s_ashr_i32 s5, s4, 31
	v_mov_b32_e32 v0, s86
	s_lshl_b64 s[4:5], s[4:5], 14
	s_lshl_b32 s2, s6, 7
	ds_read_b32 v28, v0
	v_mov_b32_e32 v0, s87
	s_or_b32 s4, s4, s2
	ds_read_b32 v29, v0
	v_lshl_add_u64 v[0:1], s[4:5], 0, v[60:61]
	s_and_b32 s10, s92, 3
	v_lshlrev_b64 v[0:1], 11, v[0:1]
	v_lshl_add_u64 v[34:35], s[84:85], 0, v[0:1]
	s_lshl_b32 s2, s10, 9
	v_lshl_add_u64 v[0:1], v[34:35], 0, s[2:3]
	v_lshlrev_b32_e32 v64, 1, v62
	v_lshl_add_u64 v[4:5], v[0:1], 0, v[64:65]
	flat_load_dwordx4 v[24:27], v[4:5] nt
	flat_load_dwordx4 v[48:51], v[4:5] offset:64 nt
	flat_load_dwordx4 v[16:19], v[4:5] offset:128 nt
	flat_load_dwordx4 v[20:23], v[4:5] offset:192 nt
	flat_load_dwordx4 v[8:11], v[4:5] offset:256 nt
	flat_load_dwordx4 v[12:15], v[4:5] offset:320 nt
	flat_load_dwordx4 v[0:3], v[4:5] offset:384 nt
	s_nop 0
	flat_load_dwordx4 v[4:7], v[4:5] offset:448 nt
	s_cmp_lg_u32 s6, 0
	s_cselect_b64 s[70:71], -1, 0
	s_add_u32 s6, s4, 0xffffff80
	s_addc_u32 s7, s5, -1
	s_lshl_b32 s8, s10, 7
	s_mov_b32 s9, s3
	v_lshl_add_u64 v[36:37], v[66:67], 0, s[8:9]
	v_readlane_b32 s8, v254, 11
	v_readlane_b32 s9, v254, 12
	s_waitcnt lgkmcnt(0)
	v_readfirstlane_b32 s11, v28
	v_readfirstlane_b32 s12, v29
	s_or_b64 s[16:17], s[8:9], s[70:71]
	v_mov_b32_e32 v28, 0
	v_mov_b32_e32 v29, 0
	v_mov_b32_e32 v30, 0
	v_mov_b32_e32 v31, 0
	s_and_saveexec_b64 s[8:9], s[16:17]
	s_cbranch_execz .LBB0_438
	v_lshl_add_u64 v[28:29], s[6:7], 0, v[68:69]
	v_lshlrev_b64 v[28:29], 9, v[28:29]
	v_lshl_add_u64 v[28:29], v[36:37], 0, v[28:29]
	flat_load_dwordx4 v[28:31], v[28:29] nt
; #define LAS __attribute__((address_space(3)))
; __device__ __forceinline__ void attn_item(ldsp lds, int item, bf16_t* aq, const bf16_t* ak, const bf16_t* avT, const float* sinks, int tid, int w, int fr, int fq) {
;     ...
;     for (int i = 0; i < 4; ++i) { const int idx = tid + 512 * i, key = idx >> 3, c = idx & 7;
;         u32x4 v = z4; if (n > 0 || key >= 128) v = *(const u32x4*)(ak + (row0 - 128 + key) * 256 + kvh * 64 + c * 8);
;         *(LAS u32x4*)(Kb + key * 144 + c * 16) = v; }
; #pragma unroll
;     for (int i = 0; i < 4; ++i) { const int idx = tid + 512 * i, dh = idx >> 5, c = idx & 31;
;         u32x4 v = z4; if (n > 0 || c >= 16) v = *(const u32x4*)(avT + (((row0 >> 7) - 1 + (c >> 4)) * 256 + kvh * 64 + dh) * 128 + (c & 15) * 8);
;         *(LAS u32x4*)(Vb + dh * 560 + c * 16) = v; }
;     if (tid < 128) { *(LAS u32x4*)(Kb + (256 + (tid >> 3)) * 144 + (tid & 7) * 16) = z4; *(LAS u32x4*)(Vb + (tid >> 1) * 560 + (32 + (tid & 1)) * 16) = z4; }
.LBB0_438:
	s_or_b64 exec, exec, s[8:9]
	v_readlane_b32 s8, v254, 13
	v_add_u32_e32 v32, v63, v92
	v_readlane_b32 s9, v254, 14
	s_waitcnt vmcnt(0) lgkmcnt(0)
	ds_write_b128 v32, v[28:31]
	s_or_b64 s[16:17], s[70:71], s[8:9]
	v_mov_b32_e32 v28, 0
	v_mov_b32_e32 v30, 0
	v_mov_b32_e32 v31, 0
	v_mov_b32_e32 v32, 0
	v_mov_b32_e32 v33, 0
	s_and_saveexec_b64 s[8:9], s[16:17]
	s_cbranch_execz .LBB0_440
	v_lshl_add_u64 v[30:31], s[6:7], 0, v[70:71]
	v_lshlrev_b64 v[30:31], 9, v[30:31]
	v_lshl_add_u64 v[30:31], v[36:37], 0, v[30:31]
	flat_load_dwordx4 v[30:33], v[30:31] nt
.LBB0_440:
	s_or_b64 exec, exec, s[8:9]
	v_readlane_b32 s8, v254, 15
	v_readlane_b32 s9, v254, 16
	s_waitcnt vmcnt(0) lgkmcnt(0)
	ds_write_b128 v97, v[30:33]
	s_or_b64 s[16:17], s[70:71], s[8:9]
	v_mov_b32_e32 v29, 0
	v_mov_b32_e32 v30, 0
	v_mov_b32_e32 v31, 0
	s_and_saveexec_b64 s[8:9], s[16:17]
	s_cbranch_execz .LBB0_442
	v_lshl_add_u64 v[28:29], s[6:7], 0, v[72:73]
	v_lshlrev_b64 v[28:29], 9, v[28:29]
	v_lshl_add_u64 v[28:29], v[36:37], 0, v[28:29]
	flat_load_dwordx4 v[28:31], v[28:29] nt
.LBB0_442:
	s_or_b64 exec, exec, s[8:9]
	v_readlane_b32 s8, v254, 17
	v_readlane_b32 s9, v254, 18
	s_waitcnt vmcnt(0) lgkmcnt(0)
	ds_write_b128 v98, v[28:31]
	s_or_b64 s[16:17], s[70:71], s[8:9]
	v_mov_b32_e32 v28, 0
	v_mov_b32_e32 v29, 0
	v_mov_b32_e32 v30, 0
	v_mov_b32_e32 v31, 0
	s_and_saveexec_b64 s[8:9], s[16:17]
	s_cbranch_execz .LBB0_444
	v_lshl_add_u64 v[28:29], s[6:7], 0, v[74:75]
	v_lshlrev_b64 v[28:29], 9, v[28:29]
	v_lshl_add_u64 v[28:29], v[36:37], 0, v[28:29]
	flat_load_dwordx4 v[28:31], v[28:29] nt
.LBB0_444:
	s_or_b64 exec, exec, s[8:9]
	v_readlane_b32 s6, v254, 19
	v_readlane_b32 s7, v254, 20
	s_nor_b64 s[6:7], s[70:71], s[6:7]
	s_waitcnt vmcnt(0) lgkmcnt(0)
	ds_write_b128 v99, v[28:31]
	s_and_saveexec_b64 s[8:9], s[6:7]
	s_xor_b64 s[8:9], exec, s[8:9]
	ds_write_b128 v116, v[120:123] offset:39168
	s_or_saveexec_b64 s[8:9], s[8:9]
	s_lshr_b64 s[4:5], s[4:5], 7
	v_lshl_add_u64 v[28:29], v[76:77], 0, s[4:5]
	s_lshl_b32 s13, s10, 6
	v_lshlrev_b64 v[32:33], 8, v[28:29]
	v_or_b32_e32 v32, s13, v32
	v_mov_b32_e32 v28, 0
	v_mov_b32_e32 v29, 0
	v_mov_b32_e32 v30, 0
	v_mov_b32_e32 v31, 0
	s_xor_b64 exec, exec, s[8:9]
	s_cbranch_execz .LBB0_448
	v_lshl_add_u64 v[28:29], v[32:33], 0, v[80:81]
	v_lshlrev_b64 v[28:29], 8, v[28:29]
	v_lshl_add_u64 v[28:29], v[78:79], 0, v[28:29]
	flat_load_dwordx4 v[28:31], v[28:29] nt
	s_waitcnt vmcnt(0) lgkmcnt(0)
	ds_write_b128 v116, v[28:31] offset:39168
	v_lshl_add_u64 v[28:29], v[32:33], 0, v[82:83]
	v_lshlrev_b64 v[28:29], 8, v[28:29]
	v_lshl_add_u64 v[28:29], v[78:79], 0, v[28:29]
	flat_load_dwordx4 v[28:31], v[28:29] nt
.LBB0_448:
	s_or_b64 exec, exec, s[8:9]
	s_waitcnt vmcnt(0) lgkmcnt(0)
	ds_write_b128 v100, v[28:31] offset:39168
	s_and_saveexec_b64 s[4:5], s[6:7]
	s_xor_b64 s[4:5], exec, s[4:5]
	ds_write_b128 v117, v[120:123] offset:39168
	s_or_saveexec_b64 s[4:5], s[4:5]
	v_mov_b32_e32 v28, 0
	v_mov_b32_e32 v29, 0
	v_mov_b32_e32 v30, 0
	v_mov_b32_e32 v31, 0
	s_xor_b64 exec, exec, s[4:5]
	s_cbranch_execz .LBB0_452
	v_lshl_add_u64 v[28:29], v[32:33], 0, v[84:85]
	v_lshlrev_b64 v[28:29], 8, v[28:29]
	v_lshl_add_u64 v[28:29], v[78:79], 0, v[28:29]
	flat_load_dwordx4 v[28:31], v[28:29] nt
	v_lshl_add_u64 v[32:33], v[32:33], 0, v[86:87]
	v_lshlrev_b64 v[32:33], 8, v[32:33]
	s_waitcnt vmcnt(0) lgkmcnt(0)
	ds_write_b128 v117, v[28:31] offset:39168
	v_lshl_add_u64 v[28:29], v[78:79], 0, v[32:33]
	flat_load_dwordx4 v[28:31], v[28:29] nt

; __device__ __forceinline__ float lg2_of(int h) {
;     const double x = 1.0 / (double)(32 << h);
;     const double sser = x * (1.0 + x * (0.5 + x * (1.0 / 3 + x * (0.25 + x * (0.2 + x * (1.0 / 6 + x * (1.0 / 7)))))));
;     return (float)(-sser * 1.4426950408889634);
; }
; __global__ void __launch_bounds__(512, 2) fwd_megakernel(Args a) {
;     ...
;     if (PH(8)) { LANEVARS; GETWS; float* LST = WSF(OFF_L); for (int v = bid * 512 + tid; v < 16 * 8192; v += G * 512) {
;         const int bh = v >> 13, e4 = v & 8191; const float lgh = lg2_of(bh & 7); const float g8 = __builtin_amdgcn_exp2f(1024.f * lgh);
;         f32x4 carry = (f32x4){0.f, 0.f, 0.f, 0.f};
;         for (int g = 0; g < 16; ++g) { f32x4* p = (f32x4*)(LST + (size_t)(bh * 16 + g) * 32768) + e4; f32x4 t = carry; if (g < 15) { const f32x4 cur = *p; carry = carry * g8 + cur; } *p = t; }
;     } }
.LBB0_500:
	v_ashrrev_i32_e32 v5, 13, v18
	v_and_b32_e32 v14, 0x1fff, v18
	v_lshlrev_b32_e32 v16, 4, v5
	v_mov_b32_e32 v15, v4
	v_lshlrev_b32_e32 v14, 4, v14
	v_ashrrev_i32_e32 v17, 31, v16
	v_lshl_add_u64 v[14:15], s[2:3], 0, v[14:15]
	v_or_b32_e32 v20, 1, v16
	v_or_b32_e32 v22, 2, v16
	v_lshlrev_b64 v[48:49], 17, v[16:17]
	v_ashrrev_i32_e32 v21, 31, v20
	v_ashrrev_i32_e32 v23, 31, v22
	v_lshl_add_u64 v[80:81], v[14:15], 0, v[48:49]
	v_lshlrev_b64 v[48:49], 17, v[20:21]
	v_lshlrev_b64 v[50:51], 17, v[22:23]
	flat_load_dwordx4 v[20:23], v[80:81] nt
	v_or_b32_e32 v24, 3, v16
	v_or_b32_e32 v26, 4, v16
	v_or_b32_e32 v28, 5, v16
	v_or_b32_e32 v30, 6, v16
	v_or_b32_e32 v32, 7, v16
	v_or_b32_e32 v34, 8, v16
	v_or_b32_e32 v36, 9, v16
	v_or_b32_e32 v38, 10, v16
	v_or_b32_e32 v40, 11, v16
	v_or_b32_e32 v42, 12, v16
	v_or_b32_e32 v44, 13, v16
	v_or_b32_e32 v46, 14, v16
	v_ashrrev_i32_e32 v25, 31, v24
	v_ashrrev_i32_e32 v27, 31, v26
	v_ashrrev_i32_e32 v29, 31, v28
	v_ashrrev_i32_e32 v31, 31, v30
	v_ashrrev_i32_e32 v33, 31, v32
	v_ashrrev_i32_e32 v35, 31, v34
	v_ashrrev_i32_e32 v37, 31, v36
	v_ashrrev_i32_e32 v39, 31, v38
	v_ashrrev_i32_e32 v41, 31, v40
	v_ashrrev_i32_e32 v43, 31, v42
	v_ashrrev_i32_e32 v45, 31, v44
	v_ashrrev_i32_e32 v47, 31, v46
	v_lshlrev_b64 v[24:25], 17, v[24:25]
	v_lshlrev_b64 v[26:27], 17, v[26:27]
	v_lshlrev_b64 v[28:29], 17, v[28:29]
	v_lshlrev_b64 v[30:31], 17, v[30:31]
	v_lshlrev_b64 v[32:33], 17, v[32:33]
	v_lshlrev_b64 v[34:35], 17, v[34:35]
	v_lshlrev_b64 v[36:37], 17, v[36:37]
	v_lshlrev_b64 v[38:39], 17, v[38:39]
	v_lshlrev_b64 v[40:41], 17, v[40:41]
	v_lshlrev_b64 v[42:43], 17, v[42:43]
	v_lshlrev_b64 v[44:45], 17, v[44:45]
	v_lshlrev_b64 v[46:47], 17, v[46:47]
	v_lshl_add_u64 v[82:83], v[14:15], 0, v[48:49]
	v_lshl_add_u64 v[84:85], v[14:15], 0, v[50:51]
	v_lshl_add_u64 v[86:87], v[14:15], 0, v[24:25]
	v_lshl_add_u64 v[88:89], v[14:15], 0, v[26:27]
	v_lshl_add_u64 v[90:91], v[14:15], 0, v[28:29]
	v_lshl_add_u64 v[92:93], v[14:15], 0, v[30:31]
	v_lshl_add_u64 v[94:95], v[14:15], 0, v[32:33]
	v_lshl_add_u64 v[96:97], v[14:15], 0, v[34:35]
	v_lshl_add_u64 v[98:99], v[14:15], 0, v[36:37]
	v_lshl_add_u64 v[100:101], v[14:15], 0, v[38:39]
	v_lshl_add_u64 v[102:103], v[14:15], 0, v[40:41]
	v_lshl_add_u64 v[104:105], v[14:15], 0, v[42:43]
	v_lshl_add_u64 v[106:107], v[14:15], 0, v[44:45]
	v_lshl_add_u64 v[108:109], v[14:15], 0, v[46:47]
	flat_load_dwordx4 v[24:27], v[82:83] nt
	flat_load_dwordx4 v[28:31], v[84:85] nt
	flat_load_dwordx4 v[32:35], v[86:87] nt
	flat_load_dwordx4 v[36:39], v[88:89] nt
	flat_load_dwordx4 v[40:43], v[90:91] nt
	flat_load_dwordx4 v[44:47], v[92:93] nt
	flat_load_dwordx4 v[48:51], v[94:95] nt
	flat_load_dwordx4 v[52:55], v[96:97] nt
	flat_load_dwordx4 v[56:59], v[98:99] nt
	flat_load_dwordx4 v[60:63], v[100:101] nt
	flat_load_dwordx4 v[64:67], v[102:103] nt
	flat_load_dwordx4 v[68:71], v[104:105] nt
	flat_load_dwordx4 v[72:75], v[106:107] nt
	flat_load_dwordx4 v[76:79], v[108:109] nt
	v_lshlrev_b32_e32 v5, 20, v5
	v_and_b32_e32 v5, 0x700000, v5
	v_or_b32_e32 v16, 15, v16
	v_add_u32_e32 v5, 0x500000, v5
	v_ashrrev_i32_e32 v17, 31, v16
	v_xor_b32_e32 v5, 0x3ff00000, v5
	v_lshlrev_b64 v[16:17], 17, v[16:17]
	v_fma_f64 v[110:111], s[6:7], v[4:5], v[6:7]
	v_lshl_add_u64 v[112:113], v[14:15], 0, v[16:17]
	v_fma_f64 v[14:15], v[4:5], v[110:111], v[8:9]
	v_fma_f64 v[14:15], v[4:5], v[14:15], v[10:11]
	v_fma_f64 v[14:15], v[4:5], v[14:15], v[12:13]
	v_fma_f64 v[14:15], v[4:5], v[14:15], 0.5
	v_fma_f64 v[14:15], v[4:5], v[14:15], 1.0
	v_mul_f64 v[14:15], v[4:5], v[14:15]
	v_mul_f64 v[14:15], v[14:15], s[8:9]
	v_cvt_f32_f64_e32 v5, v[14:15]
	v_mul_f32_e32 v5, 0xc4800000, v5
	flat_store_dwordx4 v[80:81], v[0:3]
	v_exp_f32_e32 v80, v5
	v_add_u32_e32 v18, s10, v18
	v_cmp_lt_i32_e32 vcc, s11, v18
	s_or_b64 s[4:5], vcc, s[4:5]
	s_waitcnt vmcnt(0) lgkmcnt(0)
	v_pk_fma_f32 v[16:17], v[80:81], 0, v[22:23] op_sel_hi:[0,0,1]
	v_pk_fma_f32 v[14:15], v[80:81], 0, v[20:21] op_sel_hi:[0,0,1]
	flat_store_dwordx4 v[82:83], v[14:17]
	v_pk_fma_f32 v[22:23], v[80:81], v[16:17], v[26:27] op_sel_hi:[0,1,1]
	v_pk_fma_f32 v[20:21], v[80:81], v[14:15], v[24:25] op_sel_hi:[0,1,1]
	v_pk_fma_f32 v[16:17], v[80:81], v[22:23], v[30:31] op_sel_hi:[0,1,1]
	v_pk_fma_f32 v[14:15], v[80:81], v[20:21], v[28:29] op_sel_hi:[0,1,1]
	flat_store_dwordx4 v[84:85], v[20:23]
	flat_store_dwordx4 v[86:87], v[14:17]
	s_nop 0
	v_pk_fma_f32 v[22:23], v[80:81], v[16:17], v[34:35] op_sel_hi:[0,1,1]
	v_pk_fma_f32 v[20:21], v[80:81], v[14:15], v[32:33] op_sel_hi:[0,1,1]
	v_pk_fma_f32 v[16:17], v[80:81], v[22:23], v[38:39] op_sel_hi:[0,1,1]
	v_pk_fma_f32 v[14:15], v[80:81], v[20:21], v[36:37] op_sel_hi:[0,1,1]
	flat_store_dwordx4 v[88:89], v[20:23]
	flat_store_dwordx4 v[90:91], v[14:17]
	s_nop 0
	v_pk_fma_f32 v[22:23], v[80:81], v[16:17], v[42:43] op_sel_hi:[0,1,1]
	v_pk_fma_f32 v[20:21], v[80:81], v[14:15], v[40:41] op_sel_hi:[0,1,1]
	v_pk_fma_f32 v[16:17], v[80:81], v[22:23], v[46:47] op_sel_hi:[0,1,1]
	v_pk_fma_f32 v[14:15], v[80:81], v[20:21], v[44:45] op_sel_hi:[0,1,1]
	flat_store_dwordx4 v[92:93], v[20:23]
	flat_store_dwordx4 v[94:95], v[14:17]
	s_nop 0
	v_pk_fma_f32 v[22:23], v[80:81], v[16:17], v[50:51] op_sel_hi:[0,1,1]
	v_pk_fma_f32 v[20:21], v[80:81], v[14:15], v[48:49] op_sel_hi:[0,1,1]
	v_pk_fma_f32 v[16:17], v[80:81], v[22:23], v[54:55] op_sel_hi:[0,1,1]
	v_pk_fma_f32 v[14:15], v[80:81], v[20:21], v[52:53] op_sel_hi:[0,1,1]
	flat_store_dwordx4 v[96:97], v[20:23]
	flat_store_dwordx4 v[98:99], v[14:17]
	s_nop 0
	v_pk_fma_f32 v[20:21], v[80:81], v[14:15], v[56:57] op_sel_hi:[0,1,1]
	v_pk_fma_f32 v[22:23], v[80:81], v[16:17], v[58:59] op_sel_hi:[0,1,1]
	v_pk_fma_f32 v[14:15], v[80:81], v[20:21], v[60:61] op_sel_hi:[0,1,1]
	v_pk_fma_f32 v[16:17], v[80:81], v[22:23], v[62:63] op_sel_hi:[0,1,1]
	flat_store_dwordx4 v[100:101], v[20:23]
	flat_store_dwordx4 v[102:103], v[14:17]
	s_nop 0
	v_pk_fma_f32 v[20:21], v[80:81], v[14:15], v[64:65] op_sel_hi:[0,1,1]
	v_pk_fma_f32 v[22:23], v[80:81], v[16:17], v[66:67] op_sel_hi:[0,1,1]
	v_pk_fma_f32 v[14:15], v[80:81], v[20:21], v[68:69] op_sel_hi:[0,1,1]
	v_pk_fma_f32 v[16:17], v[80:81], v[22:23], v[70:71] op_sel_hi:[0,1,1]
	flat_store_dwordx4 v[104:105], v[20:23]
	flat_store_dwordx4 v[106:107], v[14:17]
	s_nop 0
	v_pk_fma_f32 v[20:21], v[80:81], v[14:15], v[72:73] op_sel_hi:[0,1,1]
	v_pk_fma_f32 v[22:23], v[80:81], v[16:17], v[74:75] op_sel_hi:[0,1,1]
	v_pk_fma_f32 v[14:15], v[80:81], v[20:21], v[76:77] op_sel_hi:[0,1,1]
	v_pk_fma_f32 v[16:17], v[80:81], v[22:23], v[78:79] op_sel_hi:[0,1,1]
	flat_store_dwordx4 v[108:109], v[20:23]
	flat_store_dwordx4 v[112:113], v[14:17]
	s_andn2_b64 exec, exec, s[4:5]
	s_cbranch_execnz .LBB0_500

; __device__ __forceinline__ float shx(float v, int o, int lane) { return __int_as_float(__builtin_amdgcn_ds_bpermute((lane ^ o) << 2, __float_as_int(v))); }
; __device__ __forceinline__ void ret_out_item(ldsp lds, int item, const bf16_t* rq, const bf16_t* rk, const bf16_t* vT, const bf16_t* kdT, bf16_t* rg, const float* L,
;                                              const float* gn_g, float lg, int tid_, int w, int fr_, int fq_) {
;     const int b = item >> 7, h = (item >> 4) & 7, g = item & 15;
;     const float gC = __builtin_amdgcn_exp2f(128.f * lg);
;     f32x4 st[2][8];
;     const float* Lp = L + (size_t)item * 32768;
; #pragma unroll
;     for (int mt = 0; mt < 2; ++mt)
; #pragma unroll
;         for (int nt = 0; nt < 8; ++nt) st[mt][nt] = *(const f32x4*)(Lp + (32 * w + 16 * mt + fr_) * 128 + 16 * nt + 4 * fq_);
;     const int i_ = 16 * w + fr_;
;     u32x4 qv[4], kv[4];
;     {
;         const size_t r0 = (size_t)b * SEQ + g * 1024;
; #pragma unroll
;         for (int ii = 0; ii < 4; ++ii) { const int idx = tid_ + 512 * ii; qv[ii] = *(const u32x4*)(rq + (r0 + (idx >> 4)) * 1024 + h * 128 + (idx & 15) * 8); kv[ii] = *(const u32x4*)(rk + (r0 + (idx >> 4)) * 1024 + h * 128 + (idx & 15) * 8); }
;     }
;     ...
;         float s = 0.f;
; #pragma unroll
;         for (int nt = 0; nt < 16; ++nt) s += (o[nt][0] + o[nt][1]) + (o[nt][2] + o[nt][3]);
;         const int ln = fr + 16 * fq;
;         s += shx(s, 16, ln); s += shx(s, 32, ln);
.LBB0_548:
	s_bfe_u32 s4, s58, 0x30004
	s_lshl_b32 s0, s4, 20
	s_add_i32 s0, s0, 0x500000
	s_ashr_i32 s59, s58, 31
	s_xor_b32 s61, s0, 0x3ff00000
	s_lshl_b64 s[0:1], s[58:59], 17
	v_lshl_add_u64 v[32:33], v[162:163], 0, s[0:1]
	s_ashr_i32 s0, s58, 7
	s_ashr_i32 s1, s0, 31
	s_lshl_b64 s[62:63], s[0:1], 14
	s_lshl_b32 s0, s58, 10
	s_and_b32 s0, s0, 0x3c00
	s_or_b32 s62, s62, s0
	s_lshl_b32 s0, s4, 8
	v_add_co_u32_e32 v64, vcc, s88, v32
	s_add_u32 s64, s78, s0
	s_nop 0
	v_addc_co_u32_e32 v65, vcc, 0, v33, vcc
	s_addc_u32 s65, s79, 0
	flat_load_dwordx4 v[0:3], v[32:33] nt
	flat_load_dwordx4 v[4:7], v[32:33] offset:64 nt
	flat_load_dwordx4 v[8:11], v[32:33] offset:128 nt
	flat_load_dwordx4 v[12:15], v[32:33] offset:192 nt
	flat_load_dwordx4 v[16:19], v[32:33] offset:256 nt
	flat_load_dwordx4 v[20:23], v[32:33] offset:320 nt
	flat_load_dwordx4 v[24:27], v[32:33] offset:384 nt
	flat_load_dwordx4 v[28:31], v[32:33] offset:448 nt
	s_nop 0
	flat_load_dwordx4 v[32:35], v[64:65] nt
	flat_load_dwordx4 v[36:39], v[64:65] offset:64 nt
	flat_load_dwordx4 v[40:43], v[64:65] offset:128 nt
	flat_load_dwordx4 v[44:47], v[64:65] offset:192 nt
	flat_load_dwordx4 v[48:51], v[64:65] offset:256 nt
	flat_load_dwordx4 v[52:55], v[64:65] offset:320 nt
	flat_load_dwordx4 v[56:59], v[64:65] offset:384 nt
	flat_load_dwordx4 v[60:63], v[64:65] offset:448 nt
	s_add_u32 s66, s80, s0
	v_lshl_add_u64 v[64:65], s[62:63], 0, v[164:165]
	v_lshl_add_u64 v[88:89], s[64:65], 0, v[182:183]
	s_addc_u32 s67, s81, 0
	v_lshlrev_b64 v[64:65], 11, v[64:65]
	v_lshl_add_u64 v[90:91], s[66:67], 0, v[182:183]
	v_lshl_add_u64 v[72:73], v[88:89], 0, v[64:65]
	v_lshl_add_u64 v[74:75], v[90:91], 0, v[64:65]
	flat_load_dwordx4 v[64:67], v[72:73] nt
	flat_load_dwordx4 v[68:71], v[74:75] nt
	v_lshl_add_u64 v[72:73], s[62:63], 0, v[166:167]
	v_lshlrev_b64 v[72:73], 11, v[72:73]
	v_lshl_add_u64 v[80:81], v[88:89], 0, v[72:73]
	v_lshl_add_u64 v[82:83], v[90:91], 0, v[72:73]
	flat_load_dwordx4 v[72:75], v[80:81] nt
	flat_load_dwordx4 v[76:79], v[82:83] nt
	v_lshl_add_u64 v[80:81], s[62:63], 0, v[168:169]
	v_lshlrev_b64 v[80:81], 11, v[80:81]
	v_lshl_add_u64 v[92:93], v[88:89], 0, v[80:81]
	v_lshl_add_u64 v[94:95], v[90:91], 0, v[80:81]
	flat_load_dwordx4 v[80:83], v[92:93] nt
	flat_load_dwordx4 v[84:87], v[94:95] nt
	v_lshl_add_u64 v[92:93], s[62:63], 0, v[170:171]
	v_lshlrev_b64 v[92:93], 11, v[92:93]
	v_lshl_add_u64 v[88:89], v[88:89], 0, v[92:93]
	v_lshl_add_u64 v[92:93], v[90:91], 0, v[92:93]
	flat_load_dwordx4 v[88:91], v[88:89] nt
	s_nop 0
	flat_load_dwordx4 v[92:95], v[92:93] nt
	s_mov_b32 s60, 0
	v_fma_f64 v[96:97], s[60:61], v[174:175], v[172:173]
	v_mov_b32_e32 v98, 0
	v_fma_f64 v[96:97], s[60:61], v[96:97], v[176:177]
	v_mov_b32_e32 v99, 0x3fd00000
	v_fma_f64 v[96:97], s[60:61], v[96:97], v[98:99]
	v_fma_f64 v[96:97], s[60:61], v[96:97], v[180:181]
	v_fma_f64 v[96:97], s[60:61], v[96:97], 0.5
	v_fma_f64 v[96:97], s[60:61], v[96:97], 1.0
	v_mul_f64 v[96:97], s[60:61], v[96:97]
	v_mul_f64 v[96:97], v[96:97], s[2:3]
	v_cvt_f32_f64_e32 v224, v[96:97]
	s_lshl_b32 s0, s4, 16
	v_mul_f32_e32 v96, 0x43000000, v224
	s_add_u32 s59, s82, s0
	v_exp_f32_e32 v184, v96
	s_addc_u32 s61, s83, 0
	s_lshl_b32 s0, s4, 9
	s_add_u32 s68, s84, s0
	s_addc_u32 s69, s85, 0
	s_lshl_b32 s0, s4, 10
	s_add_u32 s70, s76, s0
	v_mov_b32_e32 v186, v184
	v_mov_b32_e32 v187, v184
	s_addc_u32 s71, s77, 0
	s_branch .LBB0_550
.LBB0_549:
	v_mov_b32_e32 v190, v157
	v_mov_b32_e32 v191, v158
	v_mov_b32_e32 v192, v156
	v_mov_b32_e32 v193, v159
	v_pk_add_f32 v[190:191], v[190:191], v[192:193]
	v_mov_b32_e32 v192, v153
	v_mov_b32_e32 v193, v154
	v_mov_b32_e32 v194, v152
	v_mov_b32_e32 v195, v155
	v_pk_add_f32 v[192:193], v[192:193], v[194:195]
	v_add_f32_e32 v160, v190, v191
	v_pk_add_f32 v[192:193], v[192:193], v[192:193] op_sel:[0,1] op_sel_hi:[1,0]
	v_add_f32_e32 v190, 0, v160
	v_add_f32_e32 v194, v148, v149
	v_add_f32_e32 v196, v150, v151
	v_mov_b32_e32 v191, v144
	v_mov_b32_e32 v193, v145
	v_mov_b32_e32 v195, v146
	v_mov_b32_e32 v197, v147
	v_pk_add_f32 v[190:191], v[190:191], v[192:193]
	v_pk_add_f32 v[192:193], v[194:195], v[196:197]
	v_mov_b32_e32 v194, v140
	v_pk_add_f32 v[190:191], v[190:191], v[192:193]
	v_mov_b32_e32 v192, v141
	v_mov_b32_e32 v193, v142
	v_mov_b32_e32 v195, v143
	v_pk_add_f32 v[192:193], v[192:193], v[194:195]
	v_pk_add_f32 v[190:191], v[190:191], v[190:191] op_sel:[0,1] op_sel_hi:[1,0]
	v_pk_add_f32 v[192:193], v[192:193], v[192:193] op_sel:[0,1] op_sel_hi:[1,0]
	v_add_f32_e32 v194, v136, v137
	v_add_f32_e32 v196, v138, v139
	v_mov_b32_e32 v191, v132
	v_mov_b32_e32 v193, v133
	v_mov_b32_e32 v195, v134
	v_mov_b32_e32 v197, v135
	v_pk_add_f32 v[190:191], v[190:191], v[192:193]
	v_pk_add_f32 v[192:193], v[194:195], v[196:197]
	v_mov_b32_e32 v194, v128
	v_pk_add_f32 v[190:191], v[190:191], v[192:193]
	v_mov_b32_e32 v192, v129
	v_mov_b32_e32 v193, v130
	v_mov_b32_e32 v195, v131
	v_pk_add_f32 v[192:193], v[192:193], v[194:195]
	v_pk_add_f32 v[190:191], v[190:191], v[190:191] op_sel:[0,1] op_sel_hi:[1,0]
	v_pk_add_f32 v[192:193], v[192:193], v[192:193] op_sel:[0,1] op_sel_hi:[1,0]
	v_add_f32_e32 v194, v124, v125
	v_add_f32_e32 v196, v126, v127
	v_mov_b32_e32 v191, v120
	v_mov_b32_e32 v193, v121
	v_mov_b32_e32 v195, v122
	v_mov_b32_e32 v197, v123
	v_pk_add_f32 v[190:191], v[190:191], v[192:193]
	v_pk_add_f32 v[192:193], v[194:195], v[196:197]
	v_mov_b32_e32 v194, v116
	v_pk_add_f32 v[190:191], v[190:191], v[192:193]
	v_mov_b32_e32 v192, v117
	v_mov_b32_e32 v193, v118
	v_mov_b32_e32 v195, v119
	v_pk_add_f32 v[192:193], v[192:193], v[194:195]
	v_pk_add_f32 v[190:191], v[190:191], v[190:191] op_sel:[0,1] op_sel_hi:[1,0]
	v_pk_add_f32 v[192:193], v[192:193], v[192:193] op_sel:[0,1] op_sel_hi:[1,0]
	v_add_f32_e32 v194, v112, v113
	v_add_f32_e32 v196, v114, v115
	v_mov_b32_e32 v191, v108
	v_mov_b32_e32 v193, v109
	v_mov_b32_e32 v195, v110
	v_mov_b32_e32 v197, v111
	v_pk_add_f32 v[190:191], v[190:191], v[192:193]
	v_pk_add_f32 v[192:193], v[194:195], v[196:197]
	v_mov_b32_e32 v194, v104
	v_pk_add_f32 v[190:191], v[190:191], v[192:193]
	v_mov_b32_e32 v192, v105
	v_mov_b32_e32 v193, v106
	v_mov_b32_e32 v195, v107
	v_pk_add_f32 v[192:193], v[192:193], v[194:195]
	v_pk_add_f32 v[190:191], v[190:191], v[190:191] op_sel:[0,1] op_sel_hi:[1,0]
	v_pk_add_f32 v[192:193], v[192:193], v[192:193] op_sel:[0,1] op_sel_hi:[1,0]
	v_add_f32_e32 v194, v100, v101
	v_add_f32_e32 v196, v102, v103
	v_mov_b32_e32 v191, v96
	v_mov_b32_e32 v193, v97
	v_mov_b32_e32 v195, v98
	v_mov_b32_e32 v197, v99
	v_pk_add_f32 v[190:191], v[190:191], v[192:193]
	v_pk_add_f32 v[192:193], v[194:195], v[196:197]
	v_add_lshl_u32 v178, v226, v225, 2
	v_pk_add_f32 v[190:191], v[190:191], v[192:193]
	v_xor_b32_e32 v179, 64, v178
	v_add_f32_e32 v160, v190, v191
	ds_bpermute_b32 v185, v179, v160
	v_xor_b32_e32 v178, 0x80, v178
	s_add_i32 s60, s60, 1
	s_cmp_lg_u32 s60, 8
	s_waitcnt lgkmcnt(0)
; __device__ __forceinline__ float shx(float v, int o, int lane) { return __int_as_float(__builtin_amdgcn_ds_bpermute((lane ^ o) << 2, __float_as_int(v))); }
; __device__ __forceinline__ void ret_out_item(ldsp lds, int item, const bf16_t* rq, const bf16_t* rk, const bf16_t* vT, const bf16_t* kdT, bf16_t* rg, const float* L,
;                                              const float* gn_g, float lg, int tid_, int w, int fr_, int fq_) {
;     ...
;         s += shx(s, 16, ln); s += shx(s, 32, ln);
;         const float mean = s * (1.f / 256.f); float q = 0.f;
; #pragma unroll
;         for (int nt = 0; nt < 16; ++nt) { o[nt] = o[nt] - mean; q += (o[nt][0] * o[nt][0] + o[nt][1] * o[nt][1]) + (o[nt][2] * o[nt][2] + o[nt][3] * o[nt][3]); }
;         q += shx(q, 16, ln); q += shx(q, 32, ln);
	v_add_f32_e32 v160, v160, v185
	ds_bpermute_b32 v185, v178, v160
	s_waitcnt lgkmcnt(0)
	v_add_f32_e32 v185, v160, v185
	v_fmamk_f32 v157, v185, 0xbb800000, v157
	v_fmamk_f32 v156, v185, 0xbb800000, v156
	v_fmamk_f32 v159, v185, 0xbb800000, v159
	v_fmac_f32_e32 v158, 0xbb800000, v185
	v_pk_mul_f32 v[190:191], v[158:159], v[158:159]
	v_pk_mul_f32 v[192:193], v[156:157], v[156:157]
	v_fmamk_f32 v153, v185, 0xbb800000, v153
	v_pk_mov_b32 v[194:195], v[192:193], v[190:191] op_sel:[1,0]
	v_mov_b32_e32 v193, v191
	v_fmamk_f32 v152, v185, 0xbb800000, v152
	v_fmamk_f32 v155, v185, 0xbb800000, v155
	v_fmac_f32_e32 v154, 0xbb800000, v185
	v_pk_add_f32 v[190:191], v[194:195], v[192:193]
	v_pk_mul_f32 v[192:193], v[154:155], v[154:155]
	v_pk_mul_f32 v[194:195], v[152:153], v[152:153]
	v_fmamk_f32 v148, v185, 0xbb800000, v148
	v_pk_mov_b32 v[196:197], v[194:195], v[192:193] op_sel:[1,0]
	v_mov_b32_e32 v195, v193
	v_fmamk_f32 v149, v185, 0xbb800000, v149
	v_fmac_f32_e32 v150, 0xbb800000, v185
	v_mul_f32_e32 v160, v148, v148
	v_pk_add_f32 v[192:193], v[196:197], v[194:195]
	v_fmamk_f32 v151, v185, 0xbb800000, v151
	v_pk_fma_f32 v[194:195], v[148:149], v[148:149], v[160:161] op_sel_hi:[1,1,0]
	v_mul_f32_e32 v160, v150, v150
	v_pk_add_f32 v[190:191], v[190:191], v[190:191] op_sel_hi:[0,1]
	v_pk_add_f32 v[192:193], v[192:193], v[192:193] op_sel_hi:[0,1]
	v_pk_fma_f32 v[196:197], v[150:151], v[150:151], v[160:161] op_sel_hi:[1,1,0]
	v_fmamk_f32 v160, v185, 0xbb800000, v147
	v_fmamk_f32 v202, v185, 0xbb800000, v146
	v_fmamk_f32 v145, v185, 0xbb800000, v145
	v_fmac_f32_e32 v144, 0xbb800000, v185
	v_mul_f32_e32 v194, v144, v144
	v_mul_f32_e32 v196, v145, v145
	v_mul_f32_e32 v190, v202, v202
	v_mul_f32_e32 v192, v160, v160
	v_pk_add_f32 v[146:147], v[194:195], v[196:197]
	v_pk_add_f32 v[190:191], v[190:191], v[192:193]
	v_fmamk_f32 v141, v185, 0xbb800000, v141
	v_pk_add_f32 v[146:147], v[146:147], v[190:191]
	v_fmamk_f32 v140, v185, 0xbb800000, v140
	v_fmamk_f32 v143, v185, 0xbb800000, v143
	v_fmac_f32_e32 v142, 0xbb800000, v185
	v_pk_add_f32 v[146:147], v[146:147], v[146:147] op_sel_hi:[0,1]
	v_pk_mul_f32 v[190:191], v[142:143], v[142:143]
	v_pk_mul_f32 v[192:193], v[140:141], v[140:141]
	v_fmamk_f32 v136, v185, 0xbb800000, v136
	v_pk_mov_b32 v[194:195], v[192:193], v[190:191] op_sel:[1,0]
	v_mov_b32_e32 v193, v191
	v_fmamk_f32 v137, v185, 0xbb800000, v137
	v_fmac_f32_e32 v138, 0xbb800000, v185
	v_mul_f32_e32 v146, v136, v136
	v_pk_add_f32 v[190:191], v[194:195], v[192:193]
	v_fmamk_f32 v139, v185, 0xbb800000, v139
	v_pk_fma_f32 v[192:193], v[136:137], v[136:137], v[146:147] op_sel_hi:[1,1,0]
	v_mul_f32_e32 v146, v138, v138
	v_pk_add_f32 v[190:191], v[190:191], v[190:191] op_sel_hi:[0,1]
	v_pk_fma_f32 v[194:195], v[138:139], v[138:139], v[146:147] op_sel_hi:[1,1,0]
	v_fmamk_f32 v196, v185, 0xbb800000, v135
	v_fmamk_f32 v197, v185, 0xbb800000, v134
	v_fmamk_f32 v133, v185, 0xbb800000, v133
	v_fmac_f32_e32 v132, 0xbb800000, v185
	v_mul_f32_e32 v192, v132, v132
	v_mul_f32_e32 v194, v133, v133
	v_mul_f32_e32 v190, v197, v197
	v_mul_f32_e32 v146, v196, v196
	v_pk_add_f32 v[134:135], v[192:193], v[194:195]
	v_pk_add_f32 v[146:147], v[190:191], v[146:147]
	v_fmamk_f32 v129, v185, 0xbb800000, v129
	v_pk_add_f32 v[134:135], v[134:135], v[146:147]
	v_fmamk_f32 v128, v185, 0xbb800000, v128
	v_fmamk_f32 v131, v185, 0xbb800000, v131
	v_fmac_f32_e32 v130, 0xbb800000, v185
	v_pk_add_f32 v[134:135], v[134:135], v[134:135] op_sel_hi:[0,1]
	v_pk_mul_f32 v[146:147], v[130:131], v[130:131]
	v_pk_mul_f32 v[190:191], v[128:129], v[128:129]
	v_fmamk_f32 v124, v185, 0xbb800000, v124
	v_pk_mov_b32 v[192:193], v[190:191], v[146:147] op_sel:[1,0]
	v_mov_b32_e32 v191, v147
	v_fmamk_f32 v125, v185, 0xbb800000, v125
	v_fmac_f32_e32 v126, 0xbb800000, v185
	v_mul_f32_e32 v134, v124, v124
	v_pk_add_f32 v[146:147], v[192:193], v[190:191]
	v_fmamk_f32 v127, v185, 0xbb800000, v127
	v_pk_fma_f32 v[190:191], v[124:125], v[124:125], v[134:135] op_sel_hi:[1,1,0]
	v_mul_f32_e32 v134, v126, v126
	v_pk_add_f32 v[146:147], v[146:147], v[146:147] op_sel_hi:[0,1]
	v_pk_fma_f32 v[192:193], v[126:127], v[126:127], v[134:135] op_sel_hi:[1,1,0]
	v_fmamk_f32 v203, v185, 0xbb800000, v123
	v_fmamk_f32 v225, v185, 0xbb800000, v122
	v_fmamk_f32 v226, v185, 0xbb800000, v121
	v_fmac_f32_e32 v120, 0xbb800000, v185
	v_mul_f32_e32 v190, v120, v120
	v_mul_f32_e32 v192, v226, v226
	v_mul_f32_e32 v146, v225, v225
	v_mul_f32_e32 v134, v203, v203
	v_pk_add_f32 v[122:123], v[190:191], v[192:193]
	v_pk_add_f32 v[134:135], v[146:147], v[134:135]
	v_fmamk_f32 v117, v185, 0xbb800000, v117
	v_pk_add_f32 v[122:123], v[122:123], v[134:135]
	v_fmamk_f32 v116, v185, 0xbb800000, v116
	v_fmamk_f32 v119, v185, 0xbb800000, v119
	v_fmac_f32_e32 v118, 0xbb800000, v185
	v_pk_add_f32 v[134:135], v[122:123], v[122:123] op_sel_hi:[0,1]
	v_pk_mul_f32 v[122:123], v[118:119], v[118:119]
	v_pk_mul_f32 v[146:147], v[116:117], v[116:117]
	v_fmamk_f32 v112, v185, 0xbb800000, v112
	v_pk_mov_b32 v[190:191], v[146:147], v[122:123] op_sel:[1,0]
	v_mov_b32_e32 v147, v123
	v_pk_add_f32 v[122:123], v[190:191], v[146:147]
	v_fmamk_f32 v113, v185, 0xbb800000, v113
	v_pk_add_f32 v[146:147], v[122:123], v[122:123] op_sel_hi:[0,1]
	v_fmac_f32_e32 v114, 0xbb800000, v185
	v_mul_f32_e32 v122, v112, v112
	v_fmamk_f32 v115, v185, 0xbb800000, v115
	v_pk_fma_f32 v[190:191], v[112:113], v[112:113], v[122:123] op_sel_hi:[1,1,0]
	v_mul_f32_e32 v122, v114, v114
	v_pk_fma_f32 v[192:193], v[114:115], v[114:115], v[122:123] op_sel_hi:[1,1,0]
	v_fmamk_f32 v121, v185, 0xbb800000, v111
	v_fmamk_f32 v122, v185, 0xbb800000, v110
	v_fmamk_f32 v109, v185, 0xbb800000, v109
; __device__ __forceinline__ unsigned cvt_pk_bf16(float lo, float hi) { unsigned r; asm volatile("s_nop 1\n\tv_cvt_pk_bf16_f32 %0, %1, %2" : "=v"(r) : "v"(lo), "v"(hi)); return r; }
; __device__ __forceinline__ float bf_lo(unsigned u) { return __uint_as_float(u << 16); }
; __device__ __forceinline__ float bf_hi(unsigned u) { return __uint_as_float(u & 0xffff0000u); }
; __device__ __forceinline__ float shx(float v, int o, int lane) { return __int_as_float(__builtin_amdgcn_ds_bpermute((lane ^ o) << 2, __float_as_int(v))); }
; __device__ __forceinline__ void ret_out_item(ldsp lds, int item, const bf16_t* rq, const bf16_t* rk, const bf16_t* vT, const bf16_t* kdT, bf16_t* rg, const float* L,
;                                              const float* gn_g, float lg, int tid_, int w, int fr_, int fq_) {
;     ...
;         for (int nt = 0; nt < 16; ++nt) { o[nt] = o[nt] - mean; q += (o[nt][0] * o[nt][0] + o[nt][1] * o[nt][1]) + (o[nt][2] * o[nt][2] + o[nt][3] * o[nt][3]); }
;         q += shx(q, 16, ln); q += shx(q, 32, ln);
;         const float rstd = 1.0f / sqrtf(q * (1.f / 256.f) + 1e-5f);
;         const float* gp = gn_g + h * 256 + 4 * fq;
; #pragma unroll
;         for (int nt = 0; nt < 16; ++nt) {
;             const f32x4 gg = *(const f32x4*)(gp + 16 * nt); const u32x2 sv = nt < 8 ? svr[nt] : *(const u32x2*)(rp + 16 * nt);
;             u32x2 wv; wv.x = cvt_pk_bf16(o[nt][0] * rstd * gg[0] * bf_lo(sv.x), o[nt][1] * rstd * gg[1] * bf_hi(sv.x));
;             wv.y = cvt_pk_bf16(o[nt][2] * rstd * gg[2] * bf_lo(sv.y), o[nt][3] * rstd * gg[3] * bf_hi(sv.y));
;             *(u32x2*)(rp + 16 * nt) = wv;
;         }
	v_fmac_f32_e32 v108, 0xbb800000, v185
	v_mul_f32_e32 v190, v108, v108
	v_mul_f32_e32 v192, v109, v109
	v_mul_f32_e32 v146, v122, v122
	v_mul_f32_e32 v134, v121, v121
	v_pk_add_f32 v[110:111], v[190:191], v[192:193]
	v_pk_add_f32 v[134:135], v[146:147], v[134:135]
	v_fmamk_f32 v105, v185, 0xbb800000, v105
	v_pk_add_f32 v[110:111], v[110:111], v[134:135]
	v_fmamk_f32 v104, v185, 0xbb800000, v104
	v_pk_add_f32 v[134:135], v[110:111], v[110:111] op_sel_hi:[0,1]
	v_lshl_add_u64 v[110:111], v[188:189], 2, s[70:71]
	flat_load_dwordx4 v[188:191], v[110:111] nt
	v_fmamk_f32 v107, v185, 0xbb800000, v107
	v_fmac_f32_e32 v106, 0xbb800000, v185
	v_pk_mul_f32 v[146:147], v[106:107], v[106:107]
	v_pk_mul_f32 v[192:193], v[104:105], v[104:105]
	v_fmamk_f32 v100, v185, 0xbb800000, v100
	v_pk_mov_b32 v[194:195], v[192:193], v[146:147] op_sel:[1,0]
	v_mov_b32_e32 v193, v147
	v_fmamk_f32 v101, v185, 0xbb800000, v101
	v_fmac_f32_e32 v102, 0xbb800000, v185
	v_mul_f32_e32 v134, v100, v100
	v_pk_add_f32 v[146:147], v[194:195], v[192:193]
	v_fmamk_f32 v103, v185, 0xbb800000, v103
	v_pk_fma_f32 v[192:193], v[100:101], v[100:101], v[134:135] op_sel_hi:[1,1,0]
	v_mul_f32_e32 v134, v102, v102
	v_pk_add_f32 v[146:147], v[146:147], v[146:147] op_sel_hi:[0,1]
	v_pk_fma_f32 v[194:195], v[102:103], v[102:103], v[134:135] op_sel_hi:[1,1,0]
	v_fmamk_f32 v99, v185, 0xbb800000, v99
	v_fmamk_f32 v98, v185, 0xbb800000, v98
	v_fmamk_f32 v97, v185, 0xbb800000, v97
	v_fmac_f32_e32 v96, 0xbb800000, v185
	v_mul_f32_e32 v192, v96, v96
	v_mul_f32_e32 v194, v97, v97
	v_mul_f32_e32 v146, v98, v98
	v_mul_f32_e32 v134, v99, v99
	v_pk_add_f32 v[192:193], v[192:193], v[194:195]
	v_pk_add_f32 v[134:135], v[146:147], v[134:135]
	s_nop 0
	v_pk_add_f32 v[134:135], v[192:193], v[134:135]
	s_nop 0
	v_add_f32_e32 v123, v134, v135
	ds_bpermute_b32 v134, v179, v123
	s_waitcnt lgkmcnt(0)
	v_add_f32_e32 v123, v123, v134
	ds_bpermute_b32 v134, v178, v123
	s_waitcnt lgkmcnt(0)
	v_add_f32_e32 v123, v123, v134
	v_fmamk_f32 v123, v123, 0x3b800000, v222
	v_mul_f32_e32 v134, 0x4f800000, v123
	v_cmp_gt_f32_e32 vcc, s92, v123
	s_nop 1
	v_cndmask_b32_e32 v123, v123, v134, vcc
	v_sqrt_f32_e32 v134, v123
	s_nop 0
	v_add_u32_e32 v135, -1, v134
	v_fma_f32 v146, -v135, v134, v123
	v_cmp_ge_f32_e64 s[0:1], 0, v146
	v_add_u32_e32 v146, 1, v134
	s_nop 0
	v_cndmask_b32_e64 v135, v134, v135, s[0:1]
	v_fma_f32 v134, -v146, v134, v123
	v_cmp_lt_f32_e64 s[0:1], 0, v134
	s_nop 1
	v_cndmask_b32_e64 v134, v135, v146, s[0:1]
	v_mul_f32_e32 v135, 0x37800000, v134
	v_cndmask_b32_e32 v134, v134, v135, vcc
	v_cmp_class_f32_e32 vcc, v123, v223
	s_nop 1
	v_cndmask_b32_e32 v123, v134, v123, vcc
	v_div_scale_f32 v134, s[0:1], v123, v123, 1.0
	v_rcp_f32_e32 v135, v134
	s_nop 0
	v_fma_f32 v146, -v134, v135, 1.0
	v_fmac_f32_e32 v135, v146, v135
	v_div_scale_f32 v146, vcc, 1.0, v123, 1.0
	v_mul_f32_e32 v147, v146, v135
	v_fma_f32 v178, -v134, v147, v146
	v_fmac_f32_e32 v147, v178, v135
	v_fma_f32 v134, -v134, v147, v146
	v_div_fmas_f32 v134, v134, v135, v147
	v_div_fixup_f32 v123, v134, v123, 1.0
	v_mul_f32_e32 v134, v156, v123
	s_waitcnt vmcnt(0)
	v_mul_f32_e32 v134, v188, v134
	v_lshlrev_b32_e32 v135, 16, v216
	v_mul_f32_e32 v134, v134, v135
	v_mul_f32_e32 v135, v157, v123
	v_mul_f32_e32 v135, v189, v135
	v_and_b32_e32 v146, 0xffff0000, v216
	v_mul_f32_e32 v135, v135, v146
	s_nop 1
	v_cvt_pk_bf16_f32 v134, v134, v135
	v_mul_f32_e32 v135, v158, v123
	v_mul_f32_e32 v135, v190, v135
	v_lshlrev_b32_e32 v146, 16, v217
	v_mul_f32_e32 v135, v135, v146
	v_mul_f32_e32 v146, v159, v123
	v_mul_f32_e32 v146, v191, v146
	v_and_b32_e32 v147, 0xffff0000, v217
	v_mul_f32_e32 v146, v146, v147
	s_nop 1
	v_cvt_pk_bf16_f32 v135, v135, v146
	flat_store_dwordx2 v[198:199], v[134:135]
	flat_load_dwordx4 v[156:159], v[110:111] offset:64 nt
	v_mul_f32_e32 v134, v152, v123
	v_lshlrev_b32_e32 v135, 16, v214
	v_and_b32_e32 v146, 0xffff0000, v214
	v_and_b32_e32 v147, 0xffff0000, v215
	v_mul_f32_e32 v140, v140, v123
	v_mul_f32_e32 v141, v141, v123
	v_mul_f32_e32 v142, v142, v123
	v_mul_f32_e32 v143, v143, v123
	v_mul_f32_e32 v136, v136, v123
	v_mul_f32_e32 v137, v137, v123
	v_mul_f32_e32 v138, v138, v123
	v_mul_f32_e32 v139, v139, v123
	v_mul_f32_e32 v132, v132, v123
	v_mul_f32_e32 v133, v133, v123
	v_mul_f32_e32 v128, v128, v123
	v_mul_f32_e32 v129, v129, v123
	v_mul_f32_e32 v130, v130, v123
	v_mul_f32_e32 v131, v131, v123
	v_mul_f32_e32 v124, v124, v123
	v_mul_f32_e32 v125, v125, v123
	v_mul_f32_e32 v126, v126, v123
	v_mul_f32_e32 v127, v127, v123
	v_mul_f32_e32 v120, v120, v123
	v_mul_f32_e32 v116, v116, v123
	v_mul_f32_e32 v117, v117, v123
	v_mul_f32_e32 v118, v118, v123
	v_mul_f32_e32 v119, v119, v123
	v_mul_f32_e32 v112, v112, v123
	v_mul_f32_e32 v113, v113, v123
	v_mul_f32_e32 v114, v114, v123
	v_mul_f32_e32 v115, v115, v123
	v_mul_f32_e32 v108, v108, v123
	v_mul_f32_e32 v109, v109, v123
	v_mul_f32_e32 v104, v104, v123
	v_mul_f32_e32 v105, v105, v123
	v_mul_f32_e32 v106, v106, v123
	v_mul_f32_e32 v107, v107, v123
	v_mul_f32_e32 v100, v100, v123
	v_mul_f32_e32 v101, v101, v123
	v_mul_f32_e32 v102, v102, v123
	v_mul_f32_e32 v103, v103, v123
	v_mul_f32_e32 v96, v96, v123
	v_mul_f32_e32 v97, v97, v123
	v_mul_f32_e32 v98, v98, v123
	v_mul_f32_e32 v99, v99, v123
	s_waitcnt vmcnt(0) lgkmcnt(0)
; __device__ __forceinline__ unsigned cvt_pk_bf16(float lo, float hi) { unsigned r; asm volatile("s_nop 1\n\tv_cvt_pk_bf16_f32 %0, %1, %2" : "=v"(r) : "v"(lo), "v"(hi)); return r; }
; __device__ __forceinline__ float bf_lo(unsigned u) { return __uint_as_float(u << 16); }
; __device__ __forceinline__ float bf_hi(unsigned u) { return __uint_as_float(u & 0xffff0000u); }
; __device__ __forceinline__ void ret_out_item(ldsp lds, int item, const bf16_t* rq, const bf16_t* rk, const bf16_t* vT, const bf16_t* kdT, bf16_t* rg, const float* L,
;                                              const float* gn_g, float lg, int tid_, int w, int fr_, int fq_) {
;     ...
;         const float* gp = gn_g + h * 256 + 4 * fq;
; #pragma unroll
;         for (int nt = 0; nt < 16; ++nt) {
;             const f32x4 gg = *(const f32x4*)(gp + 16 * nt); const u32x2 sv = nt < 8 ? svr[nt] : *(const u32x2*)(rp + 16 * nt);
;             u32x2 wv; wv.x = cvt_pk_bf16(o[nt][0] * rstd * gg[0] * bf_lo(sv.x), o[nt][1] * rstd * gg[1] * bf_hi(sv.x));
;             wv.y = cvt_pk_bf16(o[nt][2] * rstd * gg[2] * bf_lo(sv.y), o[nt][3] * rstd * gg[3] * bf_hi(sv.y));
;             *(u32x2*)(rp + 16 * nt) = wv;
;         }
	v_mul_f32_e32 v134, v156, v134
	v_mul_f32_e32 v134, v134, v135
	v_mul_f32_e32 v135, v153, v123
	v_mul_f32_e32 v135, v157, v135
	v_mul_f32_e32 v135, v135, v146
	s_nop 1
	v_cvt_pk_bf16_f32 v134, v134, v135
	v_mul_f32_e32 v135, v154, v123
	v_mul_f32_e32 v135, v158, v135
	v_lshlrev_b32_e32 v146, 16, v215
	v_mul_f32_e32 v135, v135, v146
	v_mul_f32_e32 v146, v155, v123
	v_mul_f32_e32 v146, v159, v146
	v_mul_f32_e32 v146, v146, v147
	s_nop 1
	v_cvt_pk_bf16_f32 v135, v135, v146
	flat_store_dwordx2 v[198:199], v[134:135] offset:32
	flat_load_dwordx4 v[152:155], v[110:111] offset:128 nt
	v_mul_f32_e32 v134, v148, v123
	v_lshlrev_b32_e32 v135, 16, v212
	v_and_b32_e32 v146, 0xffff0000, v212
	v_and_b32_e32 v147, 0xffff0000, v213
	s_waitcnt vmcnt(0) lgkmcnt(0)
	v_mul_f32_e32 v134, v152, v134
	v_mul_f32_e32 v134, v134, v135
	v_mul_f32_e32 v135, v149, v123
	v_mul_f32_e32 v135, v153, v135
	v_mul_f32_e32 v135, v135, v146
	s_nop 1
	v_cvt_pk_bf16_f32 v134, v134, v135
	v_mul_f32_e32 v135, v150, v123
	v_mul_f32_e32 v135, v154, v135
	v_lshlrev_b32_e32 v146, 16, v213
	v_mul_f32_e32 v135, v135, v146
	v_mul_f32_e32 v146, v151, v123
	v_mul_f32_e32 v146, v155, v146
	v_mul_f32_e32 v146, v146, v147
	s_nop 1
	v_cvt_pk_bf16_f32 v135, v135, v146
	flat_store_dwordx2 v[198:199], v[134:135] offset:64
	flat_load_dwordx4 v[146:149], v[110:111] offset:192 nt
	v_mul_f32_e32 v134, v144, v123
	v_lshlrev_b32_e32 v135, 16, v210
	v_and_b32_e32 v144, 0xffff0000, v210
	s_waitcnt vmcnt(0) lgkmcnt(0)
	v_mul_f32_e32 v134, v146, v134
	v_mul_f32_e32 v134, v134, v135
	v_mul_f32_e32 v135, v145, v123
	v_mul_f32_e32 v135, v147, v135
	v_mul_f32_e32 v135, v135, v144
	s_nop 1
	v_cvt_pk_bf16_f32 v134, v134, v135
	v_mul_f32_e32 v135, v202, v123
	v_mul_f32_e32 v135, v148, v135
	v_lshlrev_b32_e32 v144, 16, v211
	v_mul_f32_e32 v135, v135, v144
	v_mul_f32_e32 v144, v160, v123
	v_mul_f32_e32 v144, v149, v144
	v_and_b32_e32 v145, 0xffff0000, v211
	v_mul_f32_e32 v144, v144, v145
	s_nop 1
	v_cvt_pk_bf16_f32 v135, v135, v144
	flat_store_dwordx2 v[198:199], v[134:135] offset:96
	flat_load_dwordx4 v[144:147], v[110:111] offset:256 nt
	v_lshlrev_b32_e32 v134, 16, v208
	v_and_b32_e32 v135, 0xffff0000, v208
	v_lshlrev_b32_e32 v148, 16, v209
	v_and_b32_e32 v149, 0xffff0000, v209
	s_waitcnt vmcnt(0) lgkmcnt(0)
	v_mul_f32_e32 v140, v144, v140
	v_mul_f32_e32 v141, v145, v141
	v_mul_f32_e32 v142, v146, v142
	v_mul_f32_e32 v143, v147, v143
	v_mul_f32_e32 v134, v140, v134
	v_mul_f32_e32 v135, v141, v135
	v_mul_f32_e32 v140, v142, v148
	v_mul_f32_e32 v141, v143, v149
	s_nop 1
	v_cvt_pk_bf16_f32 v134, v134, v135
	s_nop 1
	v_cvt_pk_bf16_f32 v135, v140, v141
	flat_store_dwordx2 v[198:199], v[134:135] offset:128
	flat_load_dwordx4 v[140:143], v[110:111] offset:320 nt
	v_lshlrev_b32_e32 v134, 16, v206
	v_and_b32_e32 v135, 0xffff0000, v206
	v_lshlrev_b32_e32 v144, 16, v207
	v_and_b32_e32 v145, 0xffff0000, v207
	s_waitcnt vmcnt(0) lgkmcnt(0)
	v_mul_f32_e32 v136, v140, v136
	v_mul_f32_e32 v137, v141, v137
	v_mul_f32_e32 v138, v142, v138
	v_mul_f32_e32 v139, v143, v139
	v_mul_f32_e32 v134, v136, v134
	v_mul_f32_e32 v135, v137, v135
	v_mul_f32_e32 v136, v138, v144
	v_mul_f32_e32 v137, v139, v145
	s_nop 1
	v_cvt_pk_bf16_f32 v134, v134, v135
	s_nop 1
	v_cvt_pk_bf16_f32 v135, v136, v137
	flat_store_dwordx2 v[198:199], v[134:135] offset:160
	flat_load_dwordx4 v[134:137], v[110:111] offset:384 nt
	v_lshlrev_b32_e32 v138, 16, v204
	v_and_b32_e32 v139, 0xffff0000, v204
	v_mul_f32_e32 v142, v197, v123
	v_mul_f32_e32 v143, v196, v123
	v_lshlrev_b32_e32 v140, 16, v205
	v_and_b32_e32 v141, 0xffff0000, v205
	s_waitcnt vmcnt(0) lgkmcnt(0)
	v_mul_f32_e32 v132, v134, v132
	v_mul_f32_e32 v133, v135, v133
	v_mul_f32_e32 v134, v136, v142
	v_mul_f32_e32 v135, v137, v143
	v_mul_f32_e32 v132, v132, v138
	v_mul_f32_e32 v133, v133, v139
	v_mul_f32_e32 v134, v134, v140
	v_mul_f32_e32 v135, v135, v141
	s_nop 1
	v_cvt_pk_bf16_f32 v132, v132, v133
	s_nop 1
	v_cvt_pk_bf16_f32 v133, v134, v135
	flat_store_dwordx2 v[198:199], v[132:133] offset:192
	flat_load_dwordx4 v[132:135], v[110:111] offset:448 nt
	v_lshlrev_b32_e32 v136, 16, v200
	v_and_b32_e32 v137, 0xffff0000, v200
	v_lshlrev_b32_e32 v138, 16, v201
	v_and_b32_e32 v139, 0xffff0000, v201
	s_waitcnt vmcnt(0) lgkmcnt(0)
	v_mul_f32_e32 v128, v132, v128
	v_mul_f32_e32 v129, v133, v129
	v_mul_f32_e32 v130, v134, v130
	v_mul_f32_e32 v131, v135, v131
	v_mul_f32_e32 v128, v128, v136
	v_mul_f32_e32 v129, v129, v137
	v_mul_f32_e32 v130, v130, v138
	v_mul_f32_e32 v131, v131, v139
	s_nop 1
	v_cvt_pk_bf16_f32 v128, v128, v129
	s_nop 1
	v_cvt_pk_bf16_f32 v129, v130, v131
	flat_store_dwordx2 v[198:199], v[128:129] offset:224
	flat_load_dwordx2 v[132:133], v[198:199] offset:256 nt
	s_waitcnt vmcnt(0) lgkmcnt(0)
	v_lshlrev_b32_e32 v134, 16, v132
	flat_load_dwordx4 v[128:131], v[110:111] offset:512 nt
	v_and_b32_e32 v132, 0xffff0000, v132
	v_lshlrev_b32_e32 v135, 16, v133
	v_and_b32_e32 v133, 0xffff0000, v133
	s_waitcnt vmcnt(0) lgkmcnt(0)
; __device__ __forceinline__ unsigned cvt_pk_bf16(float lo, float hi) { unsigned r; asm volatile("s_nop 1\n\tv_cvt_pk_bf16_f32 %0, %1, %2" : "=v"(r) : "v"(lo), "v"(hi)); return r; }
; __device__ __forceinline__ float bf_lo(unsigned u) { return __uint_as_float(u << 16); }
; __device__ __forceinline__ float bf_hi(unsigned u) { return __uint_as_float(u & 0xffff0000u); }
; __device__ __forceinline__ void ret_out_item(ldsp lds, int item, const bf16_t* rq, const bf16_t* rk, const bf16_t* vT, const bf16_t* kdT, bf16_t* rg, const float* L,
;                                              const float* gn_g, float lg, int tid_, int w, int fr_, int fq_) {
;     ...
;         const float* gp = gn_g + h * 256 + 4 * fq;
; #pragma unroll
;         for (int nt = 0; nt < 16; ++nt) {
;             const f32x4 gg = *(const f32x4*)(gp + 16 * nt); const u32x2 sv = nt < 8 ? svr[nt] : *(const u32x2*)(rp + 16 * nt);
;             u32x2 wv; wv.x = cvt_pk_bf16(o[nt][0] * rstd * gg[0] * bf_lo(sv.x), o[nt][1] * rstd * gg[1] * bf_hi(sv.x));
;             wv.y = cvt_pk_bf16(o[nt][2] * rstd * gg[2] * bf_lo(sv.y), o[nt][3] * rstd * gg[3] * bf_hi(sv.y));
;             *(u32x2*)(rp + 16 * nt) = wv;
;         }
;         __syncthreads();
	v_mul_f32_e32 v124, v124, v128
	v_mul_f32_e32 v125, v125, v129
	v_mul_f32_e32 v126, v126, v130
	v_mul_f32_e32 v127, v127, v131
	v_mul_f32_e32 v124, v124, v134
	v_mul_f32_e32 v125, v125, v132
	v_mul_f32_e32 v126, v126, v135
	v_mul_f32_e32 v127, v127, v133
	s_nop 1
	v_cvt_pk_bf16_f32 v124, v124, v125
	s_nop 1
	v_cvt_pk_bf16_f32 v125, v126, v127
	flat_store_dwordx2 v[198:199], v[124:125] offset:256
	flat_load_dwordx2 v[128:129], v[198:199] offset:288 nt
	v_mul_f32_e32 v130, v226, v123
	flat_load_dwordx4 v[124:127], v[110:111] offset:576 nt
	v_mul_f32_e32 v131, v225, v123
	v_mul_f32_e32 v132, v203, v123
	s_waitcnt vmcnt(0) lgkmcnt(0)
	v_lshlrev_b32_e32 v133, 16, v128
	v_and_b32_e32 v128, 0xffff0000, v128
	v_lshlrev_b32_e32 v134, 16, v129
	v_mul_f32_e32 v120, v120, v124
	v_mul_f32_e32 v124, v130, v125
	v_mul_f32_e32 v125, v131, v126
	v_and_b32_e32 v129, 0xffff0000, v129
	v_mul_f32_e32 v126, v132, v127
	v_mul_f32_e32 v124, v124, v128
	v_mul_f32_e32 v125, v125, v134
	v_mul_f32_e32 v120, v120, v133
	v_mul_f32_e32 v126, v126, v129
	s_nop 1
	v_cvt_pk_bf16_f32 v124, v120, v124
	s_nop 1
	v_cvt_pk_bf16_f32 v125, v125, v126
	flat_store_dwordx2 v[198:199], v[124:125] offset:288
	flat_load_dwordx2 v[128:129], v[198:199] offset:320 nt
	s_waitcnt vmcnt(0) lgkmcnt(0)
	v_lshlrev_b32_e32 v120, 16, v128
	flat_load_dwordx4 v[124:127], v[110:111] offset:640 nt
	v_and_b32_e32 v128, 0xffff0000, v128
	v_lshlrev_b32_e32 v130, 16, v129
	v_and_b32_e32 v129, 0xffff0000, v129
	s_waitcnt vmcnt(0) lgkmcnt(0)
	v_mul_f32_e32 v116, v116, v124
	v_mul_f32_e32 v117, v117, v125
	v_mul_f32_e32 v118, v118, v126
	v_mul_f32_e32 v119, v119, v127
	v_mul_f32_e32 v116, v116, v120
	v_mul_f32_e32 v117, v117, v128
	v_mul_f32_e32 v118, v118, v130
	v_mul_f32_e32 v119, v119, v129
	s_nop 1
	v_cvt_pk_bf16_f32 v116, v116, v117
	s_nop 1
	v_cvt_pk_bf16_f32 v117, v118, v119
	flat_store_dwordx2 v[198:199], v[116:117] offset:320
	flat_load_dwordx2 v[124:125], v[198:199] offset:352 nt
	s_waitcnt vmcnt(0) lgkmcnt(0)
	v_lshlrev_b32_e32 v120, 16, v124
	flat_load_dwordx4 v[116:119], v[110:111] offset:704 nt
	v_and_b32_e32 v124, 0xffff0000, v124
	v_lshlrev_b32_e32 v126, 16, v125
	v_and_b32_e32 v125, 0xffff0000, v125
	s_waitcnt vmcnt(0) lgkmcnt(0)
	v_mul_f32_e32 v112, v112, v116
	v_mul_f32_e32 v113, v113, v117
	v_mul_f32_e32 v114, v114, v118
	v_mul_f32_e32 v115, v115, v119
	v_mul_f32_e32 v112, v112, v120
	v_mul_f32_e32 v113, v113, v124
	v_mul_f32_e32 v114, v114, v126
	v_mul_f32_e32 v115, v115, v125
	s_nop 1
	v_cvt_pk_bf16_f32 v112, v112, v113
	s_nop 1
	v_cvt_pk_bf16_f32 v113, v114, v115
	flat_store_dwordx2 v[198:199], v[112:113] offset:352
	flat_load_dwordx2 v[116:117], v[198:199] offset:384 nt
	v_mul_f32_e32 v118, v122, v123
	flat_load_dwordx4 v[112:115], v[110:111] offset:768 nt
	v_mul_f32_e32 v119, v121, v123
	s_waitcnt vmcnt(0) lgkmcnt(0)
	v_lshlrev_b32_e32 v120, 16, v116
	v_and_b32_e32 v116, 0xffff0000, v116
	v_mul_f32_e32 v108, v108, v112
	v_mul_f32_e32 v109, v109, v113
	v_lshlrev_b32_e32 v121, 16, v117
	v_and_b32_e32 v117, 0xffff0000, v117
	v_mul_f32_e32 v112, v118, v114
	v_mul_f32_e32 v113, v119, v115
	v_mul_f32_e32 v108, v108, v120
	v_mul_f32_e32 v109, v109, v116
	v_mul_f32_e32 v112, v112, v121
	v_mul_f32_e32 v113, v113, v117
	s_nop 1
	v_cvt_pk_bf16_f32 v108, v108, v109
	s_nop 1
	v_cvt_pk_bf16_f32 v109, v112, v113
	flat_store_dwordx2 v[198:199], v[108:109] offset:384
	flat_load_dwordx2 v[116:117], v[198:199] offset:416 nt
	flat_load_dwordx4 v[112:115], v[110:111] offset:832 nt
	s_waitcnt vmcnt(0) lgkmcnt(0)
	v_lshlrev_b32_e32 v108, 16, v116
	v_and_b32_e32 v109, 0xffff0000, v116
	v_mul_f32_e32 v104, v104, v112
	v_mul_f32_e32 v105, v105, v113
	v_lshlrev_b32_e32 v116, 16, v117
	v_and_b32_e32 v117, 0xffff0000, v117
	v_mul_f32_e32 v106, v106, v114
	v_mul_f32_e32 v107, v107, v115
	v_mul_f32_e32 v104, v104, v108
	v_mul_f32_e32 v105, v105, v109
	v_mul_f32_e32 v106, v106, v116
	v_mul_f32_e32 v107, v107, v117
	s_nop 1
	v_cvt_pk_bf16_f32 v104, v104, v105
	s_nop 1
	v_cvt_pk_bf16_f32 v105, v106, v107
	flat_store_dwordx2 v[198:199], v[104:105] offset:416
	flat_load_dwordx2 v[108:109], v[198:199] offset:448 nt
	s_waitcnt vmcnt(0) lgkmcnt(0)
	v_lshlrev_b32_e32 v112, 16, v108
	flat_load_dwordx4 v[104:107], v[110:111] offset:896 nt
	v_and_b32_e32 v108, 0xffff0000, v108
	v_lshlrev_b32_e32 v113, 16, v109
	v_and_b32_e32 v109, 0xffff0000, v109
	s_waitcnt vmcnt(0) lgkmcnt(0)
	v_mul_f32_e32 v100, v100, v104
	v_mul_f32_e32 v101, v101, v105
	v_mul_f32_e32 v102, v102, v106
	v_mul_f32_e32 v103, v103, v107
	v_mul_f32_e32 v100, v100, v112
	v_mul_f32_e32 v101, v101, v108
	v_mul_f32_e32 v102, v102, v113
	v_mul_f32_e32 v103, v103, v109
	s_nop 1
	v_cvt_pk_bf16_f32 v100, v100, v101
	s_nop 1
	v_cvt_pk_bf16_f32 v101, v102, v103
	flat_store_dwordx2 v[198:199], v[100:101] offset:448
	flat_load_dwordx2 v[104:105], v[198:199] offset:480 nt
	s_waitcnt vmcnt(0) lgkmcnt(0)
	v_lshlrev_b32_e32 v106, 16, v104
	flat_load_dwordx4 v[100:103], v[110:111] offset:960 nt
	v_and_b32_e32 v104, 0xffff0000, v104
	v_lshlrev_b32_e32 v107, 16, v105
	v_and_b32_e32 v105, 0xffff0000, v105
	s_waitcnt vmcnt(0) lgkmcnt(0)
	v_mul_f32_e32 v96, v96, v100
	v_mul_f32_e32 v97, v97, v101
	v_mul_f32_e32 v98, v98, v102
	v_mul_f32_e32 v99, v99, v103
	v_mul_f32_e32 v96, v96, v106
	v_mul_f32_e32 v97, v97, v104
	v_mul_f32_e32 v98, v98, v107
	v_mul_f32_e32 v99, v99, v105
	s_nop 1
	v_cvt_pk_bf16_f32 v96, v96, v97
	s_nop 1
	v_cvt_pk_bf16_f32 v97, v98, v99
	flat_store_dwordx2 v[198:199], v[96:97] offset:480
	s_waitcnt lgkmcnt(0)
	s_barrier
	s_cbranch_scc0 .LBB0_547

; #define LAS __attribute__((address_space(3)))
; __device__ __forceinline__ unsigned cvt_pk_bf16(float lo, float hi) { unsigned r; asm volatile("s_nop 1\n\tv_cvt_pk_bf16_f32 %0, %1, %2" : "=v"(r) : "v"(lo), "v"(hi)); return r; }
; #define MFMA16(a, b, c) __builtin_amdgcn_mfma_f32_16x16x32_bf16((a), (b), (c), 0, 0, 0)
; __device__ __forceinline__ void stage_kdT(ldsp dst, const bf16_t* src, float lg, int tid) {
;     const int c = tid & 15;
; #pragma unroll
;     for (int ii = 0; ii < 4; ++ii) {
;         const int r = (tid >> 4) + 32 * ii;
;         const u32x4 v = *(const u32x4*)(src + (size_t)r * 1024 + c * 8);
;         const float dec = __builtin_amdgcn_exp2f((float)(127 - r) * lg);
; #pragma unroll
;         for (int e = 0; e < 8; ++e) {
;             const int ee = (e + c) & 7, q2 = ee >> 1;
;             const unsigned d = q2 == 0 ? v.x : (q2 == 1 ? v.y : (q2 == 2 ? v.z : v.w));
;             const float f = __uint_as_float((ee & 1) ? (d & 0xffff0000u) : (d << 16)) * dec;
;             *(LAS unsigned short*)(dst + (8 * c + ee) * 272 + r * 2) = (unsigned short)(cvt_pk_bf16(f, 0.f) & 0xffffu);
; __device__ __forceinline__ void ret_out_item(ldsp lds, int item, const bf16_t* rq, const bf16_t* rk, const bf16_t* vT, const bf16_t* kdT, bf16_t* rg, const float* L,
;                                              const float* gn_g, float lg, int tid_, int w, int fr_, int fq_) {
;     ...
;         for (int ks = 0; ks < 4; ++ks) {
;             const bf16x8 a = frag(lds + RX0, i, ks, fq);
; #pragma unroll
;             for (int nt = 0; nt < 16; ++nt) o[nt] = MFMA16(frag(lds + RY, 16 * nt + fr, ks, fq), a, o[nt]);
;         }
;         const float qd = __builtin_amdgcn_exp2f((float)(i + 1) * lg);
; #pragma unroll
;         for (int nt = 0; nt < 16; ++nt) o[nt] = o[nt] * qd;
;         __syncthreads();
; #pragma unroll
;         for (int nt = 0; nt < 8; ++nt) *(LAS u32x2*)(lds + RX1 + i * 272 + (16 * nt + 4 * fq) * 2) = pk[nt];
.LBB0_553:
	v_add_u32_e32 v242, s0, v229
	v_add_u32_e32 v201, s0, v197
	v_add_u32_e32 v234, 0x11000, v242
	v_add_u32_e32 v238, 0x12100, v242
	ds_read_b128 v[230:233], v201
	ds_read_b128 v[234:237], v234
	ds_read_b128 v[238:241], v238
	v_add_u32_e32 v243, 0x13200, v242
	s_waitcnt lgkmcnt(1)
	v_mfma_f32_16x16x32_bf16 v[156:159], v[234:237], v[230:233], v[156:159]
	ds_read_b128 v[234:237], v243
	v_add_u32_e32 v244, 0x14300, v242
	v_add_u32_e32 v245, 0x15400, v242
	s_waitcnt lgkmcnt(1)
	v_mfma_f32_16x16x32_bf16 v[152:155], v[238:241], v[230:233], v[152:155]
	ds_read_b128 v[238:241], v244
	v_add_u32_e32 v246, 0x16500, v242
	v_add_u32_e32 v247, 0x17600, v242
	s_waitcnt lgkmcnt(1)
	v_mfma_f32_16x16x32_bf16 v[148:151], v[234:237], v[230:233], v[148:151]
	ds_read_b128 v[234:237], v245
	v_add_u32_e32 v248, 0x18700, v242
	v_add_u32_e32 v249, 0x19800, v242
	s_waitcnt lgkmcnt(1)
	v_mfma_f32_16x16x32_bf16 v[144:147], v[238:241], v[230:233], v[144:147]
	ds_read_b128 v[238:241], v246
	v_add_u32_e32 v250, 0x1a900, v242
	v_add_u32_e32 v251, 0x1ba00, v242
	s_waitcnt lgkmcnt(1)
	v_mfma_f32_16x16x32_bf16 v[140:143], v[234:237], v[230:233], v[140:143]
	ds_read_b128 v[234:237], v247
	v_add_u32_e32 v252, 0x1cb00, v242
	v_add_u32_e32 v253, 0x1dc00, v242
	s_waitcnt lgkmcnt(1)
	v_mfma_f32_16x16x32_bf16 v[136:139], v[238:241], v[230:233], v[136:139]
	ds_read_b128 v[238:241], v248
	v_add_u32_e32 v178, 0x1ed00, v242
	v_add_u32_e32 v179, 0x1fe00, v242
	s_waitcnt lgkmcnt(1)
	v_mfma_f32_16x16x32_bf16 v[132:135], v[234:237], v[230:233], v[132:135]
	ds_read_b128 v[234:237], v249
	s_add_i32 s0, s0, 64
	s_cmpk_eq_i32 s0, 0x100
	s_waitcnt lgkmcnt(1)
	v_mfma_f32_16x16x32_bf16 v[128:131], v[238:241], v[230:233], v[128:131]
	ds_read_b128 v[238:241], v250
	s_waitcnt lgkmcnt(1)
	v_mfma_f32_16x16x32_bf16 v[124:127], v[234:237], v[230:233], v[124:127]
	ds_read_b128 v[234:237], v251
	s_waitcnt lgkmcnt(1)
	v_mfma_f32_16x16x32_bf16 v[120:123], v[238:241], v[230:233], v[120:123]
	ds_read_b128 v[238:241], v252
	s_waitcnt lgkmcnt(1)
	v_mfma_f32_16x16x32_bf16 v[116:119], v[234:237], v[230:233], v[116:119]
	ds_read_b128 v[234:237], v253
	s_waitcnt lgkmcnt(1)
	v_mfma_f32_16x16x32_bf16 v[112:115], v[238:241], v[230:233], v[112:115]
	ds_read_b128 v[238:241], v178
	s_waitcnt lgkmcnt(1)
	v_mfma_f32_16x16x32_bf16 v[108:111], v[234:237], v[230:233], v[108:111]
	ds_read_b128 v[234:237], v179
	v_add_u32_e32 v178, 0x20f00, v242
	s_waitcnt lgkmcnt(0)
	v_mfma_f32_16x16x32_bf16 v[100:103], v[234:237], v[230:233], v[100:103]
	ds_read_b128 v[234:237], v178
	v_mfma_f32_16x16x32_bf16 v[104:107], v[238:241], v[230:233], v[104:107]
	s_waitcnt lgkmcnt(0)
	v_mfma_f32_16x16x32_bf16 v[96:99], v[234:237], v[230:233], v[96:99]
	s_cbranch_scc0 .LBB0_553
	s_lshl_b32 s0, s60, 7
	v_add_u32_e32 v160, v195, v160
	v_add_u32_e32 v160, 0x8800, v160
	s_or_b32 s72, s62, s0
	s_mov_b32 s73, s63
	s_barrier
	ds_write2_b64 v160, v[202:203], v[204:205] offset1:4
	ds_write2_b64 v160, v[206:207], v[208:209] offset0:8 offset1:12
	ds_write2_b64 v160, v[210:211], v[212:213] offset0:16 offset1:20
	ds_write2_b64 v160, v[214:215], v[216:217] offset0:24 offset1:28
	s_lshl_b64 s[0:1], s[72:73], 11
	v_lshlrev_b32_e32 v160, 3, v185
	s_add_u32 s0, s66, s0
	v_and_b32_e32 v202, 0x78, v160
	s_addc_u32 s1, s67, s1
	v_lshlrev_b32_e32 v160, 1, v202
	v_ashrrev_i32_e32 v197, 31, v196
	v_lshl_add_u64 v[204:205], s[0:1], 0, v[160:161]
	v_lshlrev_b64 v[206:207], 11, v[196:197]
	v_lshl_add_u64 v[206:207], v[204:205], 0, v[206:207]
	flat_load_dwordx4 v[206:209], v[206:207] nt
	v_sub_u32_e32 v160, 0x7f, v196
	v_cvt_f32_i32_e32 v160, v160
	v_bfe_u32 v203, v185, 1, 2
	v_add_u32_e32 v211, 1, v185
	v_cmp_eq_u32_e64 s[10:11], 2, v203
	v_and_b32_e32 v201, 7, v185
	v_add_u32_e32 v212, 2, v185
	v_and_b32_e32 v214, 7, v211
	v_bfe_u32 v211, v211, 1, 2
	v_mul_f32_e32 v160, v224, v160
	v_cmp_eq_u32_e64 s[18:19], 1, v203
	v_add_u32_e32 v213, 3, v185
	v_and_b32_e32 v215, 7, v212
	v_bfe_u32 v212, v212, 1, 2
	v_exp_f32_e32 v160, v160
	v_cmp_eq_u32_e64 s[12:13], 2, v211
	v_cmp_gt_u32_e64 s[22:23], 2, v201
	v_and_b32_e32 v210, 1, v185
	v_bfe_u32 v217, v213, 1, 2
	v_or_b32_e32 v230, v202, v201
	v_cmp_eq_u32_e64 s[14:15], 2, v212
	v_cmp_eq_u32_e64 s[20:21], 1, v211
	v_or_b32_e32 v231, v214, v202
	v_cmp_eq_u32_e64 s[0:1], 2, v217
	v_cmp_eq_u32_e64 s[6:7], 1, v212
	v_cmp_gt_u32_e64 s[24:25], 2, v214
	v_cmp_eq_u32_e32 vcc, 0, v210
	v_and_b32_e32 v216, 7, v213
	v_cmp_eq_u32_e64 s[56:57], 1, v217
	v_cmp_gt_u32_e64 s[8:9], 2, v215
	v_lshl_add_u32 v195, v196, 1, 0
	v_or_b32_e32 v232, v215, v202
	v_cmp_gt_u32_e64 s[4:5], 2, v216
	v_and_b32_e32 v213, 1, v213
	v_or_b32_e32 v233, v216, v202
	v_mad_u32_u24 v234, v230, s89, v195
	v_mad_u32_u24 v235, v231, s89, v195
	v_cmp_eq_u32_e64 s[16:17], 0, v213
	v_mad_u32_u24 v236, v232, s89, v195
	s_waitcnt vmcnt(0) lgkmcnt(0)
; #define LAS __attribute__((address_space(3)))
; __device__ __forceinline__ unsigned cvt_pk_bf16(float lo, float hi) { unsigned r; asm volatile("s_nop 1\n\tv_cvt_pk_bf16_f32 %0, %1, %2" : "=v"(r) : "v"(lo), "v"(hi)); return r; }
; __device__ __forceinline__ void stage_kdT(ldsp dst, const bf16_t* src, float lg, int tid) {
;     ...
;     for (int ii = 0; ii < 4; ++ii) {
;         const int r = (tid >> 4) + 32 * ii;
;         const u32x4 v = *(const u32x4*)(src + (size_t)r * 1024 + c * 8);
;         const float dec = __builtin_amdgcn_exp2f((float)(127 - r) * lg);
; #pragma unroll
;         for (int e = 0; e < 8; ++e) {
;             const int ee = (e + c) & 7, q2 = ee >> 1;
;             const unsigned d = q2 == 0 ? v.x : (q2 == 1 ? v.y : (q2 == 2 ? v.z : v.w));
;             const float f = __uint_as_float((ee & 1) ? (d & 0xffff0000u) : (d << 16)) * dec;
;             *(LAS unsigned short*)(dst + (8 * c + ee) * 272 + r * 2) = (unsigned short)(cvt_pk_bf16(f, 0.f) & 0xffffu);
;         }
;     }
	v_cndmask_b32_e64 v237, v209, v208, s[10:11]
	v_cndmask_b32_e64 v203, v237, v207, s[18:19]
	v_cndmask_b32_e64 v238, v209, v208, s[12:13]
	v_cndmask_b32_e64 v201, v203, v206, s[22:23]
	v_cndmask_b32_e64 v239, v209, v208, s[14:15]
	v_cndmask_b32_e64 v211, v238, v207, s[20:21]
	v_and_b32_e32 v214, 0xffff0000, v201
	v_lshlrev_b32_e32 v201, 16, v201
	v_cndmask_b32_e64 v240, v209, v208, s[0:1]
	v_cndmask_b32_e64 v212, v239, v207, s[6:7]
	v_cndmask_b32_e64 v203, v211, v206, s[24:25]
	v_cndmask_b32_e32 v201, v214, v201, vcc
	v_cndmask_b32_e64 v217, v240, v207, s[56:57]
	v_cndmask_b32_e64 v211, v212, v206, s[8:9]
	v_and_b32_e32 v215, 0xffff0000, v203
	v_lshlrev_b32_e32 v203, 16, v203
	v_mul_f32_e32 v201, v160, v201
	v_cndmask_b32_e64 v212, v217, v206, s[4:5]
	v_and_b32_e32 v216, 0xffff0000, v211
	v_lshlrev_b32_e32 v211, 16, v211
	v_cndmask_b32_e32 v203, v203, v215, vcc
	s_nop 1
	v_cvt_pk_bf16_f32 v201, v201, v161
	v_and_b32_e32 v217, 0xffff0000, v212
	v_lshlrev_b32_e32 v212, 16, v212
	v_cndmask_b32_e32 v210, v216, v211, vcc
	v_mul_f32_e32 v203, v160, v203
	ds_write_b16 v234, v201
	s_nop 1
	v_cvt_pk_bf16_f32 v201, v203, v161
	v_cndmask_b32_e64 v211, v217, v212, s[16:17]
	v_mul_f32_e32 v210, v160, v210
	ds_write_b16 v235, v201
	s_nop 1
	v_cvt_pk_bf16_f32 v201, v210, v161
	v_mul_f32_e32 v211, v160, v211
	ds_write_b16 v236, v201
	s_nop 1
	v_cvt_pk_bf16_f32 v201, v211, v161
	v_mad_u32_u24 v203, v233, s89, v195
	ds_write_b16 v203, v201
	v_bitop3_b32 v201, v185, 4, 7 bitop3:0x6c
	v_lshrrev_b32_e32 v203, 1, v201
	v_cmp_eq_u32_e64 s[26:27], 2, v203
	v_cmp_eq_u32_e64 s[28:29], 1, v203
	v_cmp_gt_u32_e64 s[30:31], 2, v201
	v_cndmask_b32_e64 v210, v209, v208, s[26:27]
	v_cndmask_b32_e64 v203, v210, v207, s[28:29]
	v_cndmask_b32_e64 v203, v203, v206, s[30:31]
	v_and_b32_e32 v210, 0xffff0000, v203
	v_lshlrev_b32_e32 v203, 16, v203
	v_cndmask_b32_e32 v203, v210, v203, vcc
	v_mul_f32_e32 v203, v160, v203
	v_or_b32_e32 v201, v201, v202
	s_nop 1
	v_cvt_pk_bf16_f32 v203, v203, v161
	v_mad_u32_u24 v210, v201, s89, v195
	ds_write_b16 v210, v203
	v_add_u32_e32 v203, 5, v185
	v_bfe_u32 v211, v203, 1, 2
	v_cmp_eq_u32_e64 s[34:35], 2, v211
	v_and_b32_e32 v210, 7, v203
	v_cmp_eq_u32_e64 s[36:37], 1, v211
	v_cndmask_b32_e64 v212, v209, v208, s[34:35]
	v_cmp_gt_u32_e64 s[38:39], 2, v210
	v_cndmask_b32_e64 v211, v212, v207, s[36:37]
	v_and_b32_e32 v203, 1, v203
	v_cndmask_b32_e64 v211, v211, v206, s[38:39]
	v_and_b32_e32 v212, 0xffff0000, v211
	v_lshlrev_b32_e32 v211, 16, v211
	v_cmp_eq_u32_e64 s[40:41], 0, v203
	s_nop 1
	v_cndmask_b32_e64 v203, v212, v211, s[40:41]
	v_mul_f32_e32 v203, v160, v203
	v_or_b32_e32 v212, v210, v202
	s_nop 1
	v_cvt_pk_bf16_f32 v203, v203, v161
	v_mad_u32_u24 v210, v212, s89, v195
	ds_write_b16 v210, v203
	v_add_u32_e32 v203, 6, v185
	v_and_b32_e32 v210, 7, v203
	v_bfe_u32 v203, v203, 1, 2
	v_cmp_eq_u32_e64 s[42:43], 2, v203
	v_cmp_eq_u32_e64 s[44:45], 1, v203
	v_cmp_gt_u32_e64 s[46:47], 2, v210
	v_cndmask_b32_e64 v211, v209, v208, s[42:43]
	v_cndmask_b32_e64 v203, v211, v207, s[44:45]
	v_cndmask_b32_e64 v203, v203, v206, s[46:47]
	v_and_b32_e32 v211, 0xffff0000, v203
	v_lshlrev_b32_e32 v203, 16, v203
	v_cndmask_b32_e32 v203, v211, v203, vcc
	v_mul_f32_e32 v203, v160, v203
	v_or_b32_e32 v213, v210, v202
	s_nop 1
	v_cvt_pk_bf16_f32 v203, v203, v161
	v_mad_u32_u24 v210, v213, s89, v195
	ds_write_b16 v210, v203
	v_add_u32_e32 v203, 7, v185
	v_bfe_u32 v211, v203, 1, 2
	v_cmp_eq_u32_e64 s[48:49], 2, v211
	v_and_b32_e32 v210, 7, v203
	v_cmp_eq_u32_e64 s[50:51], 1, v211
	v_cndmask_b32_e64 v208, v209, v208, s[48:49]
	v_cmp_gt_u32_e64 s[52:53], 2, v210
	v_cndmask_b32_e64 v207, v208, v207, s[50:51]
	v_and_b32_e32 v203, 1, v203
	v_cndmask_b32_e64 v206, v207, v206, s[52:53]
	v_and_b32_e32 v207, 0xffff0000, v206
	v_lshlrev_b32_e32 v206, 16, v206
	v_cmp_eq_u32_e64 s[54:55], 0, v203
	s_nop 1
	v_cndmask_b32_e64 v203, v207, v206, s[54:55]
	v_mul_f32_e32 v160, v160, v203
	v_or_b32_e32 v203, v210, v202
	v_add_u32_e32 v210, 32, v196
	v_ashrrev_i32_e32 v211, 31, v210
	v_mad_u32_u24 v195, v203, s89, v195
	v_lshlrev_b64 v[206:207], 11, v[210:211]
	s_nop 1
	v_cvt_pk_bf16_f32 v160, v160, v161
	ds_write_b16 v195, v160
	v_lshl_add_u64 v[206:207], v[204:205], 0, v[206:207]
	flat_load_dwordx4 v[206:209], v[206:207] nt
	v_sub_u32_e32 v160, 0x5f, v196
	v_cvt_f32_i32_e32 v160, v160
	v_lshl_add_u32 v195, v210, 1, 0
	v_mad_u32_u24 v210, v230, s89, v195
	v_mul_f32_e32 v160, v224, v160
	v_exp_f32_e32 v160, v160
	s_waitcnt vmcnt(0) lgkmcnt(0)
; #define LAS __attribute__((address_space(3)))
; __device__ __forceinline__ unsigned cvt_pk_bf16(float lo, float hi) { unsigned r; asm volatile("s_nop 1\n\tv_cvt_pk_bf16_f32 %0, %1, %2" : "=v"(r) : "v"(lo), "v"(hi)); return r; }
; __device__ __forceinline__ void stage_kdT(ldsp dst, const bf16_t* src, float lg, int tid) {
;     ...
;     for (int ii = 0; ii < 4; ++ii) {
;         const int r = (tid >> 4) + 32 * ii;
;         const u32x4 v = *(const u32x4*)(src + (size_t)r * 1024 + c * 8);
;         const float dec = __builtin_amdgcn_exp2f((float)(127 - r) * lg);
; #pragma unroll
;         for (int e = 0; e < 8; ++e) {
;             const int ee = (e + c) & 7, q2 = ee >> 1;
;             const unsigned d = q2 == 0 ? v.x : (q2 == 1 ? v.y : (q2 == 2 ? v.z : v.w));
;             const float f = __uint_as_float((ee & 1) ? (d & 0xffff0000u) : (d << 16)) * dec;
;             *(LAS unsigned short*)(dst + (8 * c + ee) * 272 + r * 2) = (unsigned short)(cvt_pk_bf16(f, 0.f) & 0xffffu);
;         }
;     }
	v_cndmask_b32_e64 v211, v209, v208, s[10:11]
	v_cndmask_b32_e64 v211, v211, v207, s[18:19]
	v_cndmask_b32_e64 v211, v211, v206, s[22:23]
	v_and_b32_e32 v214, 0xffff0000, v211
	v_lshlrev_b32_e32 v211, 16, v211
	v_cndmask_b32_e32 v211, v214, v211, vcc
	v_mul_f32_e32 v211, v160, v211
	s_nop 1
	v_cvt_pk_bf16_f32 v211, v211, v161
	ds_write_b16 v210, v211
	v_cndmask_b32_e64 v210, v209, v208, s[12:13]
	v_cndmask_b32_e64 v210, v210, v207, s[20:21]
	v_cndmask_b32_e64 v210, v210, v206, s[24:25]
	v_and_b32_e32 v211, 0xffff0000, v210
	v_lshlrev_b32_e32 v210, 16, v210
	v_cndmask_b32_e32 v210, v210, v211, vcc
	v_mul_f32_e32 v210, v160, v210
	s_nop 1
	v_cvt_pk_bf16_f32 v210, v210, v161
	v_mad_u32_u24 v211, v231, s89, v195
	ds_write_b16 v211, v210
	v_cndmask_b32_e64 v210, v209, v208, s[14:15]
	v_cndmask_b32_e64 v210, v210, v207, s[6:7]
	v_cndmask_b32_e64 v210, v210, v206, s[8:9]
	v_and_b32_e32 v211, 0xffff0000, v210
	v_lshlrev_b32_e32 v210, 16, v210
	v_cndmask_b32_e32 v210, v211, v210, vcc
	v_mul_f32_e32 v210, v160, v210
	s_nop 1
	v_cvt_pk_bf16_f32 v210, v210, v161
	v_mad_u32_u24 v211, v232, s89, v195
	ds_write_b16 v211, v210
	v_cndmask_b32_e64 v210, v209, v208, s[0:1]
	v_cndmask_b32_e64 v210, v210, v207, s[56:57]
	v_cndmask_b32_e64 v210, v210, v206, s[4:5]
	v_and_b32_e32 v211, 0xffff0000, v210
	v_lshlrev_b32_e32 v210, 16, v210
	v_cndmask_b32_e64 v210, v211, v210, s[16:17]
	v_mul_f32_e32 v210, v160, v210
	s_nop 1
	v_cvt_pk_bf16_f32 v210, v210, v161
	v_mad_u32_u24 v211, v233, s89, v195
	ds_write_b16 v211, v210
	v_cndmask_b32_e64 v210, v209, v208, s[26:27]
	v_cndmask_b32_e64 v210, v210, v207, s[28:29]
	v_cndmask_b32_e64 v210, v210, v206, s[30:31]
	v_and_b32_e32 v211, 0xffff0000, v210
	v_lshlrev_b32_e32 v210, 16, v210
	v_cndmask_b32_e32 v210, v211, v210, vcc
	v_mul_f32_e32 v210, v160, v210
	s_nop 1
	v_cvt_pk_bf16_f32 v210, v210, v161
	v_mad_u32_u24 v211, v201, s89, v195
	ds_write_b16 v211, v210
	v_cndmask_b32_e64 v210, v209, v208, s[34:35]
	v_cndmask_b32_e64 v210, v210, v207, s[36:37]
	v_cndmask_b32_e64 v210, v210, v206, s[38:39]
	v_and_b32_e32 v211, 0xffff0000, v210
	v_lshlrev_b32_e32 v210, 16, v210
	v_cndmask_b32_e64 v210, v211, v210, s[40:41]
	v_mul_f32_e32 v210, v160, v210
	s_nop 1
	v_cvt_pk_bf16_f32 v210, v210, v161
	v_mad_u32_u24 v211, v212, s89, v195
	ds_write_b16 v211, v210
	v_cndmask_b32_e64 v210, v209, v208, s[42:43]
	v_cndmask_b32_e64 v210, v210, v207, s[44:45]
	v_cndmask_b32_e64 v210, v210, v206, s[46:47]
	v_and_b32_e32 v211, 0xffff0000, v210
	v_lshlrev_b32_e32 v210, 16, v210
	v_cndmask_b32_e32 v210, v211, v210, vcc
	v_cndmask_b32_e64 v208, v209, v208, s[48:49]
	v_mul_f32_e32 v210, v160, v210
	v_cndmask_b32_e64 v207, v208, v207, s[50:51]
	s_nop 1
	v_cvt_pk_bf16_f32 v210, v210, v161
	v_mad_u32_u24 v211, v213, s89, v195
	v_cndmask_b32_e64 v206, v207, v206, s[52:53]
	ds_write_b16 v211, v210
	v_and_b32_e32 v207, 0xffff0000, v206
	v_lshlrev_b32_e32 v206, 16, v206
	v_add_u32_e32 v210, 64, v196
	v_cndmask_b32_e64 v206, v207, v206, s[54:55]
	v_ashrrev_i32_e32 v211, 31, v210
	v_mul_f32_e32 v160, v160, v206
	v_mad_u32_u24 v195, v203, s89, v195
	v_lshlrev_b64 v[206:207], 11, v[210:211]
	s_nop 1
	v_cvt_pk_bf16_f32 v160, v160, v161
	ds_write_b16 v195, v160
	v_lshl_add_u64 v[206:207], v[204:205], 0, v[206:207]
	flat_load_dwordx4 v[206:209], v[206:207] nt
	v_sub_u32_e32 v160, 63, v196
	v_cvt_f32_i32_e32 v160, v160
	v_lshl_add_u32 v195, v210, 1, 0
	v_mad_u32_u24 v210, v230, s89, v195
	v_mul_f32_e32 v160, v224, v160
	v_exp_f32_e32 v160, v160
	s_waitcnt vmcnt(0) lgkmcnt(0)
	v_cndmask_b32_e64 v211, v209, v208, s[10:11]
	v_cndmask_b32_e64 v211, v211, v207, s[18:19]
	v_cndmask_b32_e64 v214, v209, v208, s[12:13]
	v_cndmask_b32_e64 v211, v211, v206, s[22:23]
	v_cndmask_b32_e64 v214, v214, v207, s[20:21]
	v_and_b32_e32 v215, 0xffff0000, v211
	v_lshlrev_b32_e32 v211, 16, v211
	v_cndmask_b32_e64 v214, v214, v206, s[24:25]
	v_cndmask_b32_e32 v211, v215, v211, vcc
	v_and_b32_e32 v216, 0xffff0000, v214
	v_lshlrev_b32_e32 v214, 16, v214
	v_mul_f32_e32 v211, v160, v211
	s_nop 1
	v_cvt_pk_bf16_f32 v211, v211, v161
	ds_write_b16 v210, v211
	v_cndmask_b32_e32 v210, v214, v216, vcc
	v_mul_f32_e32 v210, v160, v210
	s_nop 1
	v_cvt_pk_bf16_f32 v210, v210, v161
	v_mad_u32_u24 v211, v231, s89, v195
	ds_write_b16 v211, v210
	v_cndmask_b32_e64 v210, v209, v208, s[14:15]
	v_cndmask_b32_e64 v210, v210, v207, s[6:7]
	v_cndmask_b32_e64 v210, v210, v206, s[8:9]
	v_and_b32_e32 v211, 0xffff0000, v210
	v_lshlrev_b32_e32 v210, 16, v210
	v_cndmask_b32_e32 v210, v211, v210, vcc
	v_mul_f32_e32 v210, v160, v210
	s_nop 1
	v_cvt_pk_bf16_f32 v210, v210, v161
	v_mad_u32_u24 v211, v232, s89, v195
	ds_write_b16 v211, v210
	v_cndmask_b32_e64 v210, v209, v208, s[0:1]
	v_cndmask_b32_e64 v210, v210, v207, s[56:57]
	v_cndmask_b32_e64 v210, v210, v206, s[4:5]
	v_and_b32_e32 v211, 0xffff0000, v210
	v_lshlrev_b32_e32 v210, 16, v210
	v_cndmask_b32_e64 v210, v211, v210, s[16:17]
	v_mul_f32_e32 v210, v160, v210
	s_nop 1
	v_cvt_pk_bf16_f32 v210, v210, v161
	v_mad_u32_u24 v211, v233, s89, v195
	ds_write_b16 v211, v210
	v_cndmask_b32_e64 v210, v209, v208, s[26:27]
	v_cndmask_b32_e64 v210, v210, v207, s[28:29]
	v_cndmask_b32_e64 v210, v210, v206, s[30:31]
	v_and_b32_e32 v211, 0xffff0000, v210
	v_lshlrev_b32_e32 v210, 16, v210
	v_cndmask_b32_e32 v210, v211, v210, vcc
	v_mul_f32_e32 v210, v160, v210
	s_nop 1
	v_cvt_pk_bf16_f32 v210, v210, v161
	v_mad_u32_u24 v211, v201, s89, v195
	ds_write_b16 v211, v210
	v_cndmask_b32_e64 v210, v209, v208, s[34:35]
	v_cndmask_b32_e64 v210, v210, v207, s[36:37]
	v_cndmask_b32_e64 v210, v210, v206, s[38:39]
	v_and_b32_e32 v211, 0xffff0000, v210
	v_lshlrev_b32_e32 v210, 16, v210
; #define LAS __attribute__((address_space(3)))
; __device__ __forceinline__ unsigned cvt_pk_bf16(float lo, float hi) { unsigned r; asm volatile("s_nop 1\n\tv_cvt_pk_bf16_f32 %0, %1, %2" : "=v"(r) : "v"(lo), "v"(hi)); return r; }
; template <int R>
; __device__ __forceinline__ void stage_tile(ldsp dst, const bf16_t* src, size_t ld, int tid) {
; #pragma unroll
;     for (int i = 0; i < R * 16 / 512; ++i) { const int idx = tid + 512 * i, r = idx >> 4, c = idx & 15;
;         const u32x4 v = *(const u32x4*)(src + (size_t)r * ld + c * 8); *(LAS u32x4*)(dst + r * 272 + c * 16) = v; }
; }
; __device__ __forceinline__ void stage_kdT(ldsp dst, const bf16_t* src, float lg, int tid) {
;     ...
;     for (int ii = 0; ii < 4; ++ii) {
;         const int r = (tid >> 4) + 32 * ii;
;         const u32x4 v = *(const u32x4*)(src + (size_t)r * 1024 + c * 8);
;         const float dec = __builtin_amdgcn_exp2f((float)(127 - r) * lg);
; #pragma unroll
;         for (int e = 0; e < 8; ++e) {
;             const int ee = (e + c) & 7, q2 = ee >> 1;
;             const unsigned d = q2 == 0 ? v.x : (q2 == 1 ? v.y : (q2 == 2 ? v.z : v.w));
;             const float f = __uint_as_float((ee & 1) ? (d & 0xffff0000u) : (d << 16)) * dec;
;             *(LAS unsigned short*)(dst + (8 * c + ee) * 272 + r * 2) = (unsigned short)(cvt_pk_bf16(f, 0.f) & 0xffffu);
;         }
;     }
	v_cndmask_b32_e64 v210, v211, v210, s[40:41]
	v_mul_f32_e32 v210, v160, v210
	s_nop 1
	v_cvt_pk_bf16_f32 v210, v210, v161
	v_mad_u32_u24 v211, v212, s89, v195
	ds_write_b16 v211, v210
	v_cndmask_b32_e64 v210, v209, v208, s[42:43]
	v_cndmask_b32_e64 v208, v209, v208, s[48:49]
	v_cndmask_b32_e64 v210, v210, v207, s[44:45]
	v_cndmask_b32_e64 v207, v208, v207, s[50:51]
	v_cndmask_b32_e64 v210, v210, v206, s[46:47]
	v_cndmask_b32_e64 v206, v207, v206, s[52:53]
	v_and_b32_e32 v211, 0xffff0000, v210
	v_lshlrev_b32_e32 v210, 16, v210
	v_and_b32_e32 v207, 0xffff0000, v206
	v_lshlrev_b32_e32 v206, 16, v206
	v_add_u32_e32 v208, 0x60, v196
	v_cndmask_b32_e32 v210, v211, v210, vcc
	v_cndmask_b32_e64 v206, v207, v206, s[54:55]
	v_ashrrev_i32_e32 v209, 31, v208
	v_mul_f32_e32 v210, v160, v210
	v_mad_u32_u24 v211, v213, s89, v195
	v_mul_f32_e32 v160, v160, v206
	v_mad_u32_u24 v195, v203, s89, v195
	v_lshlrev_b64 v[206:207], 11, v[208:209]
	s_nop 1
	v_cvt_pk_bf16_f32 v210, v210, v161
	ds_write_b16 v211, v210
	s_nop 1
	v_cvt_pk_bf16_f32 v160, v160, v161
	ds_write_b16 v195, v160
	v_lshl_add_u64 v[204:205], v[204:205], 0, v[206:207]
	flat_load_dwordx4 v[204:207], v[204:205] nt
	v_sub_u32_e32 v160, 31, v196
	v_cvt_f32_i32_e32 v160, v160
	v_lshl_add_u32 v195, v208, 1, 0
	v_mad_u32_u24 v208, v230, s89, v195
	v_mad_u32_u24 v209, v231, s89, v195
	v_mul_f32_e32 v160, v224, v160
	v_exp_f32_e32 v160, v160
	v_mad_u32_u24 v201, v201, s89, v195
	s_waitcnt vmcnt(0) lgkmcnt(0)
	v_cndmask_b32_e64 v210, v207, v206, s[10:11]
	v_cndmask_b32_e64 v211, v207, v206, s[12:13]
	v_cndmask_b32_e64 v210, v210, v205, s[18:19]
	v_cndmask_b32_e64 v211, v211, v205, s[20:21]
	v_cndmask_b32_e64 v210, v210, v204, s[22:23]
	v_cndmask_b32_e64 v211, v211, v204, s[24:25]
	v_and_b32_e32 v215, 0xffff0000, v210
	v_lshlrev_b32_e32 v210, 16, v210
	v_and_b32_e32 v216, 0xffff0000, v211
	v_lshlrev_b32_e32 v211, 16, v211
	v_cndmask_b32_e32 v210, v215, v210, vcc
	v_cndmask_b32_e32 v211, v211, v216, vcc
	v_mul_f32_e32 v210, v160, v210
	v_cndmask_b32_e64 v214, v207, v206, s[14:15]
	v_mul_f32_e32 v211, v160, v211
	s_nop 1
	v_cvt_pk_bf16_f32 v210, v210, v161
	ds_write_b16 v208, v210
	s_nop 1
	v_cvt_pk_bf16_f32 v208, v211, v161
	ds_write_b16 v209, v208
	v_cndmask_b32_e64 v208, v214, v205, s[6:7]
	v_cndmask_b32_e64 v208, v208, v204, s[8:9]
	v_and_b32_e32 v209, 0xffff0000, v208
	v_lshlrev_b32_e32 v208, 16, v208
	v_cndmask_b32_e32 v208, v209, v208, vcc
	v_mul_f32_e32 v208, v160, v208
	s_nop 1
	v_cvt_pk_bf16_f32 v208, v208, v161
	v_mad_u32_u24 v209, v232, s89, v195
	ds_write_b16 v209, v208
	v_cndmask_b32_e64 v208, v207, v206, s[0:1]
	v_cndmask_b32_e64 v208, v208, v205, s[56:57]
	v_cndmask_b32_e64 v208, v208, v204, s[4:5]
	v_and_b32_e32 v209, 0xffff0000, v208
	v_lshlrev_b32_e32 v208, 16, v208
	v_cndmask_b32_e64 v208, v209, v208, s[16:17]
	v_mul_f32_e32 v208, v160, v208
	s_nop 1
	v_cvt_pk_bf16_f32 v208, v208, v161
	v_mad_u32_u24 v209, v233, s89, v195
	ds_write_b16 v209, v208
	v_cndmask_b32_e64 v208, v207, v206, s[26:27]
	v_cndmask_b32_e64 v208, v208, v205, s[28:29]
	v_cndmask_b32_e64 v208, v208, v204, s[30:31]
	v_and_b32_e32 v209, 0xffff0000, v208
	v_lshlrev_b32_e32 v208, 16, v208
	v_cndmask_b32_e32 v208, v209, v208, vcc
	v_mul_f32_e32 v208, v160, v208
	s_nop 1
	v_cvt_pk_bf16_f32 v208, v208, v161
	ds_write_b16 v201, v208
	v_cndmask_b32_e64 v201, v207, v206, s[34:35]
	v_cndmask_b32_e64 v201, v201, v205, s[36:37]
	v_cndmask_b32_e64 v201, v201, v204, s[38:39]
	v_and_b32_e32 v208, 0xffff0000, v201
	v_lshlrev_b32_e32 v201, 16, v201
	v_cndmask_b32_e64 v201, v208, v201, s[40:41]
	v_mul_f32_e32 v201, v160, v201
	s_nop 1
	v_cvt_pk_bf16_f32 v201, v201, v161
	v_mad_u32_u24 v208, v212, s89, v195
	ds_write_b16 v208, v201
	v_cndmask_b32_e64 v201, v207, v206, s[42:43]
	v_cndmask_b32_e64 v201, v201, v205, s[44:45]
	v_cndmask_b32_e64 v201, v201, v204, s[46:47]
	v_and_b32_e32 v208, 0xffff0000, v201
	v_lshlrev_b32_e32 v201, 16, v201
	v_cndmask_b32_e32 v201, v208, v201, vcc
	v_mul_f32_e32 v201, v160, v201
	s_nop 1
	v_cvt_pk_bf16_f32 v201, v201, v161
	v_mad_u32_u24 v208, v213, s89, v195
	ds_write_b16 v208, v201
	v_cndmask_b32_e64 v201, v207, v206, s[48:49]
	v_cndmask_b32_e64 v201, v201, v205, s[50:51]
	v_cndmask_b32_e64 v201, v201, v204, s[52:53]
	v_and_b32_e32 v204, 0xffff0000, v201
	v_lshlrev_b32_e32 v201, 16, v201
	s_lshl_b64 s[0:1], s[72:73], 12
	v_cndmask_b32_e64 v201, v204, v201, s[54:55]
	s_add_u32 s0, s59, s0
	v_mul_f32_e32 v160, v160, v201
	v_mad_u32_u24 v195, v203, s89, v195
	s_addc_u32 s1, s61, s1
	v_mov_b32_e32 v201, v161
	s_nop 1
	v_cvt_pk_bf16_f32 v160, v160, v161
	ds_write_b16 v195, v160
	v_lshl_add_u64 v[208:209], s[0:1], 0, v[200:201]
	v_lshlrev_b64 v[204:205], 8, v[196:197]
	v_lshl_add_u64 v[204:205], v[208:209], 0, v[204:205]
	flat_load_dwordx4 v[204:207], v[204:205] nt
	v_add_u32_e32 v160, s90, v200
	v_ashrrev_i32_e32 v195, 31, v194
	v_add_u32_e32 v193, v160, v193
	v_lshlrev_b64 v[200:201], 8, v[194:195]
	v_lshl_add_u64 v[200:201], v[208:209], 0, v[200:201]
	v_add_u32_e32 v191, v160, v191
	v_add_u32_e32 v199, v160, v199
	v_add_u32_e32 v189, v160, v189
	s_waitcnt vmcnt(0) lgkmcnt(0)
	ds_write_b128 v193, v[204:207]
	flat_load_dwordx4 v[204:207], v[200:201] nt
	v_ashrrev_i32_e32 v193, 31, v192
	v_lshlrev_b64 v[200:201], 8, v[192:193]
	v_lshl_add_u64 v[200:201], v[208:209], 0, v[200:201]
	s_waitcnt vmcnt(0) lgkmcnt(0)
	ds_write_b128 v191, v[204:207]
	flat_load_dwordx4 v[204:207], v[200:201] nt
	v_ashrrev_i32_e32 v191, 31, v190
	v_lshlrev_b64 v[200:201], 8, v[190:191]
	v_lshl_add_u64 v[200:201], v[208:209], 0, v[200:201]
	s_waitcnt vmcnt(0) lgkmcnt(0)
; #define LAS __attribute__((address_space(3)))
; #define MFMA16(a, b, c) __builtin_amdgcn_mfma_f32_16x16x32_bf16((a), (b), (c), 0, 0, 0)
; template <int R>
; __device__ __forceinline__ void stage_tile(ldsp dst, const bf16_t* src, size_t ld, int tid) {
;     ...
;     for (int i = 0; i < R * 16 / 512; ++i) { const int idx = tid + 512 * i, r = idx >> 4, c = idx & 15;
;         const u32x4 v = *(const u32x4*)(src + (size_t)r * ld + c * 8); *(LAS u32x4*)(dst + r * 272 + c * 16) = v; }
; __device__ __forceinline__ void ret_out_item(ldsp lds, int item, const bf16_t* rq, const bf16_t* rk, const bf16_t* vT, const bf16_t* kdT, bf16_t* rg, const float* L,
;                                              const float* gn_g, float lg, int tid_, int w, int fr_, int fq_) {
;     ...
;         const float qd = __builtin_amdgcn_exp2f((float)(i + 1) * lg);
; #pragma unroll
;         for (int nt = 0; nt < 16; ++nt) o[nt] = o[nt] * qd;
;         __syncthreads();
; #pragma unroll
;         for (int nt = 0; nt < 8; ++nt) *(LAS u32x2*)(lds + RX1 + i * 272 + (16 * nt + 4 * fq) * 2) = pk[nt];
;         stage_kdT(lds + RX0, kdT + row0 * 1024 + h * 128, lg, tid);
;         asm volatile("" ::: "memory");
;         stage_tile<256>(lds + RY, vT + ((row0 >> 7) * 2048 + h * 256) * 128, 128, tid);
;         __syncthreads();
;         bf16_t* rp = rg + (row0 + i) * 2048 + h * 256 + 4 * fq;
; #pragma unroll
;         for (int mt = 0; mt < 2; ++mt)
; #pragma unroll
;             for (int nt = 0; nt < 8; ++nt) st[mt][nt] = st[mt][nt] * gC;
; #pragma unroll 1
;         for (int ks = 0; ks < 4; ++ks) {
;             const bf16x8 a = frag(lds + RX1, i, ks, fq);
; #pragma unroll
;             for (int nt = 0; nt < 16; ++nt) o[nt] = MFMA16(frag(lds + RY, 16 * nt + fr, ks, fq), a, o[nt]);
;         }
	ds_write_b128 v199, v[204:207]
	flat_load_dwordx4 v[204:207], v[200:201] nt
	v_add_u32_e32 v199, 0x800, v185
	v_ashrrev_i32_e32 v200, 4, v199
	v_ashrrev_i32_e32 v201, 31, v200
	v_lshlrev_b64 v[210:211], 8, v[200:201]
	v_lshl_add_u64 v[210:211], v[208:209], 0, v[210:211]
	v_mad_u64_u32 v[200:201], s[0:1], v200, s89, v[160:161]
	s_waitcnt vmcnt(0) lgkmcnt(0)
	ds_write_b128 v189, v[204:207]
	flat_load_dwordx4 v[204:207], v[210:211] nt
	v_add_u32_e32 v189, 0xa00, v185
	v_ashrrev_i32_e32 v210, 4, v189
	v_ashrrev_i32_e32 v211, 31, v210
	v_lshlrev_b64 v[212:213], 8, v[210:211]
	v_lshl_add_u64 v[212:213], v[208:209], 0, v[212:213]
	v_add_u32_e32 v189, 0xc00, v185
	v_mad_u64_u32 v[210:211], s[0:1], v210, s89, v[160:161]
	v_add_u32_e32 v185, 0xe00, v185
	s_waitcnt vmcnt(0) lgkmcnt(0)
	ds_write_b128 v200, v[204:207]
	flat_load_dwordx4 v[204:207], v[212:213] nt
	v_ashrrev_i32_e32 v200, 4, v189
	v_ashrrev_i32_e32 v201, 31, v200
	v_lshlrev_b64 v[212:213], 8, v[200:201]
	v_lshl_add_u64 v[212:213], v[208:209], 0, v[212:213]
	v_mad_u64_u32 v[200:201], s[0:1], v200, s89, v[160:161]
	s_mov_b32 s0, 0
	s_waitcnt vmcnt(0) lgkmcnt(0)
	ds_write_b128 v210, v[204:207]
	flat_load_dwordx4 v[204:207], v[212:213] nt
	v_ashrrev_i32_e32 v210, 4, v185
	v_ashrrev_i32_e32 v211, 31, v210
	v_lshlrev_b64 v[212:213], 8, v[210:211]
	v_lshl_add_u64 v[208:209], v[208:209], 0, v[212:213]
	v_add_u32_e32 v185, 1, v198
	v_cvt_f32_i32_e32 v185, v185
	v_mul_f32_e32 v185, v224, v185
	s_waitcnt vmcnt(0) lgkmcnt(0)
	ds_write_b128 v200, v[204:207]
	flat_load_dwordx4 v[204:207], v[208:209] nt
	v_exp_f32_e32 v200, v185
	v_mad_u64_u32 v[208:209], s[4:5], v210, s89, v[160:161]
	v_add3_u32 v160, v228, v226, s91
	v_pk_mul_f32 v[158:159], v[200:201], v[158:159] op_sel_hi:[0,1]
	v_pk_mul_f32 v[156:157], v[200:201], v[156:157] op_sel_hi:[0,1]
	v_pk_mul_f32 v[154:155], v[200:201], v[154:155] op_sel_hi:[0,1]
	v_pk_mul_f32 v[152:153], v[200:201], v[152:153] op_sel_hi:[0,1]
	v_pk_mul_f32 v[150:151], v[200:201], v[150:151] op_sel_hi:[0,1]
	v_pk_mul_f32 v[148:149], v[200:201], v[148:149] op_sel_hi:[0,1]
	v_pk_mul_f32 v[146:147], v[200:201], v[146:147] op_sel_hi:[0,1]
	v_pk_mul_f32 v[144:145], v[200:201], v[144:145] op_sel_hi:[0,1]
	v_pk_mul_f32 v[142:143], v[200:201], v[142:143] op_sel_hi:[0,1]
	v_pk_mul_f32 v[140:141], v[200:201], v[140:141] op_sel_hi:[0,1]
	v_pk_mul_f32 v[138:139], v[200:201], v[138:139] op_sel_hi:[0,1]
	v_pk_mul_f32 v[136:137], v[200:201], v[136:137] op_sel_hi:[0,1]
	v_pk_mul_f32 v[134:135], v[200:201], v[134:135] op_sel_hi:[0,1]
	v_pk_mul_f32 v[132:133], v[200:201], v[132:133] op_sel_hi:[0,1]
	v_pk_mul_f32 v[130:131], v[200:201], v[130:131] op_sel_hi:[0,1]
	v_pk_mul_f32 v[128:129], v[200:201], v[128:129] op_sel_hi:[0,1]
	v_pk_mul_f32 v[126:127], v[200:201], v[126:127] op_sel_hi:[0,1]
	v_pk_mul_f32 v[124:125], v[200:201], v[124:125] op_sel_hi:[0,1]
	v_pk_mul_f32 v[122:123], v[200:201], v[122:123] op_sel_hi:[0,1]
	v_pk_mul_f32 v[120:121], v[200:201], v[120:121] op_sel_hi:[0,1]
	v_pk_mul_f32 v[118:119], v[200:201], v[118:119] op_sel_hi:[0,1]
	v_pk_mul_f32 v[116:117], v[200:201], v[116:117] op_sel_hi:[0,1]
	v_pk_mul_f32 v[114:115], v[200:201], v[114:115] op_sel_hi:[0,1]
	v_pk_mul_f32 v[112:113], v[200:201], v[112:113] op_sel_hi:[0,1]
	v_pk_mul_f32 v[110:111], v[200:201], v[110:111] op_sel_hi:[0,1]
	v_pk_mul_f32 v[108:109], v[200:201], v[108:109] op_sel_hi:[0,1]
	v_pk_mul_f32 v[106:107], v[200:201], v[106:107] op_sel_hi:[0,1]
	v_pk_mul_f32 v[104:105], v[200:201], v[104:105] op_sel_hi:[0,1]
	v_pk_mul_f32 v[102:103], v[200:201], v[102:103] op_sel_hi:[0,1]
	v_pk_mul_f32 v[100:101], v[200:201], v[100:101] op_sel_hi:[0,1]
	v_pk_mul_f32 v[98:99], v[200:201], v[98:99] op_sel_hi:[0,1]
	v_pk_mul_f32 v[96:97], v[200:201], v[96:97] op_sel_hi:[0,1]
	s_waitcnt vmcnt(0) lgkmcnt(0)
	ds_write_b128 v208, v[204:207]
	s_waitcnt lgkmcnt(0)
	s_barrier
.LBB0_555:
	v_add_u32_e32 v178, s0, v160
	v_add_u32_e32 v179, s0, v229
	v_add_u32_e32 v185, 0x11000, v179
	v_add_u32_e32 v189, 0x12100, v179
	ds_read_b128 v[204:207], v178
	ds_read_b128 v[208:211], v185
	ds_read_b128 v[212:215], v189
	v_add_u32_e32 v199, 0x13200, v179
	s_waitcnt lgkmcnt(1)
	v_mfma_f32_16x16x32_bf16 v[156:159], v[208:211], v[204:207], v[156:159]
	ds_read_b128 v[208:211], v199
	v_add_u32_e32 v201, 0x15400, v179
	v_add_u32_e32 v216, 0x17600, v179
	v_add_u32_e32 v228, 0x19800, v179
	v_add_u32_e32 v231, 0x1ba00, v179
	s_waitcnt lgkmcnt(0)
	v_mfma_f32_16x16x32_bf16 v[148:151], v[208:211], v[204:207], v[148:151]
	ds_read_b128 v[208:211], v201
	v_add_u32_e32 v233, 0x1dc00, v179
	v_add_u32_e32 v200, 0x14300, v179
	v_add_u32_e32 v235, 0x1fe00, v179
	s_waitcnt lgkmcnt(0)
	v_mfma_f32_16x16x32_bf16 v[140:143], v[208:211], v[204:207], v[140:143]
	ds_read_b128 v[208:211], v216
	v_add_u32_e32 v203, 0x16500, v179
	v_add_u32_e32 v178, 0x20f00, v179
	s_waitcnt lgkmcnt(0)
	v_mfma_f32_16x16x32_bf16 v[132:135], v[208:211], v[204:207], v[132:135]
	ds_read_b128 v[208:211], v228
	v_add_u32_e32 v217, 0x18700, v179
	v_add_u32_e32 v230, 0x1a900, v179
	s_waitcnt lgkmcnt(0)
	v_mfma_f32_16x16x32_bf16 v[124:127], v[208:211], v[204:207], v[124:127]
	ds_read_b128 v[208:211], v231
	v_add_u32_e32 v232, 0x1cb00, v179
	v_add_u32_e32 v234, 0x1ed00, v179
	s_waitcnt lgkmcnt(0)
	v_mfma_f32_16x16x32_bf16 v[116:119], v[208:211], v[204:207], v[116:119]
	ds_read_b128 v[208:211], v233
	s_add_i32 s0, s0, 64
	s_cmpk_eq_i32 s0, 0x100
	v_mfma_f32_16x16x32_bf16 v[152:155], v[212:215], v[204:207], v[152:155]
	ds_read_b128 v[212:215], v200
	s_waitcnt lgkmcnt(1)
	v_mfma_f32_16x16x32_bf16 v[108:111], v[208:211], v[204:207], v[108:111]
	ds_read_b128 v[208:211], v235
	s_waitcnt lgkmcnt(0)
	v_mfma_f32_16x16x32_bf16 v[100:103], v[208:211], v[204:207], v[100:103]
	ds_read_b128 v[208:211], v178
	v_mfma_f32_16x16x32_bf16 v[144:147], v[212:215], v[204:207], v[144:147]
	ds_read_b128 v[212:215], v203
	s_waitcnt lgkmcnt(0)
	v_mfma_f32_16x16x32_bf16 v[136:139], v[212:215], v[204:207], v[136:139]
	ds_read_b128 v[212:215], v217
	s_waitcnt lgkmcnt(0)
	v_mfma_f32_16x16x32_bf16 v[128:131], v[212:215], v[204:207], v[128:131]
	ds_read_b128 v[212:215], v230
	s_waitcnt lgkmcnt(0)
	v_mfma_f32_16x16x32_bf16 v[120:123], v[212:215], v[204:207], v[120:123]
	ds_read_b128 v[212:215], v232
	s_waitcnt lgkmcnt(0)
	v_mfma_f32_16x16x32_bf16 v[112:115], v[212:215], v[204:207], v[112:115]
	ds_read_b128 v[212:215], v234
	s_waitcnt lgkmcnt(0)
	v_mfma_f32_16x16x32_bf16 v[104:107], v[212:215], v[204:207], v[104:107]
	v_mfma_f32_16x16x32_bf16 v[96:99], v[208:211], v[204:207], v[96:99]
	s_cbranch_scc0 .LBB0_555
; #define MFMA16(a, b, c) __builtin_amdgcn_mfma_f32_16x16x32_bf16((a), (b), (c), 0, 0, 0)
; __device__ __forceinline__ void ret_out_item(ldsp lds, int item, const bf16_t* rq, const bf16_t* rk, const bf16_t* vT, const bf16_t* kdT, bf16_t* rg, const float* L,
;                                              const float* gn_g, float lg, int tid_, int w, int fr_, int fq_) {
;     ...
; #pragma unroll
;         for (int mt = 0; mt < 2; ++mt)
; #pragma unroll
;             for (int nt = 0; nt < 8; ++nt) st[mt][nt] = st[mt][nt] * gC;
; #pragma unroll 1
;         for (int ks = 0; ks < 4; ++ks) {
;             const bf16x8 a = frag(lds + RX1, i, ks, fq);
; #pragma unroll
;             for (int nt = 0; nt < 16; ++nt) o[nt] = MFMA16(frag(lds + RY, 16 * nt + fr, ks, fq), a, o[nt]);
;         }
;         u32x2 svr[8];
; #pragma unroll
;         for (int nt = 0; nt < 8; ++nt) svr[nt] = *(const u32x2*)(rp + 16 * nt);
; #pragma unroll 1
;         for (int ks = 0; ks < 4; ++ks) {
;             const bf16x8 a0 = frag(lds + RY, 32 * w + fr, ks, fq), a1 = frag(lds + RY, 32 * w + 16 + fr, ks, fq);
; #pragma unroll
;             for (int nt = 0; nt < 8; ++nt) { const bf16x8 bb = frag(lds + RX0, 16 * nt + fr, ks, fq); st[0][nt] = MFMA16(bb, a0, st[0][nt]); st[1][nt] = MFMA16(bb, a1, st[1][nt]); }
;         }
;         if (c < 7) {
; #pragma unroll
;             for (int ii = 0; ii < 4; ++ii) { const int idx = tid + 512 * ii; qv[ii] = *(const u32x4*)(rq + (row0 + 128 + (idx >> 4)) * 1024 + h * 128 + (idx & 15) * 8); kv[ii] = *(const u32x4*)(rk + (row0 + 128 + (idx >> 4)) * 1024 + h * 128 + (idx & 15) * 8); }
;         }
	v_ashrrev_i32_e32 v199, 31, v198
	v_lshl_add_u64 v[198:199], s[72:73], 0, v[198:199]
	v_lshlrev_b64 v[198:199], 12, v[198:199]
	v_ashrrev_i32_e32 v189, 31, v188
	v_lshl_add_u64 v[198:199], s[68:69], 0, v[198:199]
	v_lshl_add_u64 v[198:199], v[188:189], 1, v[198:199]
	flat_load_dwordx2 v[216:217], v[198:199] nt
	flat_load_dwordx2 v[214:215], v[198:199] offset:32 nt
	flat_load_dwordx2 v[212:213], v[198:199] offset:64 nt
	flat_load_dwordx2 v[210:211], v[198:199] offset:96 nt
	flat_load_dwordx2 v[208:209], v[198:199] offset:128 nt
	flat_load_dwordx2 v[206:207], v[198:199] offset:160 nt
	flat_load_dwordx2 v[204:205], v[198:199] offset:192 nt
	flat_load_dwordx2 v[200:201], v[198:199] offset:224 nt
	v_mov_b32_e32 v185, v184
	v_pk_mul_f32 v[6:7], v[184:185], v[6:7]
	v_pk_mul_f32 v[4:5], v[186:187], v[4:5]
	v_pk_mul_f32 v[14:15], v[184:185], v[14:15]
	v_pk_mul_f32 v[12:13], v[186:187], v[12:13]
	v_pk_mul_f32 v[22:23], v[184:185], v[22:23]
	v_pk_mul_f32 v[20:21], v[186:187], v[20:21]
	v_pk_mul_f32 v[30:31], v[184:185], v[30:31]
	v_pk_mul_f32 v[28:29], v[186:187], v[28:29]
	v_pk_mul_f32 v[38:39], v[184:185], v[38:39]
	v_pk_mul_f32 v[36:37], v[186:187], v[36:37]
	v_pk_mul_f32 v[46:47], v[184:185], v[46:47]
	v_pk_mul_f32 v[44:45], v[186:187], v[44:45]
	v_pk_mul_f32 v[54:55], v[184:185], v[54:55]
	v_pk_mul_f32 v[52:53], v[186:187], v[52:53]
	v_pk_mul_f32 v[62:63], v[184:185], v[62:63]
	v_pk_mul_f32 v[60:61], v[186:187], v[60:61]
	v_pk_mul_f32 v[2:3], v[184:185], v[2:3]
	v_pk_mul_f32 v[0:1], v[186:187], v[0:1]
	v_pk_mul_f32 v[10:11], v[184:185], v[10:11]
	v_pk_mul_f32 v[8:9], v[186:187], v[8:9]
	v_pk_mul_f32 v[18:19], v[184:185], v[18:19]
	v_pk_mul_f32 v[16:17], v[186:187], v[16:17]
	v_pk_mul_f32 v[26:27], v[184:185], v[26:27]
	v_pk_mul_f32 v[24:25], v[186:187], v[24:25]
	v_pk_mul_f32 v[34:35], v[184:185], v[34:35]
	v_pk_mul_f32 v[32:33], v[186:187], v[32:33]
	v_pk_mul_f32 v[42:43], v[184:185], v[42:43]
	v_pk_mul_f32 v[40:41], v[186:187], v[40:41]
	v_pk_mul_f32 v[50:51], v[184:185], v[50:51]
	v_pk_mul_f32 v[48:49], v[186:187], v[48:49]
	v_pk_mul_f32 v[58:59], v[184:185], v[58:59]
	v_pk_mul_f32 v[56:57], v[186:187], v[56:57]
	v_add3_u32 v160, 0, v226, v227
	s_mov_b32 s0, 4
.LBB0_557:
	v_add_u32_e32 v178, s87, v160
	v_add_u32_e32 v179, 0x11000, v178
	ds_read_b128 v[228:231], v160
	ds_read_b128 v[232:235], v160 offset:4352
	v_add_u32_e32 v178, 0x12100, v178
	ds_read_b128 v[236:239], v179
	ds_read_b128 v[240:243], v178
	s_add_i32 s0, s0, -1
	s_waitcnt lgkmcnt(0)
	v_mfma_f32_16x16x32_bf16 v[0:3], v[228:231], v[236:239], v[0:3]
	s_cmp_eq_u32 s0, 0
	v_mfma_f32_16x16x32_bf16 v[32:35], v[228:231], v[240:243], v[32:35]
	v_mfma_f32_16x16x32_bf16 v[4:7], v[232:235], v[236:239], v[4:7]
	v_mfma_f32_16x16x32_bf16 v[36:39], v[232:235], v[240:243], v[36:39]
	ds_read_b128 v[228:231], v160 offset:8704
	ds_read_b128 v[232:235], v160 offset:13056
	s_waitcnt lgkmcnt(0)
	v_mfma_f32_16x16x32_bf16 v[8:11], v[228:231], v[236:239], v[8:11]
	v_mfma_f32_16x16x32_bf16 v[40:43], v[228:231], v[240:243], v[40:43]
	v_mfma_f32_16x16x32_bf16 v[12:15], v[232:235], v[236:239], v[12:15]
	v_mfma_f32_16x16x32_bf16 v[44:47], v[232:235], v[240:243], v[44:47]
	ds_read_b128 v[228:231], v160 offset:17408
	ds_read_b128 v[232:235], v160 offset:21760
	s_waitcnt lgkmcnt(0)
	v_mfma_f32_16x16x32_bf16 v[16:19], v[228:231], v[236:239], v[16:19]
	v_mfma_f32_16x16x32_bf16 v[48:51], v[228:231], v[240:243], v[48:51]
	v_mfma_f32_16x16x32_bf16 v[20:23], v[232:235], v[236:239], v[20:23]
	v_mfma_f32_16x16x32_bf16 v[52:55], v[232:235], v[240:243], v[52:55]
	ds_read_b128 v[228:231], v160 offset:26112
	ds_read_b128 v[232:235], v160 offset:30464
	v_add_u32_e32 v160, 64, v160
	s_waitcnt lgkmcnt(0)
	v_mfma_f32_16x16x32_bf16 v[24:27], v[228:231], v[236:239], v[24:27]
	v_mfma_f32_16x16x32_bf16 v[56:59], v[228:231], v[240:243], v[56:59]
	v_mfma_f32_16x16x32_bf16 v[28:31], v[232:235], v[236:239], v[28:31]
	v_mfma_f32_16x16x32_bf16 v[60:63], v[232:235], v[240:243], v[60:63]
	s_cbranch_scc0 .LBB0_557
	s_cmp_eq_u32 s60, 7
	s_cbranch_scc1 .LBB0_549
	s_add_u32 s0, s72, 0x80
	s_addc_u32 s1, s73, 0
	v_lshlrev_b32_e32 v160, 1, v202
	v_lshl_add_u64 v[64:65], s[0:1], 0, v[196:197]
	v_lshl_add_u64 v[72:73], s[0:1], 0, v[194:195]
	v_lshl_add_u64 v[80:81], s[0:1], 0, v[192:193]
	v_lshl_add_u64 v[92:93], s[0:1], 0, v[190:191]
	v_lshl_add_u64 v[88:89], s[64:65], 0, v[160:161]
	v_lshl_add_u64 v[90:91], s[66:67], 0, v[160:161]
	v_lshlrev_b64 v[64:65], 11, v[64:65]
	v_lshlrev_b64 v[72:73], 11, v[72:73]
	v_lshlrev_b64 v[80:81], 11, v[80:81]
	v_lshlrev_b64 v[92:93], 11, v[92:93]
	v_lshl_add_u64 v[66:67], v[88:89], 0, v[64:65]
	v_lshl_add_u64 v[68:69], v[90:91], 0, v[64:65]
	v_lshl_add_u64 v[74:75], v[88:89], 0, v[72:73]
	v_lshl_add_u64 v[76:77], v[90:91], 0, v[72:73]
	v_lshl_add_u64 v[82:83], v[88:89], 0, v[80:81]
	v_lshl_add_u64 v[84:85], v[90:91], 0, v[80:81]
	v_lshl_add_u64 v[88:89], v[88:89], 0, v[92:93]
	v_lshl_add_u64 v[92:93], v[90:91], 0, v[92:93]
	flat_load_dwordx4 v[64:67], v[66:67] nt
	s_nop 0
	flat_load_dwordx4 v[68:71], v[68:69] nt
	s_nop 0
	flat_load_dwordx4 v[72:75], v[74:75] nt
	s_nop 0
	flat_load_dwordx4 v[76:79], v[76:77] nt
	s_nop 0
	flat_load_dwordx4 v[80:83], v[82:83] nt
	s_nop 0
	flat_load_dwordx4 v[84:87], v[84:85] nt
	s_nop 0
	flat_load_dwordx4 v[88:91], v[88:89] nt
	s_nop 0
	flat_load_dwordx4 v[92:95], v[92:93] nt
	s_branch .LBB0_549
